# XNACK-replay padding s_nop removed between global loads in the pipelined GEMM loops
# speedup vs baseline: 1.0058x; 1.0058x over previous
; DI f32x4 mfma16(bf16x8 a, bf16x8 b, f32x4 c) { return __builtin_amdgcn_mfma_f32_16x16x32_bf16(a, b, c, 0, 0, 0); }
; template <int MI, int NJ, bool SWAP, class AP, class BP>
; DI void gemm_main(f32x4 (&acc)[MI][NJ], const AP& ap, int a_kstep, const BP& bp, int b_kstep, int nk, bf16_t* smem) {
;     ...
;   for (int kt = 0; kt < nk; ++kt) {
;     const int buf = kt & 1;
;     sstore(buf ^ 1);
;     gload(kt + 2 < nk ? kt + 2 : nk - 1);
;     __builtin_amdgcn_sched_barrier(0);
;     const bf16_t* As = smem + buf * L::STAGE + (wm * 16 * MI + l15) * LDT + quad * 8;
;     const bf16_t* Bs = smem + buf * L::STAGE + L::A_ELEMS + (wn * 16 * NJ + l15) * LDT + quad * 8;
; #pragma unroll
;     for (int ks = 0; ks < 2; ++ks) {
;       if (MI * NJ >= 32 && ks == 1) asm volatile("" ::: "memory");
;       bf16x8 b[NJ];
; #pragma unroll
;       for (int j = 0; j < NJ; ++j) b[j] = *(const bf16x8*)(Bs + j * 16 * LDT + ks * 32);
; #pragma unroll
;       for (int i = 0; i < MI; ++i) {
;         const bf16x8 a = *(const bf16x8*)(As + i * 16 * LDT + ks * 32);
; #pragma unroll
;         for (int j = 0; j < NJ; ++j) acc[i][j] = SWAP ? mfma16(b[j], a, acc[i][j]) : mfma16(a, b[j], acc[i][j]);
;       }
;     }
;     __syncthreads();
;   }
.Lgm0_main:
	ds_read_b128 v[242:245], v176 offset:4608
	s_waitcnt lgkmcnt(4)
	v_mfma_f32_16x16x32_bf16 v[124:127], v[178:181], v[212:215], v[124:127]
	s_waitcnt lgkmcnt(3)
	v_mfma_f32_16x16x32_bf16 v[120:123], v[200:203], v[212:215], v[120:123]
	s_waitcnt lgkmcnt(2)
	v_mfma_f32_16x16x32_bf16 v[116:119], v[204:207], v[212:215], v[116:119]
	s_waitcnt lgkmcnt(1)
	v_mfma_f32_16x16x32_bf16 v[112:115], v[208:211], v[212:215], v[112:115]
	s_and_b32 s5, s4, 1
	s_min_u32 s6, s4, 13
	s_xor_b32 s7, s5, 1
	s_lshl_b32 s33, s6, 7
	s_mul_i32 s7, s7, 0x12000
	s_add_u32 s6, s0, s33
	v_add3_u32 v250, s7, v171, v169
	v_add3_u32 v251, s7, v173, v169
	v_add3_u32 v252, s7, v174, v169
	v_add3_u32 v253, s7, v175, v169
	s_addc_u32 s7, s1, 0
	s_waitcnt vmcnt(7)
	ds_write_b128 v250, v[128:131]
	ds_read_b128 v[246:249], v176 offset:6912
	v_mfma_f32_16x16x32_bf16 v[108:111], v[178:181], v[216:219], v[108:111]
	v_mfma_f32_16x16x32_bf16 v[104:107], v[200:203], v[216:219], v[104:107]
	v_mfma_f32_16x16x32_bf16 v[100:103], v[204:207], v[216:219], v[100:103]
	v_mfma_f32_16x16x32_bf16 v[96:99], v[208:211], v[216:219], v[96:99]
	s_waitcnt vmcnt(6)
	ds_write_b128 v251, v[132:135]
	ds_read_b128 v[212:215], v176 offset:9216
	s_waitcnt lgkmcnt(4)
	v_mfma_f32_16x16x32_bf16 v[92:95], v[178:181], v[242:245], v[92:95]
	v_mfma_f32_16x16x32_bf16 v[88:91], v[200:203], v[242:245], v[88:91]
	v_mfma_f32_16x16x32_bf16 v[84:87], v[204:207], v[242:245], v[84:87]
	v_mfma_f32_16x16x32_bf16 v[80:83], v[208:211], v[242:245], v[80:83]
	ds_read_b128 v[216:219], v176 offset:11520
	s_waitcnt lgkmcnt(3)
	v_mfma_f32_16x16x32_bf16 v[76:79], v[178:181], v[246:249], v[76:79]
	s_waitcnt vmcnt(5)
	ds_write_b128 v252, v[136:139]
	v_mfma_f32_16x16x32_bf16 v[72:75], v[200:203], v[246:249], v[72:75]
	v_mfma_f32_16x16x32_bf16 v[68:71], v[204:207], v[246:249], v[68:71]
	v_mfma_f32_16x16x32_bf16 v[64:67], v[208:211], v[246:249], v[64:67]
	ds_read_b128 v[242:245], v176 offset:13824
	s_waitcnt lgkmcnt(3)
	v_mfma_f32_16x16x32_bf16 v[60:63], v[178:181], v[212:215], v[60:63]
	s_waitcnt vmcnt(4)
	ds_write_b128 v253, v[140:143]
	v_mfma_f32_16x16x32_bf16 v[56:59], v[200:203], v[212:215], v[56:59]
	v_mfma_f32_16x16x32_bf16 v[52:55], v[204:207], v[212:215], v[52:55]
	v_mfma_f32_16x16x32_bf16 v[48:51], v[208:211], v[212:215], v[48:51]
	ds_read_b128 v[246:249], v176 offset:16128
	s_waitcnt lgkmcnt(4)
	v_mfma_f32_16x16x32_bf16 v[44:47], v[178:181], v[216:219], v[44:47]
	s_waitcnt vmcnt(3)
	ds_write_b128 v250, v[144:147] offset:36864
	v_mfma_f32_16x16x32_bf16 v[40:43], v[200:203], v[216:219], v[40:43]
	v_mfma_f32_16x16x32_bf16 v[36:39], v[204:207], v[216:219], v[36:39]
	v_mfma_f32_16x16x32_bf16 v[32:35], v[208:211], v[216:219], v[32:35]
	ds_read_b128 v[212:215], v176 offset:64
	s_waitcnt lgkmcnt(4)
	v_mfma_f32_16x16x32_bf16 v[28:31], v[178:181], v[242:245], v[28:31]
	s_waitcnt vmcnt(2)
	ds_write_b128 v251, v[148:151] offset:36864
	v_mfma_f32_16x16x32_bf16 v[24:27], v[200:203], v[242:245], v[24:27]
	v_mfma_f32_16x16x32_bf16 v[20:23], v[204:207], v[242:245], v[20:23]
	v_mfma_f32_16x16x32_bf16 v[16:19], v[208:211], v[242:245], v[16:19]
	ds_read_b128 v[216:219], v176 offset:2368
	s_waitcnt lgkmcnt(4)
	v_mfma_f32_16x16x32_bf16 v[12:15], v[178:181], v[246:249], v[12:15]
	ds_read_b128 v[178:181], v182 offset:36928
	s_waitcnt vmcnt(1)
	ds_write_b128 v252, v[152:155] offset:36864
	v_mfma_f32_16x16x32_bf16 v[8:11], v[200:203], v[246:249], v[8:11]
	ds_read_b128 v[200:203], v182 offset:39232
	v_mfma_f32_16x16x32_bf16 v[0:3], v[204:207], v[246:249], v[0:3]
	ds_read_b128 v[204:207], v182 offset:41536
	v_mfma_f32_16x16x32_bf16 v[4:7], v[208:211], v[246:249], v[4:7]
	ds_read_b128 v[208:211], v182 offset:43840
	ds_read_b128 v[242:245], v176 offset:4672
	s_waitcnt lgkmcnt(5)
	v_mfma_f32_16x16x32_bf16 v[124:127], v[178:181], v[212:215], v[124:127]
	s_waitcnt lgkmcnt(3)
	v_mfma_f32_16x16x32_bf16 v[120:123], v[200:203], v[212:215], v[120:123]
	s_waitcnt vmcnt(0)
	ds_write_b128 v253, v[156:159] offset:36864
	s_waitcnt lgkmcnt(3)
	v_mfma_f32_16x16x32_bf16 v[116:119], v[204:207], v[212:215], v[116:119]
	s_waitcnt lgkmcnt(2)
	v_mfma_f32_16x16x32_bf16 v[112:115], v[208:211], v[212:215], v[112:115]
	v_lshl_add_u64 v[128:129], s[6:7], 0, v[160:161]
	v_lshl_add_u64 v[132:133], s[6:7], 0, v[162:163]
	v_lshl_add_u64 v[136:137], s[6:7], 0, v[164:165]
	v_lshl_add_u64 v[140:141], s[6:7], 0, v[166:167]
	s_add_u32 s6, s2, s33
	s_addc_u32 s7, s3, 0
	v_lshl_add_u64 v[144:145], s[6:7], 0, v[160:161]
	v_lshl_add_u64 v[148:149], s[6:7], 0, v[162:163]
	v_lshl_add_u64 v[152:153], s[6:7], 0, v[164:165]
	v_lshl_add_u64 v[156:157], s[6:7], 0, v[166:167]
	global_load_dwordx4 v[128:131], v[128:129], off offset:256
	ds_read_b128 v[246:249], v176 offset:6976
	v_mfma_f32_16x16x32_bf16 v[108:111], v[178:181], v[216:219], v[108:111]
	v_mfma_f32_16x16x32_bf16 v[104:107], v[200:203], v[216:219], v[104:107]
	global_load_dwordx4 v[132:135], v[132:133], off offset:256
	v_mfma_f32_16x16x32_bf16 v[100:103], v[204:207], v[216:219], v[100:103]
	v_mfma_f32_16x16x32_bf16 v[96:99], v[208:211], v[216:219], v[96:99]
	ds_read_b128 v[212:215], v176 offset:9280
	s_waitcnt lgkmcnt(3)
	v_mfma_f32_16x16x32_bf16 v[92:95], v[178:181], v[242:245], v[92:95]
	global_load_dwordx4 v[136:139], v[136:137], off offset:256
	v_mfma_f32_16x16x32_bf16 v[88:91], v[200:203], v[242:245], v[88:91]
	v_mfma_f32_16x16x32_bf16 v[84:87], v[204:207], v[242:245], v[84:87]
	global_load_dwordx4 v[140:143], v[140:141], off offset:256
	v_mfma_f32_16x16x32_bf16 v[80:83], v[208:211], v[242:245], v[80:83]
	ds_read_b128 v[216:219], v176 offset:11584
	s_waitcnt lgkmcnt(2)
	v_mfma_f32_16x16x32_bf16 v[76:79], v[178:181], v[246:249], v[76:79]
	v_mfma_f32_16x16x32_bf16 v[72:75], v[200:203], v[246:249], v[72:75]
	global_load_dwordx4 v[144:147], v[144:145], off offset:256
	v_mfma_f32_16x16x32_bf16 v[68:71], v[204:207], v[246:249], v[68:71]
	v_mfma_f32_16x16x32_bf16 v[64:67], v[208:211], v[246:249], v[64:67]
	global_load_dwordx4 v[148:151], v[148:149], off offset:256
	ds_read_b128 v[242:245], v176 offset:13888
	s_waitcnt lgkmcnt(2)
	v_mfma_f32_16x16x32_bf16 v[60:63], v[178:181], v[212:215], v[60:63]
	v_mfma_f32_16x16x32_bf16 v[56:59], v[200:203], v[212:215], v[56:59]
	v_mfma_f32_16x16x32_bf16 v[52:55], v[204:207], v[212:215], v[52:55]
	global_load_dwordx4 v[152:155], v[152:153], off offset:256
	v_mfma_f32_16x16x32_bf16 v[48:51], v[208:211], v[212:215], v[48:51]
	ds_read_b128 v[246:249], v176 offset:16192
	s_waitcnt lgkmcnt(2)
	v_mfma_f32_16x16x32_bf16 v[44:47], v[178:181], v[216:219], v[44:47]
	global_load_dwordx4 v[156:159], v[156:157], off offset:256
	v_mfma_f32_16x16x32_bf16 v[40:43], v[200:203], v[216:219], v[40:43]
	v_mfma_f32_16x16x32_bf16 v[36:39], v[204:207], v[216:219], v[36:39]
	v_mfma_f32_16x16x32_bf16 v[32:35], v[208:211], v[216:219], v[32:35]
	s_waitcnt lgkmcnt(0)
	s_barrier
; DI f32x4 mfma16(bf16x8 a, bf16x8 b, f32x4 c) { return __builtin_amdgcn_mfma_f32_16x16x32_bf16(a, b, c, 0, 0, 0); }
; template <int MI, int NJ, bool SWAP, class AP, class BP>
; DI void gemm_main(f32x4 (&acc)[MI][NJ], const AP& ap, int a_kstep, const BP& bp, int b_kstep, int nk, bf16_t* smem) {
;     ...
;   for (int kt = 0; kt < nk; ++kt) {
;     const int buf = kt & 1;
;     sstore(buf ^ 1);
;     gload(kt + 2 < nk ? kt + 2 : nk - 1);
;     __builtin_amdgcn_sched_barrier(0);
;     const bf16_t* As = smem + buf * L::STAGE + (wm * 16 * MI + l15) * LDT + quad * 8;
;     const bf16_t* Bs = smem + buf * L::STAGE + L::A_ELEMS + (wn * 16 * NJ + l15) * LDT + quad * 8;
; #pragma unroll
;     for (int ks = 0; ks < 2; ++ks) {
;       if (MI * NJ >= 32 && ks == 1) asm volatile("" ::: "memory");
;       bf16x8 b[NJ];
; #pragma unroll
;       for (int j = 0; j < NJ; ++j) b[j] = *(const bf16x8*)(Bs + j * 16 * LDT + ks * 32);
; #pragma unroll
;       for (int i = 0; i < MI; ++i) {
;         const bf16x8 a = *(const bf16x8*)(As + i * 16 * LDT + ks * 32);
; #pragma unroll
;         for (int j = 0; j < NJ; ++j) acc[i][j] = SWAP ? mfma16(b[j], a, acc[i][j]) : mfma16(a, b[j], acc[i][j]);
;       }
;     }
;     __syncthreads();
;   }
	s_add_i32 s4, s4, 1
	s_cmp_lg_u32 s4, 16
	s_cbranch_scc0 .Lgm0_exit
	s_and_b32 s98, s4, 1
	s_mul_i32 s98, s98, 0x12000
	v_add3_u32 v182, s98, v168, v172
	v_add3_u32 v176, s98, v170, v172
	ds_read_b128 v[212:215], v176
	ds_read_b128 v[216:219], v176 offset:2304
	v_mfma_f32_16x16x32_bf16 v[28:31], v[178:181], v[242:245], v[28:31]
	v_mfma_f32_16x16x32_bf16 v[12:15], v[178:181], v[246:249], v[12:15]
	ds_read_b128 v[178:181], v182 offset:36864
	v_mfma_f32_16x16x32_bf16 v[24:27], v[200:203], v[242:245], v[24:27]
	v_mfma_f32_16x16x32_bf16 v[8:11], v[200:203], v[246:249], v[8:11]
	ds_read_b128 v[200:203], v182 offset:39168
	v_mfma_f32_16x16x32_bf16 v[20:23], v[204:207], v[242:245], v[20:23]
	v_mfma_f32_16x16x32_bf16 v[0:3], v[204:207], v[246:249], v[0:3]
	ds_read_b128 v[204:207], v182 offset:41472
	v_mfma_f32_16x16x32_bf16 v[16:19], v[208:211], v[242:245], v[16:19]
	v_mfma_f32_16x16x32_bf16 v[4:7], v[208:211], v[246:249], v[4:7]
	ds_read_b128 v[208:211], v182 offset:43776
	s_branch .Lgm0_main

; DI f32x4 mfma16(bf16x8 a, bf16x8 b, f32x4 c) { return __builtin_amdgcn_mfma_f32_16x16x32_bf16(a, b, c, 0, 0, 0); }
; template <int MI, int NJ, bool SWAP, class AP, class BP>
; DI void gemm_main(f32x4 (&acc)[MI][NJ], const AP& ap, int a_kstep, const BP& bp, int b_kstep, int nk, bf16_t* smem) {
;     ...
;   for (int kt = 0; kt < nk; ++kt) {
;     const int buf = kt & 1;
;     sstore(buf ^ 1);
;     gload(kt + 2 < nk ? kt + 2 : nk - 1);
;     __builtin_amdgcn_sched_barrier(0);
;     const bf16_t* As = smem + buf * L::STAGE + (wm * 16 * MI + l15) * LDT + quad * 8;
;     const bf16_t* Bs = smem + buf * L::STAGE + L::A_ELEMS + (wn * 16 * NJ + l15) * LDT + quad * 8;
; #pragma unroll
;     for (int ks = 0; ks < 2; ++ks) {
;       if (MI * NJ >= 32 && ks == 1) asm volatile("" ::: "memory");
;       bf16x8 b[NJ];
; #pragma unroll
;       for (int j = 0; j < NJ; ++j) b[j] = *(const bf16x8*)(Bs + j * 16 * LDT + ks * 32);
; #pragma unroll
;       for (int i = 0; i < MI; ++i) {
;         const bf16x8 a = *(const bf16x8*)(As + i * 16 * LDT + ks * 32);
; #pragma unroll
;         for (int j = 0; j < NJ; ++j) acc[i][j] = SWAP ? mfma16(b[j], a, acc[i][j]) : mfma16(a, b[j], acc[i][j]);
;       }
;     }
;     __syncthreads();
;   }
.Lgm1_main:
	ds_read_b128 v[242:245], v176 offset:4608
	s_waitcnt lgkmcnt(4)
	v_mfma_f32_16x16x32_bf16 v[124:127], v[212:215], v[178:181], v[124:127]
	s_waitcnt lgkmcnt(3)
	v_mfma_f32_16x16x32_bf16 v[120:123], v[212:215], v[200:203], v[120:123]
	s_waitcnt lgkmcnt(2)
	v_mfma_f32_16x16x32_bf16 v[116:119], v[212:215], v[204:207], v[116:119]
	s_waitcnt lgkmcnt(1)
	v_mfma_f32_16x16x32_bf16 v[112:115], v[212:215], v[208:211], v[112:115]
	s_and_b32 s5, s4, 1
	s_min_u32 s6, s4, 13
	s_xor_b32 s7, s5, 1
	s_lshl_b32 s33, s6, 7
	v_lshlrev_b32_e32 v250, 1, v168
	v_lshlrev_b32_e32 v251, 1, v171
	v_lshlrev_b32_e32 v252, 1, v172
	v_lshlrev_b32_e32 v253, 1, v173
	s_mul_i32 s7, s7, 0x12000
	s_add_u32 s6, s0, s33
	v_add3_u32 v250, s7, v250, v170
	v_add3_u32 v251, s7, v251, v170
	v_add3_u32 v252, s7, v252, v170
	v_add3_u32 v253, s7, v253, v170
	s_addc_u32 s7, s1, 0
	s_waitcnt vmcnt(7)
	ds_write_b128 v250, v[128:131]
	ds_read_b128 v[246:249], v176 offset:6912
	v_mfma_f32_16x16x32_bf16 v[108:111], v[216:219], v[178:181], v[108:111]
	v_mfma_f32_16x16x32_bf16 v[104:107], v[216:219], v[200:203], v[104:107]
	v_mfma_f32_16x16x32_bf16 v[100:103], v[216:219], v[204:207], v[100:103]
	v_mfma_f32_16x16x32_bf16 v[96:99], v[216:219], v[208:211], v[96:99]
	s_waitcnt vmcnt(6)
	ds_write_b128 v251, v[132:135]
	ds_read_b128 v[212:215], v176 offset:9216
	s_waitcnt lgkmcnt(4)
	v_mfma_f32_16x16x32_bf16 v[92:95], v[242:245], v[178:181], v[92:95]
	v_mfma_f32_16x16x32_bf16 v[88:91], v[242:245], v[200:203], v[88:91]
	v_mfma_f32_16x16x32_bf16 v[84:87], v[242:245], v[204:207], v[84:87]
	v_mfma_f32_16x16x32_bf16 v[80:83], v[242:245], v[208:211], v[80:83]
	ds_read_b128 v[216:219], v176 offset:11520
	s_waitcnt lgkmcnt(3)
	v_mfma_f32_16x16x32_bf16 v[76:79], v[246:249], v[178:181], v[76:79]
	s_waitcnt vmcnt(5)
	ds_write_b128 v252, v[136:139]
	v_mfma_f32_16x16x32_bf16 v[72:75], v[246:249], v[200:203], v[72:75]
	v_mfma_f32_16x16x32_bf16 v[68:71], v[246:249], v[204:207], v[68:71]
	v_mfma_f32_16x16x32_bf16 v[64:67], v[246:249], v[208:211], v[64:67]
	ds_read_b128 v[242:245], v176 offset:13824
	s_waitcnt lgkmcnt(3)
	v_mfma_f32_16x16x32_bf16 v[60:63], v[212:215], v[178:181], v[60:63]
	s_waitcnt vmcnt(4)
	ds_write_b128 v253, v[140:143]
	v_mfma_f32_16x16x32_bf16 v[56:59], v[212:215], v[200:203], v[56:59]
	v_mfma_f32_16x16x32_bf16 v[52:55], v[212:215], v[204:207], v[52:55]
	v_mfma_f32_16x16x32_bf16 v[48:51], v[212:215], v[208:211], v[48:51]
	ds_read_b128 v[246:249], v176 offset:16128
	s_waitcnt lgkmcnt(4)
	v_mfma_f32_16x16x32_bf16 v[44:47], v[216:219], v[178:181], v[44:47]
	s_waitcnt vmcnt(3)
	ds_write_b128 v250, v[144:147] offset:36864
	v_mfma_f32_16x16x32_bf16 v[40:43], v[216:219], v[200:203], v[40:43]
	v_mfma_f32_16x16x32_bf16 v[36:39], v[216:219], v[204:207], v[36:39]
	v_mfma_f32_16x16x32_bf16 v[32:35], v[216:219], v[208:211], v[32:35]
	ds_read_b128 v[212:215], v176 offset:64
	s_waitcnt lgkmcnt(4)
	v_mfma_f32_16x16x32_bf16 v[28:31], v[242:245], v[178:181], v[28:31]
	s_waitcnt vmcnt(2)
	ds_write_b128 v251, v[148:151] offset:36864
	v_mfma_f32_16x16x32_bf16 v[24:27], v[242:245], v[200:203], v[24:27]
	v_mfma_f32_16x16x32_bf16 v[20:23], v[242:245], v[204:207], v[20:23]
	v_mfma_f32_16x16x32_bf16 v[16:19], v[242:245], v[208:211], v[16:19]
	ds_read_b128 v[216:219], v176 offset:2368
	s_waitcnt lgkmcnt(4)
	v_mfma_f32_16x16x32_bf16 v[8:11], v[246:249], v[178:181], v[8:11]
	ds_read_b128 v[178:181], v182 offset:36928
	s_waitcnt vmcnt(1)
	ds_write_b128 v252, v[152:155] offset:36864
	v_mfma_f32_16x16x32_bf16 v[4:7], v[246:249], v[200:203], v[4:7]
	ds_read_b128 v[200:203], v182 offset:39232
	v_mfma_f32_16x16x32_bf16 v[0:3], v[246:249], v[204:207], v[0:3]
	ds_read_b128 v[204:207], v182 offset:41536
	v_mfma_f32_16x16x32_bf16 v[12:15], v[246:249], v[208:211], v[12:15]
	ds_read_b128 v[208:211], v182 offset:43840
	ds_read_b128 v[242:245], v176 offset:4672
	s_waitcnt lgkmcnt(5)
	v_mfma_f32_16x16x32_bf16 v[124:127], v[212:215], v[178:181], v[124:127]
	s_waitcnt lgkmcnt(3)
	v_mfma_f32_16x16x32_bf16 v[120:123], v[212:215], v[200:203], v[120:123]
	s_waitcnt vmcnt(0)
	ds_write_b128 v253, v[156:159] offset:36864
	s_waitcnt lgkmcnt(3)
	v_mfma_f32_16x16x32_bf16 v[116:119], v[212:215], v[204:207], v[116:119]
	s_waitcnt lgkmcnt(2)
	v_mfma_f32_16x16x32_bf16 v[112:115], v[212:215], v[208:211], v[112:115]
	v_lshl_add_u64 v[128:129], s[6:7], 0, v[160:161]
	v_lshl_add_u64 v[132:133], s[6:7], 0, v[162:163]
	v_lshl_add_u64 v[136:137], s[6:7], 0, v[164:165]
	v_lshl_add_u64 v[140:141], s[6:7], 0, v[166:167]
	s_add_u32 s6, s2, s33
	s_addc_u32 s7, s3, 0
	v_lshl_add_u64 v[144:145], s[6:7], 0, v[160:161]
	v_lshl_add_u64 v[148:149], s[6:7], 0, v[162:163]
	v_lshl_add_u64 v[152:153], s[6:7], 0, v[164:165]
	v_lshl_add_u64 v[156:157], s[6:7], 0, v[166:167]
	global_load_dwordx4 v[128:131], v[128:129], off offset:256
	ds_read_b128 v[246:249], v176 offset:6976
	v_mfma_f32_16x16x32_bf16 v[108:111], v[216:219], v[178:181], v[108:111]
	v_mfma_f32_16x16x32_bf16 v[104:107], v[216:219], v[200:203], v[104:107]
	global_load_dwordx4 v[132:135], v[132:133], off offset:256
	v_mfma_f32_16x16x32_bf16 v[100:103], v[216:219], v[204:207], v[100:103]
	v_mfma_f32_16x16x32_bf16 v[96:99], v[216:219], v[208:211], v[96:99]
	ds_read_b128 v[212:215], v176 offset:9280
	s_waitcnt lgkmcnt(3)
	v_mfma_f32_16x16x32_bf16 v[92:95], v[242:245], v[178:181], v[92:95]
	global_load_dwordx4 v[136:139], v[136:137], off offset:256
	v_mfma_f32_16x16x32_bf16 v[88:91], v[242:245], v[200:203], v[88:91]
	v_mfma_f32_16x16x32_bf16 v[84:87], v[242:245], v[204:207], v[84:87]
	global_load_dwordx4 v[140:143], v[140:141], off offset:256
	v_mfma_f32_16x16x32_bf16 v[80:83], v[242:245], v[208:211], v[80:83]
	ds_read_b128 v[216:219], v176 offset:11584
	s_waitcnt lgkmcnt(2)
	v_mfma_f32_16x16x32_bf16 v[76:79], v[246:249], v[178:181], v[76:79]
	v_mfma_f32_16x16x32_bf16 v[72:75], v[246:249], v[200:203], v[72:75]
	global_load_dwordx4 v[144:147], v[144:145], off offset:256
	v_mfma_f32_16x16x32_bf16 v[68:71], v[246:249], v[204:207], v[68:71]
	v_mfma_f32_16x16x32_bf16 v[64:67], v[246:249], v[208:211], v[64:67]
	global_load_dwordx4 v[148:151], v[148:149], off offset:256
	ds_read_b128 v[242:245], v176 offset:13888
	s_waitcnt lgkmcnt(2)
	v_mfma_f32_16x16x32_bf16 v[60:63], v[212:215], v[178:181], v[60:63]
	v_mfma_f32_16x16x32_bf16 v[56:59], v[212:215], v[200:203], v[56:59]
	v_mfma_f32_16x16x32_bf16 v[52:55], v[212:215], v[204:207], v[52:55]
	global_load_dwordx4 v[152:155], v[152:153], off offset:256
	v_mfma_f32_16x16x32_bf16 v[48:51], v[212:215], v[208:211], v[48:51]
	ds_read_b128 v[246:249], v176 offset:16192
	s_waitcnt lgkmcnt(2)
	v_mfma_f32_16x16x32_bf16 v[44:47], v[216:219], v[178:181], v[44:47]
	global_load_dwordx4 v[156:159], v[156:157], off offset:256
	v_mfma_f32_16x16x32_bf16 v[40:43], v[216:219], v[200:203], v[40:43]
	v_mfma_f32_16x16x32_bf16 v[36:39], v[216:219], v[204:207], v[36:39]
	v_mfma_f32_16x16x32_bf16 v[32:35], v[216:219], v[208:211], v[32:35]
	s_waitcnt lgkmcnt(0)
	s_barrier
; DI f32x4 mfma16(bf16x8 a, bf16x8 b, f32x4 c) { return __builtin_amdgcn_mfma_f32_16x16x32_bf16(a, b, c, 0, 0, 0); }
; template <int MI, int NJ, bool SWAP, class AP, class BP>
; DI void gemm_main(f32x4 (&acc)[MI][NJ], const AP& ap, int a_kstep, const BP& bp, int b_kstep, int nk, bf16_t* smem) {
;     ...
;   for (int kt = 0; kt < nk; ++kt) {
;     const int buf = kt & 1;
;     sstore(buf ^ 1);
;     gload(kt + 2 < nk ? kt + 2 : nk - 1);
;     __builtin_amdgcn_sched_barrier(0);
;     const bf16_t* As = smem + buf * L::STAGE + (wm * 16 * MI + l15) * LDT + quad * 8;
;     const bf16_t* Bs = smem + buf * L::STAGE + L::A_ELEMS + (wn * 16 * NJ + l15) * LDT + quad * 8;
; #pragma unroll
;     for (int ks = 0; ks < 2; ++ks) {
;       if (MI * NJ >= 32 && ks == 1) asm volatile("" ::: "memory");
;       bf16x8 b[NJ];
; #pragma unroll
;       for (int j = 0; j < NJ; ++j) b[j] = *(const bf16x8*)(Bs + j * 16 * LDT + ks * 32);
; #pragma unroll
;       for (int i = 0; i < MI; ++i) {
;         const bf16x8 a = *(const bf16x8*)(As + i * 16 * LDT + ks * 32);
; #pragma unroll
;         for (int j = 0; j < NJ; ++j) acc[i][j] = SWAP ? mfma16(b[j], a, acc[i][j]) : mfma16(a, b[j], acc[i][j]);
;       }
;     }
;     __syncthreads();
;   }
	s_add_i32 s4, s4, 1
	s_cmp_lg_u32 s4, 16
	s_cbranch_scc0 .Lgm1_exit
	s_and_b32 s98, s4, 1
	s_mul_i32 s98, s98, 0x12000
	v_add3_u32 v176, s98, v174, v175
	v_add3_u32 v182, s98, v169, v175
	ds_read_b128 v[212:215], v176
	ds_read_b128 v[216:219], v176 offset:2304
	v_mfma_f32_16x16x32_bf16 v[28:31], v[242:245], v[178:181], v[28:31]
	v_mfma_f32_16x16x32_bf16 v[8:11], v[246:249], v[178:181], v[8:11]
	ds_read_b128 v[178:181], v182 offset:36864
	v_mfma_f32_16x16x32_bf16 v[24:27], v[242:245], v[200:203], v[24:27]
	v_mfma_f32_16x16x32_bf16 v[4:7], v[246:249], v[200:203], v[4:7]
	ds_read_b128 v[200:203], v182 offset:39168
	v_mfma_f32_16x16x32_bf16 v[20:23], v[242:245], v[204:207], v[20:23]
	v_mfma_f32_16x16x32_bf16 v[0:3], v[246:249], v[204:207], v[0:3]
	ds_read_b128 v[204:207], v182 offset:41472
	v_mfma_f32_16x16x32_bf16 v[16:19], v[242:245], v[208:211], v[16:19]
	v_mfma_f32_16x16x32_bf16 v[12:15], v[246:249], v[208:211], v[12:15]
	ds_read_b128 v[208:211], v182 offset:43776
	s_branch .Lgm1_main

; DI f32x4 mfma16(bf16x8 a, bf16x8 b, f32x4 c) { return __builtin_amdgcn_mfma_f32_16x16x32_bf16(a, b, c, 0, 0, 0); }
; template <int MI, int NJ, bool SWAP, class AP, class BP>
; DI void gemm_main(f32x4 (&acc)[MI][NJ], const AP& ap, int a_kstep, const BP& bp, int b_kstep, int nk, bf16_t* smem) {
;     ...
;   for (int kt = 0; kt < nk; ++kt) {
;     const int buf = kt & 1;
;     sstore(buf ^ 1);
;     gload(kt + 2 < nk ? kt + 2 : nk - 1);
;     __builtin_amdgcn_sched_barrier(0);
;     const bf16_t* As = smem + buf * L::STAGE + (wm * 16 * MI + l15) * LDT + quad * 8;
;     const bf16_t* Bs = smem + buf * L::STAGE + L::A_ELEMS + (wn * 16 * NJ + l15) * LDT + quad * 8;
; #pragma unroll
;     for (int ks = 0; ks < 2; ++ks) {
;       if (MI * NJ >= 32 && ks == 1) asm volatile("" ::: "memory");
;       bf16x8 b[NJ];
; #pragma unroll
;       for (int j = 0; j < NJ; ++j) b[j] = *(const bf16x8*)(Bs + j * 16 * LDT + ks * 32);
; #pragma unroll
;       for (int i = 0; i < MI; ++i) {
;         const bf16x8 a = *(const bf16x8*)(As + i * 16 * LDT + ks * 32);
; #pragma unroll
;         for (int j = 0; j < NJ; ++j) acc[i][j] = SWAP ? mfma16(b[j], a, acc[i][j]) : mfma16(a, b[j], acc[i][j]);
;       }
;     }
;     __syncthreads();
;   }
.Lgm2_main:
	ds_read_b128 v[242:245], v182 offset:4608
	s_waitcnt lgkmcnt(4)
	v_mfma_f32_16x16x32_bf16 v[156:159], v[178:181], v[198:201], v[156:159]
	s_waitcnt lgkmcnt(3)
	v_mfma_f32_16x16x32_bf16 v[152:155], v[186:189], v[198:201], v[152:155]
	s_waitcnt lgkmcnt(2)
	v_mfma_f32_16x16x32_bf16 v[148:151], v[190:193], v[198:201], v[148:151]
	s_waitcnt lgkmcnt(1)
	v_mfma_f32_16x16x32_bf16 v[144:147], v[194:197], v[198:201], v[144:147]
	s_and_b32 s33, s16, 1
	s_min_u32 s52, s16, 3
	s_xor_b32 s53, s33, 1
	s_lshl_b32 s54, s52, 7
	s_mul_i32 s53, s53, 0x12000
	s_add_u32 s52, s0, s54
	v_add3_u32 v250, s53, v173, v171
	v_add3_u32 v251, s53, v174, v171
	v_add3_u32 v252, s53, v175, v171
	v_add3_u32 v253, s53, v176, v171
	s_addc_u32 s53, s1, 0
	s_waitcnt vmcnt(7)
	ds_write_b128 v250, v[112:115]
	ds_read_b128 v[246:249], v182 offset:6912
	v_mfma_f32_16x16x32_bf16 v[108:111], v[178:181], v[202:205], v[108:111]
	v_mfma_f32_16x16x32_bf16 v[104:107], v[186:189], v[202:205], v[104:107]
	v_mfma_f32_16x16x32_bf16 v[100:103], v[190:193], v[202:205], v[100:103]
	v_mfma_f32_16x16x32_bf16 v[96:99], v[194:197], v[202:205], v[96:99]
	s_waitcnt vmcnt(5)
	ds_write_b128 v251, v[116:119]
	ds_read_b128 v[198:201], v182 offset:9216
	s_waitcnt lgkmcnt(4)
	v_mfma_f32_16x16x32_bf16 v[92:95], v[178:181], v[242:245], v[92:95]
	v_mfma_f32_16x16x32_bf16 v[88:91], v[186:189], v[242:245], v[88:91]
	v_mfma_f32_16x16x32_bf16 v[84:87], v[190:193], v[242:245], v[84:87]
	v_mfma_f32_16x16x32_bf16 v[80:83], v[194:197], v[242:245], v[80:83]
	ds_read_b128 v[202:205], v182 offset:11520
	s_waitcnt lgkmcnt(3)
	v_mfma_f32_16x16x32_bf16 v[76:79], v[178:181], v[246:249], v[76:79]
	s_waitcnt vmcnt(4)
	ds_write_b128 v252, v[120:123]
	v_mfma_f32_16x16x32_bf16 v[72:75], v[186:189], v[246:249], v[72:75]
	v_mfma_f32_16x16x32_bf16 v[68:71], v[190:193], v[246:249], v[68:71]
	v_mfma_f32_16x16x32_bf16 v[64:67], v[194:197], v[246:249], v[64:67]
	ds_read_b128 v[242:245], v182 offset:13824
	s_waitcnt lgkmcnt(3)
	v_mfma_f32_16x16x32_bf16 v[60:63], v[178:181], v[198:201], v[60:63]
	s_waitcnt vmcnt(3)
	ds_write_b128 v253, v[124:127]
	v_mfma_f32_16x16x32_bf16 v[56:59], v[186:189], v[198:201], v[56:59]
	v_mfma_f32_16x16x32_bf16 v[52:55], v[190:193], v[198:201], v[52:55]
	v_mfma_f32_16x16x32_bf16 v[48:51], v[194:197], v[198:201], v[48:51]
	ds_read_b128 v[246:249], v182 offset:16128
	s_waitcnt lgkmcnt(4)
	v_mfma_f32_16x16x32_bf16 v[44:47], v[178:181], v[202:205], v[44:47]
	ds_write_b128 v250, v[128:131] offset:36864
	v_mfma_f32_16x16x32_bf16 v[40:43], v[186:189], v[202:205], v[40:43]
	v_mfma_f32_16x16x32_bf16 v[36:39], v[190:193], v[202:205], v[36:39]
	v_mfma_f32_16x16x32_bf16 v[32:35], v[194:197], v[202:205], v[32:35]
	ds_read_b128 v[198:201], v182 offset:64
	s_waitcnt lgkmcnt(4)
	v_mfma_f32_16x16x32_bf16 v[28:31], v[178:181], v[242:245], v[28:31]
	s_waitcnt vmcnt(2)
	ds_write_b128 v251, v[132:135] offset:36864
	v_mfma_f32_16x16x32_bf16 v[24:27], v[186:189], v[242:245], v[24:27]
	v_mfma_f32_16x16x32_bf16 v[20:23], v[190:193], v[242:245], v[20:23]
	v_mfma_f32_16x16x32_bf16 v[16:19], v[194:197], v[242:245], v[16:19]
	ds_read_b128 v[202:205], v182 offset:2368
	s_waitcnt lgkmcnt(4)
	v_mfma_f32_16x16x32_bf16 v[8:11], v[178:181], v[246:249], v[8:11]
	ds_read_b128 v[178:181], v183 offset:36928
	s_waitcnt vmcnt(1)
	ds_write_b128 v252, v[136:139] offset:36864
	v_mfma_f32_16x16x32_bf16 v[4:7], v[186:189], v[246:249], v[4:7]
	ds_read_b128 v[186:189], v183 offset:39232
	v_mfma_f32_16x16x32_bf16 v[0:3], v[190:193], v[246:249], v[0:3]
	ds_read_b128 v[190:193], v183 offset:41536
	v_mfma_f32_16x16x32_bf16 v[12:15], v[194:197], v[246:249], v[12:15]
	ds_read_b128 v[194:197], v183 offset:43840
	ds_read_b128 v[242:245], v182 offset:4672
	s_waitcnt lgkmcnt(5)
	v_mfma_f32_16x16x32_bf16 v[156:159], v[178:181], v[198:201], v[156:159]
	s_waitcnt lgkmcnt(3)
	v_mfma_f32_16x16x32_bf16 v[152:155], v[186:189], v[198:201], v[152:155]
	s_waitcnt vmcnt(0)
	ds_write_b128 v253, v[140:143] offset:36864
	s_waitcnt lgkmcnt(3)
	v_mfma_f32_16x16x32_bf16 v[148:151], v[190:193], v[198:201], v[148:151]
	s_waitcnt lgkmcnt(2)
	v_mfma_f32_16x16x32_bf16 v[144:147], v[194:197], v[198:201], v[144:147]
	v_lshl_add_u64 v[112:113], s[52:53], 0, v[162:163]
	v_lshl_add_u64 v[116:117], s[52:53], 0, v[164:165]
	v_lshl_add_u64 v[120:121], s[52:53], 0, v[166:167]
	v_lshl_add_u64 v[124:125], s[52:53], 0, v[168:169]
	s_add_u32 s52, s2, s54
	s_addc_u32 s53, s3, 0
	v_lshl_add_u64 v[128:129], s[52:53], 0, v[162:163]
	v_lshl_add_u64 v[132:133], s[52:53], 0, v[164:165]
	v_lshl_add_u64 v[136:137], s[52:53], 0, v[166:167]
	v_lshl_add_u64 v[140:141], s[52:53], 0, v[168:169]
	global_load_dwordx4 v[112:115], v[112:113], off offset:256
	ds_read_b128 v[246:249], v182 offset:6976
	v_mfma_f32_16x16x32_bf16 v[108:111], v[178:181], v[202:205], v[108:111]
	v_mfma_f32_16x16x32_bf16 v[104:107], v[186:189], v[202:205], v[104:107]
	global_load_dwordx4 v[116:119], v[116:117], off offset:256
	v_mfma_f32_16x16x32_bf16 v[100:103], v[190:193], v[202:205], v[100:103]
	v_mfma_f32_16x16x32_bf16 v[96:99], v[194:197], v[202:205], v[96:99]
	ds_read_b128 v[198:201], v182 offset:9280
	s_waitcnt lgkmcnt(3)
	v_mfma_f32_16x16x32_bf16 v[92:95], v[178:181], v[242:245], v[92:95]
	global_load_dwordx4 v[120:123], v[120:121], off offset:256
	v_mfma_f32_16x16x32_bf16 v[88:91], v[186:189], v[242:245], v[88:91]
	v_mfma_f32_16x16x32_bf16 v[84:87], v[190:193], v[242:245], v[84:87]
	global_load_dwordx4 v[124:127], v[124:125], off offset:256
	v_mfma_f32_16x16x32_bf16 v[80:83], v[194:197], v[242:245], v[80:83]
	ds_read_b128 v[202:205], v182 offset:11584
	s_waitcnt lgkmcnt(2)
	v_mfma_f32_16x16x32_bf16 v[76:79], v[178:181], v[246:249], v[76:79]
	v_mfma_f32_16x16x32_bf16 v[72:75], v[186:189], v[246:249], v[72:75]
	global_load_dwordx4 v[128:131], v[128:129], off offset:256
	v_mfma_f32_16x16x32_bf16 v[68:71], v[190:193], v[246:249], v[68:71]
	v_mfma_f32_16x16x32_bf16 v[64:67], v[194:197], v[246:249], v[64:67]
	global_load_dwordx4 v[132:135], v[132:133], off offset:256
	ds_read_b128 v[242:245], v182 offset:13888
	s_waitcnt lgkmcnt(2)
	v_mfma_f32_16x16x32_bf16 v[60:63], v[178:181], v[198:201], v[60:63]
	v_mfma_f32_16x16x32_bf16 v[56:59], v[186:189], v[198:201], v[56:59]
	v_mfma_f32_16x16x32_bf16 v[52:55], v[190:193], v[198:201], v[52:55]
	global_load_dwordx4 v[136:139], v[136:137], off offset:256
	v_mfma_f32_16x16x32_bf16 v[48:51], v[194:197], v[198:201], v[48:51]
	ds_read_b128 v[246:249], v182 offset:16192
	s_waitcnt lgkmcnt(2)
	v_mfma_f32_16x16x32_bf16 v[44:47], v[178:181], v[202:205], v[44:47]
	global_load_dwordx4 v[140:143], v[140:141], off offset:256
	v_mfma_f32_16x16x32_bf16 v[40:43], v[186:189], v[202:205], v[40:43]
	v_mfma_f32_16x16x32_bf16 v[36:39], v[190:193], v[202:205], v[36:39]
	v_mfma_f32_16x16x32_bf16 v[32:35], v[194:197], v[202:205], v[32:35]
	s_waitcnt lgkmcnt(0)
	s_barrier
; DI f32x4 mfma16(bf16x8 a, bf16x8 b, f32x4 c) { return __builtin_amdgcn_mfma_f32_16x16x32_bf16(a, b, c, 0, 0, 0); }
; template <int MI, int NJ, bool SWAP, class AP, class BP>
; DI void gemm_main(f32x4 (&acc)[MI][NJ], const AP& ap, int a_kstep, const BP& bp, int b_kstep, int nk, bf16_t* smem) {
;     ...
;   for (int kt = 0; kt < nk; ++kt) {
;     const int buf = kt & 1;
;     sstore(buf ^ 1);
;     gload(kt + 2 < nk ? kt + 2 : nk - 1);
;     __builtin_amdgcn_sched_barrier(0);
;     const bf16_t* As = smem + buf * L::STAGE + (wm * 16 * MI + l15) * LDT + quad * 8;
;     const bf16_t* Bs = smem + buf * L::STAGE + L::A_ELEMS + (wn * 16 * NJ + l15) * LDT + quad * 8;
; #pragma unroll
;     for (int ks = 0; ks < 2; ++ks) {
;       if (MI * NJ >= 32 && ks == 1) asm volatile("" ::: "memory");
;       bf16x8 b[NJ];
; #pragma unroll
;       for (int j = 0; j < NJ; ++j) b[j] = *(const bf16x8*)(Bs + j * 16 * LDT + ks * 32);
; #pragma unroll
;       for (int i = 0; i < MI; ++i) {
;         const bf16x8 a = *(const bf16x8*)(As + i * 16 * LDT + ks * 32);
; #pragma unroll
;         for (int j = 0; j < NJ; ++j) acc[i][j] = SWAP ? mfma16(b[j], a, acc[i][j]) : mfma16(a, b[j], acc[i][j]);
;       }
;     }
;     __syncthreads();
;   }
	s_add_i32 s16, s16, 1
	s_cmp_lg_u32 s16, 6
	s_cbranch_scc0 .Lgm2_exit
	s_and_b32 s98, s16, 1
	s_mul_i32 s98, s98, 0x12000
	v_add3_u32 v183, s98, v160, v177
	v_add3_u32 v182, s98, v172, v177
	ds_read_b128 v[198:201], v182
	ds_read_b128 v[202:205], v182 offset:2304
	v_mfma_f32_16x16x32_bf16 v[28:31], v[178:181], v[242:245], v[28:31]
	v_mfma_f32_16x16x32_bf16 v[8:11], v[178:181], v[246:249], v[8:11]
	ds_read_b128 v[178:181], v183 offset:36864
	v_mfma_f32_16x16x32_bf16 v[24:27], v[186:189], v[242:245], v[24:27]
	v_mfma_f32_16x16x32_bf16 v[4:7], v[186:189], v[246:249], v[4:7]
	ds_read_b128 v[186:189], v183 offset:39168
	v_mfma_f32_16x16x32_bf16 v[20:23], v[190:193], v[242:245], v[20:23]
	v_mfma_f32_16x16x32_bf16 v[0:3], v[190:193], v[246:249], v[0:3]
	ds_read_b128 v[190:193], v183 offset:41472
	v_mfma_f32_16x16x32_bf16 v[16:19], v[194:197], v[242:245], v[16:19]
	v_mfma_f32_16x16x32_bf16 v[12:15], v[194:197], v[246:249], v[12:15]
	ds_read_b128 v[194:197], v183 offset:43776
	s_branch .Lgm2_main

; DI f32x4 mfma16(bf16x8 a, bf16x8 b, f32x4 c) { return __builtin_amdgcn_mfma_f32_16x16x32_bf16(a, b, c, 0, 0, 0); }
; template <int MI, int NJ, bool SWAP, class AP, class BP>
; DI void gemm_main(f32x4 (&acc)[MI][NJ], const AP& ap, int a_kstep, const BP& bp, int b_kstep, int nk, bf16_t* smem) {
;     ...
;   for (int kt = 0; kt < nk; ++kt) {
;     const int buf = kt & 1;
;     sstore(buf ^ 1);
;     gload(kt + 2 < nk ? kt + 2 : nk - 1);
;     __builtin_amdgcn_sched_barrier(0);
;     const bf16_t* As = smem + buf * L::STAGE + (wm * 16 * MI + l15) * LDT + quad * 8;
;     const bf16_t* Bs = smem + buf * L::STAGE + L::A_ELEMS + (wn * 16 * NJ + l15) * LDT + quad * 8;
; #pragma unroll
;     for (int ks = 0; ks < 2; ++ks) {
;       if (MI * NJ >= 32 && ks == 1) asm volatile("" ::: "memory");
;       bf16x8 b[NJ];
; #pragma unroll
;       for (int j = 0; j < NJ; ++j) b[j] = *(const bf16x8*)(Bs + j * 16 * LDT + ks * 32);
; #pragma unroll
;       for (int i = 0; i < MI; ++i) {
;         const bf16x8 a = *(const bf16x8*)(As + i * 16 * LDT + ks * 32);
; #pragma unroll
;         for (int j = 0; j < NJ; ++j) acc[i][j] = SWAP ? mfma16(b[j], a, acc[i][j]) : mfma16(a, b[j], acc[i][j]);
;       }
;     }
;     __syncthreads();
;   }
.Lgm3_main:
	ds_read_b128 v[242:245], v182 offset:4608
	s_waitcnt lgkmcnt(4)
	v_mfma_f32_16x16x32_bf16 v[156:159], v[178:181], v[198:201], v[156:159]
	s_waitcnt lgkmcnt(3)
	v_mfma_f32_16x16x32_bf16 v[152:155], v[186:189], v[198:201], v[152:155]
	s_waitcnt lgkmcnt(2)
	v_mfma_f32_16x16x32_bf16 v[148:151], v[190:193], v[198:201], v[148:151]
	s_waitcnt lgkmcnt(1)
	v_mfma_f32_16x16x32_bf16 v[144:147], v[194:197], v[198:201], v[144:147]
	s_and_b32 s54, s33, 1
	s_xor_b32 s52, s54, 1
	s_cmp_eq_u32 s33, 0
	v_lshlrev_b32_e32 v250, 1, v160
	v_lshlrev_b32_e32 v251, 1, v173
	v_lshlrev_b32_e32 v252, 1, v174
	v_lshlrev_b32_e32 v253, 1, v175
	s_mul_i32 s52, s52, 0x12000
	s_cselect_b32 s55, s48, 0x180
	v_add3_u32 v250, s52, v250, v172
	v_add3_u32 v251, s52, v251, v172
	v_add3_u32 v252, s52, v252, v172
	v_add3_u32 v253, s52, v253, v172
	s_add_u32 s52, s0, s55
	s_addc_u32 s53, s1, 0
	s_waitcnt vmcnt(7)
	ds_write_b128 v250, v[112:115]
	ds_read_b128 v[246:249], v182 offset:6912
	v_mfma_f32_16x16x32_bf16 v[108:111], v[178:181], v[202:205], v[108:111]
	v_mfma_f32_16x16x32_bf16 v[104:107], v[186:189], v[202:205], v[104:107]
	v_mfma_f32_16x16x32_bf16 v[100:103], v[190:193], v[202:205], v[100:103]
	v_mfma_f32_16x16x32_bf16 v[96:99], v[194:197], v[202:205], v[96:99]
	s_waitcnt vmcnt(6)
	ds_write_b128 v251, v[116:119]
	ds_read_b128 v[198:201], v182 offset:9216
	s_waitcnt lgkmcnt(4)
	v_mfma_f32_16x16x32_bf16 v[92:95], v[178:181], v[242:245], v[92:95]
	v_mfma_f32_16x16x32_bf16 v[88:91], v[186:189], v[242:245], v[88:91]
	v_mfma_f32_16x16x32_bf16 v[84:87], v[190:193], v[242:245], v[84:87]
	v_mfma_f32_16x16x32_bf16 v[80:83], v[194:197], v[242:245], v[80:83]
	ds_read_b128 v[202:205], v182 offset:11520
	s_waitcnt lgkmcnt(3)
	v_mfma_f32_16x16x32_bf16 v[76:79], v[178:181], v[246:249], v[76:79]
	s_waitcnt vmcnt(5)
	ds_write_b128 v252, v[120:123]
	v_mfma_f32_16x16x32_bf16 v[72:75], v[186:189], v[246:249], v[72:75]
	v_mfma_f32_16x16x32_bf16 v[68:71], v[190:193], v[246:249], v[68:71]
	v_mfma_f32_16x16x32_bf16 v[64:67], v[194:197], v[246:249], v[64:67]
	ds_read_b128 v[242:245], v182 offset:13824
	s_waitcnt lgkmcnt(3)
	v_mfma_f32_16x16x32_bf16 v[60:63], v[178:181], v[198:201], v[60:63]
	s_waitcnt vmcnt(4)
	ds_write_b128 v253, v[124:127]
	v_mfma_f32_16x16x32_bf16 v[56:59], v[186:189], v[198:201], v[56:59]
	v_mfma_f32_16x16x32_bf16 v[52:55], v[190:193], v[198:201], v[52:55]
	v_mfma_f32_16x16x32_bf16 v[48:51], v[194:197], v[198:201], v[48:51]
	ds_read_b128 v[246:249], v182 offset:16128
	s_waitcnt lgkmcnt(4)
	v_mfma_f32_16x16x32_bf16 v[44:47], v[178:181], v[202:205], v[44:47]
	s_waitcnt vmcnt(3)
	ds_write_b128 v250, v[128:131] offset:36864
	v_mfma_f32_16x16x32_bf16 v[40:43], v[186:189], v[202:205], v[40:43]
	v_mfma_f32_16x16x32_bf16 v[36:39], v[190:193], v[202:205], v[36:39]
	v_mfma_f32_16x16x32_bf16 v[32:35], v[194:197], v[202:205], v[32:35]
	ds_read_b128 v[198:201], v182 offset:64
	s_waitcnt lgkmcnt(4)
	v_mfma_f32_16x16x32_bf16 v[28:31], v[178:181], v[242:245], v[28:31]
	s_waitcnt vmcnt(2)
	ds_write_b128 v251, v[132:135] offset:36864
	v_mfma_f32_16x16x32_bf16 v[24:27], v[186:189], v[242:245], v[24:27]
	v_mfma_f32_16x16x32_bf16 v[20:23], v[190:193], v[242:245], v[20:23]
	v_mfma_f32_16x16x32_bf16 v[16:19], v[194:197], v[242:245], v[16:19]
	ds_read_b128 v[202:205], v182 offset:2368
	s_waitcnt lgkmcnt(4)
	v_mfma_f32_16x16x32_bf16 v[8:11], v[178:181], v[246:249], v[8:11]
	ds_read_b128 v[178:181], v183 offset:36928
	s_waitcnt vmcnt(1)
	ds_write_b128 v252, v[136:139] offset:36864
	v_mfma_f32_16x16x32_bf16 v[4:7], v[186:189], v[246:249], v[4:7]
	ds_read_b128 v[186:189], v183 offset:39232
	v_mfma_f32_16x16x32_bf16 v[0:3], v[190:193], v[246:249], v[0:3]
	ds_read_b128 v[190:193], v183 offset:41536
	v_mfma_f32_16x16x32_bf16 v[12:15], v[194:197], v[246:249], v[12:15]
	ds_read_b128 v[194:197], v183 offset:43840
	ds_read_b128 v[242:245], v182 offset:4672
	s_waitcnt lgkmcnt(5)
	v_mfma_f32_16x16x32_bf16 v[156:159], v[178:181], v[198:201], v[156:159]
	s_waitcnt lgkmcnt(3)
	v_mfma_f32_16x16x32_bf16 v[152:155], v[186:189], v[198:201], v[152:155]
	s_waitcnt vmcnt(0)
	ds_write_b128 v253, v[140:143] offset:36864
	s_waitcnt lgkmcnt(3)
	v_mfma_f32_16x16x32_bf16 v[148:151], v[190:193], v[198:201], v[148:151]
	s_waitcnt lgkmcnt(2)
	v_mfma_f32_16x16x32_bf16 v[144:147], v[194:197], v[198:201], v[144:147]
	v_lshl_add_u64 v[112:113], s[52:53], 0, v[162:163]
	v_lshl_add_u64 v[116:117], s[52:53], 0, v[164:165]
	v_lshl_add_u64 v[120:121], s[52:53], 0, v[166:167]
	v_lshl_add_u64 v[124:125], s[52:53], 0, v[168:169]
	s_add_u32 s52, s2, s55
	s_addc_u32 s53, s3, 0
	v_lshl_add_u64 v[128:129], s[52:53], 0, v[162:163]
	v_lshl_add_u64 v[132:133], s[52:53], 0, v[164:165]
	v_lshl_add_u64 v[136:137], s[52:53], 0, v[166:167]
	v_lshl_add_u64 v[140:141], s[52:53], 0, v[168:169]
	global_load_dwordx4 v[112:115], v[112:113], off
	ds_read_b128 v[246:249], v182 offset:6976
	v_mfma_f32_16x16x32_bf16 v[108:111], v[178:181], v[202:205], v[108:111]
	v_mfma_f32_16x16x32_bf16 v[104:107], v[186:189], v[202:205], v[104:107]
	global_load_dwordx4 v[116:119], v[116:117], off
	v_mfma_f32_16x16x32_bf16 v[100:103], v[190:193], v[202:205], v[100:103]
	v_mfma_f32_16x16x32_bf16 v[96:99], v[194:197], v[202:205], v[96:99]
	ds_read_b128 v[198:201], v182 offset:9280
	s_waitcnt lgkmcnt(3)
	v_mfma_f32_16x16x32_bf16 v[92:95], v[178:181], v[242:245], v[92:95]
	global_load_dwordx4 v[120:123], v[120:121], off
	v_mfma_f32_16x16x32_bf16 v[88:91], v[186:189], v[242:245], v[88:91]
	v_mfma_f32_16x16x32_bf16 v[84:87], v[190:193], v[242:245], v[84:87]
	global_load_dwordx4 v[124:127], v[124:125], off
	v_mfma_f32_16x16x32_bf16 v[80:83], v[194:197], v[242:245], v[80:83]
	ds_read_b128 v[202:205], v182 offset:11584
	s_waitcnt lgkmcnt(2)
	v_mfma_f32_16x16x32_bf16 v[76:79], v[178:181], v[246:249], v[76:79]
	v_mfma_f32_16x16x32_bf16 v[72:75], v[186:189], v[246:249], v[72:75]
	global_load_dwordx4 v[128:131], v[128:129], off
	v_mfma_f32_16x16x32_bf16 v[68:71], v[190:193], v[246:249], v[68:71]
	v_mfma_f32_16x16x32_bf16 v[64:67], v[194:197], v[246:249], v[64:67]
	global_load_dwordx4 v[132:135], v[132:133], off
	ds_read_b128 v[242:245], v182 offset:13888
	s_waitcnt lgkmcnt(2)
	v_mfma_f32_16x16x32_bf16 v[60:63], v[178:181], v[198:201], v[60:63]
	v_mfma_f32_16x16x32_bf16 v[56:59], v[186:189], v[198:201], v[56:59]
	v_mfma_f32_16x16x32_bf16 v[52:55], v[190:193], v[198:201], v[52:55]
	global_load_dwordx4 v[136:139], v[136:137], off
	v_mfma_f32_16x16x32_bf16 v[48:51], v[194:197], v[198:201], v[48:51]
	ds_read_b128 v[246:249], v182 offset:16192
	s_waitcnt lgkmcnt(2)
	v_mfma_f32_16x16x32_bf16 v[44:47], v[178:181], v[202:205], v[44:47]
	global_load_dwordx4 v[140:143], v[140:141], off
	v_mfma_f32_16x16x32_bf16 v[40:43], v[186:189], v[202:205], v[40:43]
	v_mfma_f32_16x16x32_bf16 v[36:39], v[190:193], v[202:205], v[36:39]
	v_mfma_f32_16x16x32_bf16 v[32:35], v[194:197], v[202:205], v[32:35]
	s_waitcnt lgkmcnt(0)
	s_barrier
; DI f32x4 mfma16(bf16x8 a, bf16x8 b, f32x4 c) { return __builtin_amdgcn_mfma_f32_16x16x32_bf16(a, b, c, 0, 0, 0); }
; template <int MI, int NJ, bool SWAP, class AP, class BP>
; DI void gemm_main(f32x4 (&acc)[MI][NJ], const AP& ap, int a_kstep, const BP& bp, int b_kstep, int nk, bf16_t* smem) {
;     ...
;   for (int kt = 0; kt < nk; ++kt) {
;     const int buf = kt & 1;
;     sstore(buf ^ 1);
;     gload(kt + 2 < nk ? kt + 2 : nk - 1);
;     __builtin_amdgcn_sched_barrier(0);
;     const bf16_t* As = smem + buf * L::STAGE + (wm * 16 * MI + l15) * LDT + quad * 8;
;     const bf16_t* Bs = smem + buf * L::STAGE + L::A_ELEMS + (wn * 16 * NJ + l15) * LDT + quad * 8;
; #pragma unroll
;     for (int ks = 0; ks < 2; ++ks) {
;       if (MI * NJ >= 32 && ks == 1) asm volatile("" ::: "memory");
;       bf16x8 b[NJ];
; #pragma unroll
;       for (int j = 0; j < NJ; ++j) b[j] = *(const bf16x8*)(Bs + j * 16 * LDT + ks * 32);
; #pragma unroll
;       for (int i = 0; i < MI; ++i) {
;         const bf16x8 a = *(const bf16x8*)(As + i * 16 * LDT + ks * 32);
; #pragma unroll
;         for (int j = 0; j < NJ; ++j) acc[i][j] = SWAP ? mfma16(b[j], a, acc[i][j]) : mfma16(a, b[j], acc[i][j]);
;       }
;     }
;     __syncthreads();
;   }
	s_add_i32 s33, s33, 1
	s_cmp_lg_u32 s33, 4
	s_cbranch_scc0 .Lgm3_exit
	s_and_b32 s98, s33, 1
	s_mul_i32 s98, s98, 0x12000
	v_add3_u32 v183, s98, v171, v177
	v_add3_u32 v182, s98, v176, v177
	ds_read_b128 v[198:201], v182
	ds_read_b128 v[202:205], v182 offset:2304
	v_mfma_f32_16x16x32_bf16 v[28:31], v[178:181], v[242:245], v[28:31]
	v_mfma_f32_16x16x32_bf16 v[8:11], v[178:181], v[246:249], v[8:11]
	ds_read_b128 v[178:181], v183 offset:36864
	v_mfma_f32_16x16x32_bf16 v[24:27], v[186:189], v[242:245], v[24:27]
	v_mfma_f32_16x16x32_bf16 v[4:7], v[186:189], v[246:249], v[4:7]
	ds_read_b128 v[186:189], v183 offset:39168
	v_mfma_f32_16x16x32_bf16 v[20:23], v[190:193], v[242:245], v[20:23]
	v_mfma_f32_16x16x32_bf16 v[0:3], v[190:193], v[246:249], v[0:3]
	ds_read_b128 v[190:193], v183 offset:41472
	v_mfma_f32_16x16x32_bf16 v[16:19], v[194:197], v[242:245], v[16:19]
	v_mfma_f32_16x16x32_bf16 v[12:15], v[194:197], v[246:249], v[12:15]
	ds_read_b128 v[194:197], v183 offset:43776
	s_branch .Lgm3_main

; DI f32x4 mfma16(bf16x8 a, bf16x8 b, f32x4 c) { return __builtin_amdgcn_mfma_f32_16x16x32_bf16(a, b, c, 0, 0, 0); }
; template <int MI, int NJ, bool SWAP, class AP, class BP>
; DI void gemm_main(f32x4 (&acc)[MI][NJ], const AP& ap, int a_kstep, const BP& bp, int b_kstep, int nk, bf16_t* smem) {
;     ...
;   for (int kt = 0; kt < nk; ++kt) {
;     const int buf = kt & 1;
;     sstore(buf ^ 1);
;     gload(kt + 2 < nk ? kt + 2 : nk - 1);
;     __builtin_amdgcn_sched_barrier(0);
;     const bf16_t* As = smem + buf * L::STAGE + (wm * 16 * MI + l15) * LDT + quad * 8;
;     const bf16_t* Bs = smem + buf * L::STAGE + L::A_ELEMS + (wn * 16 * NJ + l15) * LDT + quad * 8;
; #pragma unroll
;     for (int ks = 0; ks < 2; ++ks) {
;       if (MI * NJ >= 32 && ks == 1) asm volatile("" ::: "memory");
;       bf16x8 b[NJ];
; #pragma unroll
;       for (int j = 0; j < NJ; ++j) b[j] = *(const bf16x8*)(Bs + j * 16 * LDT + ks * 32);
; #pragma unroll
;       for (int i = 0; i < MI; ++i) {
;         const bf16x8 a = *(const bf16x8*)(As + i * 16 * LDT + ks * 32);
; #pragma unroll
;         for (int j = 0; j < NJ; ++j) acc[i][j] = SWAP ? mfma16(b[j], a, acc[i][j]) : mfma16(a, b[j], acc[i][j]);
;       }
;     }
;     __syncthreads();
;   }
.Lgm4_main:
	ds_read_b128 v[242:245], v182 offset:4608
	s_waitcnt lgkmcnt(4)
	v_mfma_f32_16x16x32_bf16 v[140:143], v[198:201], v[178:181], v[140:143]
	s_waitcnt lgkmcnt(3)
	v_mfma_f32_16x16x32_bf16 v[120:123], v[198:201], v[186:189], v[120:123]
	s_waitcnt lgkmcnt(2)
	v_mfma_f32_16x16x32_bf16 v[116:119], v[198:201], v[190:193], v[116:119]
	s_waitcnt lgkmcnt(1)
	v_mfma_f32_16x16x32_bf16 v[112:115], v[198:201], v[194:197], v[112:115]
	s_and_b32 s16, s5, 1
	s_xor_b32 s33, s16, 1
	v_lshlrev_b32_e32 v250, 1, v160
	v_lshlrev_b32_e32 v251, 1, v173
	v_lshlrev_b32_e32 v252, 1, v174
	v_lshlrev_b32_e32 v253, 1, v175
	s_mul_i32 s33, s33, 0x12000
	s_cmp_eq_u32 s5, 0
	v_add3_u32 v250, s33, v250, v172
	v_add3_u32 v251, s33, v251, v172
	v_add3_u32 v252, s33, v252, v172
	v_add3_u32 v253, s33, v253, v172
	s_cselect_b32 s33, s48, 0x180
	s_add_u32 s52, s0, s33
	s_addc_u32 s53, s1, 0
	s_waitcnt vmcnt(7)
	ds_write_b128 v250, v[124:127]
	ds_read_b128 v[246:249], v182 offset:6912
	v_mfma_f32_16x16x32_bf16 v[108:111], v[202:205], v[178:181], v[108:111]
	v_mfma_f32_16x16x32_bf16 v[104:107], v[202:205], v[186:189], v[104:107]
	v_mfma_f32_16x16x32_bf16 v[100:103], v[202:205], v[190:193], v[100:103]
	v_mfma_f32_16x16x32_bf16 v[96:99], v[202:205], v[194:197], v[96:99]
	s_waitcnt vmcnt(6)
	ds_write_b128 v251, v[128:131]
	ds_read_b128 v[198:201], v182 offset:9216
	s_waitcnt lgkmcnt(4)
	v_mfma_f32_16x16x32_bf16 v[92:95], v[242:245], v[178:181], v[92:95]
	v_mfma_f32_16x16x32_bf16 v[88:91], v[242:245], v[186:189], v[88:91]
	v_mfma_f32_16x16x32_bf16 v[84:87], v[242:245], v[190:193], v[84:87]
	v_mfma_f32_16x16x32_bf16 v[80:83], v[242:245], v[194:197], v[80:83]
	ds_read_b128 v[202:205], v182 offset:11520
	s_waitcnt lgkmcnt(3)
	v_mfma_f32_16x16x32_bf16 v[76:79], v[246:249], v[178:181], v[76:79]
	s_waitcnt vmcnt(5)
	ds_write_b128 v252, v[132:135]
	v_mfma_f32_16x16x32_bf16 v[72:75], v[246:249], v[186:189], v[72:75]
	v_mfma_f32_16x16x32_bf16 v[68:71], v[246:249], v[190:193], v[68:71]
	v_mfma_f32_16x16x32_bf16 v[64:67], v[246:249], v[194:197], v[64:67]
	ds_read_b128 v[242:245], v182 offset:13824
	s_waitcnt lgkmcnt(3)
	v_mfma_f32_16x16x32_bf16 v[60:63], v[198:201], v[178:181], v[60:63]
	s_waitcnt vmcnt(4)
	ds_write_b128 v253, v[136:139]
	v_mfma_f32_16x16x32_bf16 v[56:59], v[198:201], v[186:189], v[56:59]
	v_mfma_f32_16x16x32_bf16 v[52:55], v[198:201], v[190:193], v[52:55]
	v_mfma_f32_16x16x32_bf16 v[48:51], v[198:201], v[194:197], v[48:51]
	ds_read_b128 v[246:249], v182 offset:16128
	s_waitcnt lgkmcnt(4)
	v_mfma_f32_16x16x32_bf16 v[44:47], v[202:205], v[178:181], v[44:47]
	s_waitcnt vmcnt(3)
	ds_write_b128 v250, v[144:147] offset:36864
	v_mfma_f32_16x16x32_bf16 v[40:43], v[202:205], v[186:189], v[40:43]
	v_mfma_f32_16x16x32_bf16 v[36:39], v[202:205], v[190:193], v[36:39]
	v_mfma_f32_16x16x32_bf16 v[32:35], v[202:205], v[194:197], v[32:35]
	ds_read_b128 v[198:201], v182 offset:64
	s_waitcnt lgkmcnt(4)
	v_mfma_f32_16x16x32_bf16 v[28:31], v[242:245], v[178:181], v[28:31]
	s_waitcnt vmcnt(2)
	ds_write_b128 v251, v[148:151] offset:36864
	v_mfma_f32_16x16x32_bf16 v[24:27], v[242:245], v[186:189], v[24:27]
	v_mfma_f32_16x16x32_bf16 v[20:23], v[242:245], v[190:193], v[20:23]
	v_mfma_f32_16x16x32_bf16 v[16:19], v[242:245], v[194:197], v[16:19]
	ds_read_b128 v[202:205], v182 offset:2368
	s_waitcnt lgkmcnt(4)
	v_mfma_f32_16x16x32_bf16 v[8:11], v[246:249], v[178:181], v[8:11]
	ds_read_b128 v[178:181], v183 offset:36928
	s_waitcnt vmcnt(1)
	ds_write_b128 v252, v[152:155] offset:36864
	v_mfma_f32_16x16x32_bf16 v[4:7], v[246:249], v[186:189], v[4:7]
	ds_read_b128 v[186:189], v183 offset:39232
	v_mfma_f32_16x16x32_bf16 v[0:3], v[246:249], v[190:193], v[0:3]
	ds_read_b128 v[190:193], v183 offset:41536
	v_mfma_f32_16x16x32_bf16 v[12:15], v[246:249], v[194:197], v[12:15]
	ds_read_b128 v[194:197], v183 offset:43840
	ds_read_b128 v[242:245], v182 offset:4672
	s_waitcnt lgkmcnt(5)
	v_mfma_f32_16x16x32_bf16 v[140:143], v[198:201], v[178:181], v[140:143]
	s_waitcnt lgkmcnt(3)
	v_mfma_f32_16x16x32_bf16 v[120:123], v[198:201], v[186:189], v[120:123]
	s_waitcnt vmcnt(0)
	ds_write_b128 v253, v[156:159] offset:36864
	s_waitcnt lgkmcnt(3)
	v_mfma_f32_16x16x32_bf16 v[116:119], v[198:201], v[190:193], v[116:119]
	s_waitcnt lgkmcnt(2)
	v_mfma_f32_16x16x32_bf16 v[112:115], v[198:201], v[194:197], v[112:115]
	v_lshl_add_u64 v[124:125], s[52:53], 0, v[162:163]
	v_lshl_add_u64 v[128:129], s[52:53], 0, v[164:165]
	v_lshl_add_u64 v[132:133], s[52:53], 0, v[166:167]
	v_lshl_add_u64 v[136:137], s[52:53], 0, v[168:169]
	s_add_u32 s52, s2, s33
	s_addc_u32 s53, s3, 0
	v_lshl_add_u64 v[144:145], s[52:53], 0, v[162:163]
	v_lshl_add_u64 v[148:149], s[52:53], 0, v[164:165]
	v_lshl_add_u64 v[152:153], s[52:53], 0, v[166:167]
	v_lshl_add_u64 v[156:157], s[52:53], 0, v[168:169]
	global_load_dwordx4 v[124:127], v[124:125], off
	ds_read_b128 v[246:249], v182 offset:6976
	v_mfma_f32_16x16x32_bf16 v[108:111], v[202:205], v[178:181], v[108:111]
	v_mfma_f32_16x16x32_bf16 v[104:107], v[202:205], v[186:189], v[104:107]
	global_load_dwordx4 v[128:131], v[128:129], off
	v_mfma_f32_16x16x32_bf16 v[100:103], v[202:205], v[190:193], v[100:103]
	v_mfma_f32_16x16x32_bf16 v[96:99], v[202:205], v[194:197], v[96:99]
	ds_read_b128 v[198:201], v182 offset:9280
	s_waitcnt lgkmcnt(3)
	v_mfma_f32_16x16x32_bf16 v[92:95], v[242:245], v[178:181], v[92:95]
	global_load_dwordx4 v[132:135], v[132:133], off
	v_mfma_f32_16x16x32_bf16 v[88:91], v[242:245], v[186:189], v[88:91]
	v_mfma_f32_16x16x32_bf16 v[84:87], v[242:245], v[190:193], v[84:87]
	global_load_dwordx4 v[136:139], v[136:137], off
	v_mfma_f32_16x16x32_bf16 v[80:83], v[242:245], v[194:197], v[80:83]
	ds_read_b128 v[202:205], v182 offset:11584
	s_waitcnt lgkmcnt(2)
	v_mfma_f32_16x16x32_bf16 v[76:79], v[246:249], v[178:181], v[76:79]
	v_mfma_f32_16x16x32_bf16 v[72:75], v[246:249], v[186:189], v[72:75]
	global_load_dwordx4 v[144:147], v[144:145], off
	v_mfma_f32_16x16x32_bf16 v[68:71], v[246:249], v[190:193], v[68:71]
	v_mfma_f32_16x16x32_bf16 v[64:67], v[246:249], v[194:197], v[64:67]
	global_load_dwordx4 v[148:151], v[148:149], off
	ds_read_b128 v[242:245], v182 offset:13888
	s_waitcnt lgkmcnt(2)
	v_mfma_f32_16x16x32_bf16 v[60:63], v[198:201], v[178:181], v[60:63]
	v_mfma_f32_16x16x32_bf16 v[56:59], v[198:201], v[186:189], v[56:59]
	v_mfma_f32_16x16x32_bf16 v[52:55], v[198:201], v[190:193], v[52:55]
	global_load_dwordx4 v[152:155], v[152:153], off
	v_mfma_f32_16x16x32_bf16 v[48:51], v[198:201], v[194:197], v[48:51]
	ds_read_b128 v[246:249], v182 offset:16192
	s_waitcnt lgkmcnt(2)
	v_mfma_f32_16x16x32_bf16 v[44:47], v[202:205], v[178:181], v[44:47]
	global_load_dwordx4 v[156:159], v[156:157], off
	v_mfma_f32_16x16x32_bf16 v[40:43], v[202:205], v[186:189], v[40:43]
	v_mfma_f32_16x16x32_bf16 v[36:39], v[202:205], v[190:193], v[36:39]
	v_mfma_f32_16x16x32_bf16 v[32:35], v[202:205], v[194:197], v[32:35]
	s_waitcnt lgkmcnt(0)
	s_barrier
; DI f32x4 mfma16(bf16x8 a, bf16x8 b, f32x4 c) { return __builtin_amdgcn_mfma_f32_16x16x32_bf16(a, b, c, 0, 0, 0); }
; template <int MI, int NJ, bool SWAP, class AP, class BP>
; DI void gemm_main(f32x4 (&acc)[MI][NJ], const AP& ap, int a_kstep, const BP& bp, int b_kstep, int nk, bf16_t* smem) {
;     ...
;   for (int kt = 0; kt < nk; ++kt) {
;     const int buf = kt & 1;
;     sstore(buf ^ 1);
;     gload(kt + 2 < nk ? kt + 2 : nk - 1);
;     __builtin_amdgcn_sched_barrier(0);
;     const bf16_t* As = smem + buf * L::STAGE + (wm * 16 * MI + l15) * LDT + quad * 8;
;     const bf16_t* Bs = smem + buf * L::STAGE + L::A_ELEMS + (wn * 16 * NJ + l15) * LDT + quad * 8;
; #pragma unroll
;     for (int ks = 0; ks < 2; ++ks) {
;       if (MI * NJ >= 32 && ks == 1) asm volatile("" ::: "memory");
;       bf16x8 b[NJ];
; #pragma unroll
;       for (int j = 0; j < NJ; ++j) b[j] = *(const bf16x8*)(Bs + j * 16 * LDT + ks * 32);
; #pragma unroll
;       for (int i = 0; i < MI; ++i) {
;         const bf16x8 a = *(const bf16x8*)(As + i * 16 * LDT + ks * 32);
; #pragma unroll
;         for (int j = 0; j < NJ; ++j) acc[i][j] = SWAP ? mfma16(b[j], a, acc[i][j]) : mfma16(a, b[j], acc[i][j]);
;       }
;     }
;     __syncthreads();
;   }
	s_add_i32 s5, s5, 1
	s_cmp_lg_u32 s5, 4
	s_cbranch_scc0 .Lgm4_exit
	s_and_b32 s98, s5, 1
	s_mul_i32 s98, s98, 0x12000
	v_add3_u32 v182, s98, v176, v177
	v_add3_u32 v183, s98, v171, v177
	ds_read_b128 v[198:201], v182
	ds_read_b128 v[202:205], v182 offset:2304
	v_mfma_f32_16x16x32_bf16 v[28:31], v[242:245], v[178:181], v[28:31]
	v_mfma_f32_16x16x32_bf16 v[8:11], v[246:249], v[178:181], v[8:11]
	ds_read_b128 v[178:181], v183 offset:36864
	v_mfma_f32_16x16x32_bf16 v[24:27], v[242:245], v[186:189], v[24:27]
	v_mfma_f32_16x16x32_bf16 v[4:7], v[246:249], v[186:189], v[4:7]
	ds_read_b128 v[186:189], v183 offset:39168
	v_mfma_f32_16x16x32_bf16 v[20:23], v[242:245], v[190:193], v[20:23]
	v_mfma_f32_16x16x32_bf16 v[0:3], v[246:249], v[190:193], v[0:3]
	ds_read_b128 v[190:193], v183 offset:41472
	v_mfma_f32_16x16x32_bf16 v[16:19], v[242:245], v[194:197], v[16:19]
	v_mfma_f32_16x16x32_bf16 v[12:15], v[246:249], v[194:197], v[12:15]
	ds_read_b128 v[194:197], v183 offset:43776
	s_branch .Lgm4_main

; DI f32x4 mfma16(bf16x8 a, bf16x8 b, f32x4 c) { return __builtin_amdgcn_mfma_f32_16x16x32_bf16(a, b, c, 0, 0, 0); }
; template <int MI, int NJ, bool SWAP, class AP, class BP>
; DI void gemm_main(f32x4 (&acc)[MI][NJ], const AP& ap, int a_kstep, const BP& bp, int b_kstep, int nk, bf16_t* smem) {
;     ...
;   auto sstore = [&](int buf) {
;     bf16_t* As = smem + buf * L::STAGE; bf16_t* Bs = As + L::A_ELEMS;
; #pragma unroll
;     for (int i = 0; i < CA; ++i) { const int c = tid + NTHR * i; *(u32x4*)(As + (c >> 3) * LDT + (c & 7) * 8) = oka[i] ? ra[i] : (u32x4){0u, 0u, 0u, 0u}; }
; #pragma unroll
;     for (int i = 0; i < CB; ++i) { const int c = tid + NTHR * i; *(u32x4*)(Bs + (c >> 3) * LDT + (c & 7) * 8) = rb[i]; }
;   };
;   gload(0); sstore(0); gload(nk > 1 ? 1 : 0); __syncthreads();
; #pragma unroll 1
;   for (int kt = 0; kt < nk; ++kt) {
;     const int buf = kt & 1;
;     sstore(buf ^ 1);
;     gload(kt + 2 < nk ? kt + 2 : nk - 1);
;     __builtin_amdgcn_sched_barrier(0);
;     const bf16_t* As = smem + buf * L::STAGE + (wm * 16 * MI + l15) * LDT + quad * 8;
;     const bf16_t* Bs = smem + buf * L::STAGE + L::A_ELEMS + (wn * 16 * NJ + l15) * LDT + quad * 8;
; #pragma unroll
;     for (int ks = 0; ks < 2; ++ks) {
;       if (MI * NJ >= 32 && ks == 1) asm volatile("" ::: "memory");
;       bf16x8 b[NJ];
; #pragma unroll
;       for (int j = 0; j < NJ; ++j) b[j] = *(const bf16x8*)(Bs + j * 16 * LDT + ks * 32);
; #pragma unroll
;       for (int i = 0; i < MI; ++i) {
;         const bf16x8 a = *(const bf16x8*)(As + i * 16 * LDT + ks * 32);
; #pragma unroll
;         for (int j = 0; j < NJ; ++j) acc[i][j] = SWAP ? mfma16(b[j], a, acc[i][j]) : mfma16(a, b[j], acc[i][j]);
;       }
;     }
;     __syncthreads();
;   }
.Lcp0_main:
	ds_read_b128 v[132:135], v156 offset:4608
	s_waitcnt lgkmcnt(4)
	v_mfma_f32_16x16x32_bf16 v[60:63], v[108:111], v[124:127], v[60:63]
	s_waitcnt lgkmcnt(3)
	v_mfma_f32_16x16x32_bf16 v[44:47], v[112:115], v[124:127], v[44:47]
	s_min_u32 s16, s14, 29
	s_and_b32 s15, s14, 1
	s_add_i32 s18, s16, 2
	s_xor_b32 s17, s15, 1
	s_lshl_b32 s16, s18, 9
	s_mul_i32 s17, s17, 0xd800
	s_add_u32 s16, s6, s16
	s_waitcnt vmcnt(5)
	v_cndmask_b32_e32 v79, 0, v79, vcc
	v_cndmask_b32_e32 v78, 0, v78, vcc
	v_cndmask_b32_e32 v77, 0, v77, vcc
	v_cndmask_b32_e32 v76, 0, v76, vcc
	v_add3_u32 v246, s17, v103, v100
	v_add3_u32 v247, s17, v104, v100
	v_add3_u32 v248, s17, v105, v100
	v_add3_u32 v249, s17, v106, v100
	s_addc_u32 s17, s7, 0
	s_lshl_b32 s18, s18, 7
	s_waitcnt vmcnt(4)
	v_cndmask_b32_e64 v67, 0, v67, s[0:1]
	v_cndmask_b32_e64 v66, 0, v66, s[0:1]
	v_cndmask_b32_e64 v65, 0, v65, s[0:1]
	v_cndmask_b32_e64 v64, 0, v64, s[0:1]
	ds_write_b128 v246, v[76:79]
	s_waitcnt lgkmcnt(3)
	v_mfma_f32_16x16x32_bf16 v[28:31], v[116:119], v[124:127], v[28:31]
	s_waitcnt lgkmcnt(2)
	v_mfma_f32_16x16x32_bf16 v[12:15], v[120:123], v[124:127], v[12:15]
	ds_read_b128 v[136:139], v156 offset:6912
	ds_read_b128 v[140:143], v144 offset:18496
	ds_read_b128 v[148:151], v144 offset:20800
	ds_read_b128 v[152:155], v144 offset:23104
	ds_read_b128 v[242:245], v144 offset:25408
	v_mfma_f32_16x16x32_bf16 v[56:59], v[108:111], v[128:131], v[56:59]
	ds_write_b128 v247, v[64:67]
	v_mfma_f32_16x16x32_bf16 v[40:43], v[112:115], v[128:131], v[40:43]
	v_mfma_f32_16x16x32_bf16 v[24:27], v[116:119], v[128:131], v[24:27]
	s_waitcnt vmcnt(3)
	ds_write_b128 v246, v[68:71] offset:18432
	v_mfma_f32_16x16x32_bf16 v[8:11], v[120:123], v[128:131], v[8:11]
	ds_read_b128 v[124:127], v156 offset:64
	s_waitcnt lgkmcnt(9)
	v_mfma_f32_16x16x32_bf16 v[52:55], v[108:111], v[132:135], v[52:55]
	v_mfma_f32_16x16x32_bf16 v[36:39], v[112:115], v[132:135], v[36:39]
	s_waitcnt vmcnt(2)
	ds_write_b128 v247, v[72:75] offset:18432
	v_mfma_f32_16x16x32_bf16 v[20:23], v[116:119], v[132:135], v[20:23]
	v_mfma_f32_16x16x32_bf16 v[4:7], v[120:123], v[132:135], v[4:7]
	s_waitcnt vmcnt(1)
	ds_write_b128 v248, v[80:83] offset:18432
	ds_read_b128 v[128:131], v156 offset:2368
	s_waitcnt lgkmcnt(10)
	v_mfma_f32_16x16x32_bf16 v[48:51], v[108:111], v[136:139], v[48:51]
	v_mfma_f32_16x16x32_bf16 v[32:35], v[112:115], v[136:139], v[32:35]
	s_waitcnt vmcnt(0)
	ds_write_b128 v249, v[84:87] offset:18432
	v_mfma_f32_16x16x32_bf16 v[16:19], v[116:119], v[136:139], v[16:19]
	v_mfma_f32_16x16x32_bf16 v[0:3], v[120:123], v[136:139], v[0:3]
	v_lshl_add_u64 v[68:69], v[88:89], 1, s[16:17]
	v_lshl_add_u64 v[70:71], v[90:91], 1, s[16:17]
	s_add_u32 s16, s8, s18
	s_addc_u32 s17, s9, 0
	global_load_dwordx4 v[76:79], v[68:69], off
	ds_read_b128 v[132:135], v156 offset:4672
	s_waitcnt lgkmcnt(5)
	v_mfma_f32_16x16x32_bf16 v[60:63], v[140:143], v[124:127], v[60:63]
	global_load_dwordx4 v[64:67], v[70:71], off
	v_mfma_f32_16x16x32_bf16 v[44:47], v[148:151], v[124:127], v[44:47]
	v_mfma_f32_16x16x32_bf16 v[28:31], v[152:155], v[124:127], v[28:31]
	v_lshl_add_u64 v[68:69], v[92:93], 1, s[16:17]
	v_lshl_add_u64 v[246:247], v[94:95], 1, s[16:17]
	v_lshl_add_u64 v[248:249], v[96:97], 1, s[16:17]
	v_lshl_add_u64 v[250:251], v[98:99], 1, s[16:17]
	global_load_dwordx4 v[68:71], v[68:69], off
	v_mfma_f32_16x16x32_bf16 v[12:15], v[242:245], v[124:127], v[12:15]
	global_load_dwordx4 v[72:75], v[246:247], off
	ds_read_b128 v[136:139], v156 offset:6976
	s_waitcnt lgkmcnt(3)
	v_mfma_f32_16x16x32_bf16 v[56:59], v[140:143], v[128:131], v[56:59]
	global_load_dwordx4 v[80:83], v[248:249], off
	v_mfma_f32_16x16x32_bf16 v[40:43], v[148:151], v[128:131], v[40:43]
	v_mfma_f32_16x16x32_bf16 v[24:27], v[152:155], v[128:131], v[24:27]
	global_load_dwordx4 v[84:87], v[250:251], off
	v_mfma_f32_16x16x32_bf16 v[8:11], v[242:245], v[128:131], v[8:11]
	s_waitcnt lgkmcnt(0)
	s_barrier
	s_add_i32 s14, s14, 1
	s_cmp_lg_u32 s14, 32
	s_cbranch_scc0 .Lcp0_exit
	s_and_b32 s98, s14, 1
	s_mul_i32 s98, s98, 0xd800
	v_add3_u32 v144, s98, v102, v107
	v_add3_u32 v156, s98, v101, v107
	ds_read_b128 v[124:127], v156
	ds_read_b128 v[128:131], v156 offset:2304
	ds_read_b128 v[108:111], v144 offset:18432
	ds_read_b128 v[112:115], v144 offset:20736
	ds_read_b128 v[116:119], v144 offset:23040
	ds_read_b128 v[120:123], v144 offset:25344
	v_mfma_f32_16x16x32_bf16 v[52:55], v[140:143], v[132:135], v[52:55]
	v_mfma_f32_16x16x32_bf16 v[48:51], v[140:143], v[136:139], v[48:51]
	v_mfma_f32_16x16x32_bf16 v[36:39], v[148:151], v[132:135], v[36:39]
	v_mfma_f32_16x16x32_bf16 v[32:35], v[148:151], v[136:139], v[32:35]
	v_mfma_f32_16x16x32_bf16 v[20:23], v[152:155], v[132:135], v[20:23]
	v_mfma_f32_16x16x32_bf16 v[16:19], v[152:155], v[136:139], v[16:19]
	v_mfma_f32_16x16x32_bf16 v[4:7], v[242:245], v[132:135], v[4:7]
	v_mfma_f32_16x16x32_bf16 v[0:3], v[242:245], v[136:139], v[0:3]
	s_branch .Lcp0_main

; DI f32x4 mfma16(bf16x8 a, bf16x8 b, f32x4 c) { return __builtin_amdgcn_mfma_f32_16x16x32_bf16(a, b, c, 0, 0, 0); }
; DI void merge_tile(const Params& p, int layer, int tm, int tn, bf16_t* smem) {
;     ...
;   auto gload_next = [&]() {
;     const bf16_t* ab = la + (size_t)lkt * laks; const bf16_t* bb = lb + (size_t)lkt * 64;
; #pragma unroll
;     for (int i = 0; i < 4; ++i) ra[i] = *(const u32x4*)(ab + pa0 + (size_t)i * 64 * lald);
; #pragma unroll
;     for (int i = 0; i < 2; ++i) rb[i] = *(const u32x4*)(bb + pb0 + (size_t)i * 64 * lbld);
;     if (++lkt == lnk) {
;       if (ls + 1 < 6) { ++ls; lkt = 0; get_seg(ls); set_offsets(); } else lkt = lnk - 1;
;     }
;   };
;   auto sstore = [&](int buf) {
;     bf16_t* As = smem + buf * L::STAGE; bf16_t* Bs = As + L::A_ELEMS;
; #pragma unroll
;     for (int i = 0; i < 4; ++i) { const int c = tid + NTHR * i; *(u32x4*)(As + (c >> 3) * LDT + (c & 7) * 8) = ra[i]; }
; #pragma unroll
;     for (int i = 0; i < 2; ++i) { const int c = tid + NTHR * i; *(u32x4*)(Bs + (c >> 3) * LDT + (c & 7) * 8) = rb[i]; }
;   };
;   gload_next(); sstore(0); gload_next(); __syncthreads();
;   int buf = 0;
; #pragma unroll 1
;   for (int sg = 0; sg < 6; ++sg) {
;     const int nk = (sg & 1) ? 8 : 16;
; #pragma unroll 1
;     for (int kt = 0; kt < nk; ++kt) {
;       sstore(buf ^ 1);
;       gload_next();
;       __builtin_amdgcn_sched_barrier(0);
;       const bf16_t* As = smem + buf * L::STAGE + (wm * 128 + l15) * LDT + quad * 8;
;       const bf16_t* Bs = smem + buf * L::STAGE + L::A_ELEMS + (wn * 32 + l15) * LDT + quad * 8;
; #pragma unroll
;       for (int ks = 0; ks < 2; ++ks) {
;         if (ks == 1) asm volatile("" ::: "memory");
;         bf16x8 b[2];
; #pragma unroll
;         for (int j = 0; j < 2; ++j) b[j] = *(const bf16x8*)(Bs + j * 16 * LDT + ks * 32);
; #pragma unroll
;         for (int i = 0; i < 8; ++i) {
;           const bf16x8 a = *(const bf16x8*)(As + i * 16 * LDT + ks * 32);
; #pragma unroll
;           for (int j = 0; j < 2; ++j) acc[i][j] = mfma16(b[j], a, acc[i][j]);
;         }
;       }
;       __syncthreads();
;       buf ^= 1;
;     }
.Lmg0_main:
	ds_read_b128 v[178:181], v165 offset:9216
	s_waitcnt lgkmcnt(2)
	v_mfma_f32_16x16x32_bf16 v[148:151], v[152:155], v[156:159], v[148:151]
	s_waitcnt lgkmcnt(1)
	v_mfma_f32_16x16x32_bf16 v[144:147], v[160:163], v[156:159], v[144:147]
	s_xor_b32 s44, s45, 1
	s_mul_i32 s15, s44, 0xd800
	v_add3_u32 v202, s15, v232, v229
	s_waitcnt vmcnt(5)
	ds_write_b128 v202, v[4:7]
	ds_read_b128 v[182:185], v165 offset:11520
	ds_read_b128 v[194:197], v164 offset:36928
	ds_read_b128 v[198:201], v164 offset:39232
	v_mfma_f32_16x16x32_bf16 v[140:143], v[152:155], v[166:169], v[140:143]
	v_mfma_f32_16x16x32_bf16 v[136:139], v[160:163], v[166:169], v[136:139]
	v_add3_u32 v4, s15, v233, v229
	s_waitcnt vmcnt(4)
	ds_write_b128 v4, v[0:3]
	ds_read_b128 v[186:189], v165 offset:13824
	v_mfma_f32_16x16x32_bf16 v[132:135], v[152:155], v[170:173], v[132:135]
	v_add3_u32 v0, s15, v234, v229
	s_ashr_i32 s21, s20, 31
	s_waitcnt vmcnt(3)
	ds_write_b128 v0, v[12:15]
	v_mfma_f32_16x16x32_bf16 v[128:131], v[160:163], v[170:173], v[128:131]
	ds_read_b128 v[190:193], v165 offset:16128
	v_mfma_f32_16x16x32_bf16 v[124:127], v[152:155], v[174:177], v[124:127]
	v_add3_u32 v0, s15, v235, v229
	s_mul_hi_u32 s15, s41, s20
	s_mul_i32 s46, s41, s21
	s_add_i32 s47, s15, s46
	s_mul_i32 s46, s41, s20
	s_lshl_b64 s[46:47], s[46:47], 1
	s_add_u32 s46, s18, s46
	s_addc_u32 s47, s19, s47
	s_waitcnt vmcnt(2)
	ds_write_b128 v0, v[8:11]
	v_mfma_f32_16x16x32_bf16 v[120:123], v[160:163], v[174:177], v[120:123]
	ds_read_b128 v[156:159], v165 offset:64
	s_waitcnt lgkmcnt(10)
	v_mfma_f32_16x16x32_bf16 v[116:119], v[152:155], v[178:181], v[116:119]
	s_waitcnt vmcnt(1)
	ds_write_b128 v202, v[16:19] offset:36864
	v_mfma_f32_16x16x32_bf16 v[112:115], v[160:163], v[178:181], v[112:115]
	ds_read_b128 v[166:169], v165 offset:2368
	s_waitcnt lgkmcnt(10)
	v_mfma_f32_16x16x32_bf16 v[108:111], v[152:155], v[182:185], v[108:111]
	s_waitcnt vmcnt(0)
	ds_write_b128 v4, v[20:23] offset:36864
	v_mfma_f32_16x16x32_bf16 v[104:107], v[160:163], v[182:185], v[104:107]
	v_lshl_add_u64 v[0:1], v[216:217], 1, s[46:47]
	s_lshl_b64 s[46:47], s[2:3], 7
	v_lshl_add_u64 v[8:9], v[0:1], 0, s[46:47]
	s_lshl_b64 s[48:49], s[20:21], 7
	global_load_dwordx4 v[4:7], v[0:1], off
	ds_read_b128 v[170:173], v165 offset:4672
	s_waitcnt lgkmcnt(8)
	v_mfma_f32_16x16x32_bf16 v[100:103], v[152:155], v[186:189], v[100:103]
	v_mfma_f32_16x16x32_bf16 v[96:99], v[160:163], v[186:189], v[96:99]
	global_load_dwordx4 v[0:3], v[8:9], off
	ds_read_b128 v[174:177], v165 offset:6976
	s_waitcnt lgkmcnt(7)
	v_mfma_f32_16x16x32_bf16 v[92:95], v[152:155], v[190:193], v[92:95]
	v_mfma_f32_16x16x32_bf16 v[88:91], v[160:163], v[190:193], v[88:91]
	v_lshl_add_u64 v[8:9], v[8:9], 0, s[46:47]
	v_lshl_add_u64 v[10:11], v[8:9], 0, s[46:47]
	s_add_u32 s46, s16, s48
	s_addc_u32 s47, s17, s49
	v_mov_b32_e32 v219, v217
	s_mov_b32 s15, s3
	v_lshl_add_u64 v[16:17], v[218:219], 1, s[46:47]
	s_lshl_b64 s[46:47], s[14:15], 7
	v_lshl_add_u64 v[20:21], v[16:17], 0, s[46:47]
	global_load_dwordx4 v[12:15], v[8:9], off
	ds_read_b128 v[178:181], v165 offset:9280
	s_waitcnt lgkmcnt(6)
	v_mfma_f32_16x16x32_bf16 v[148:151], v[194:197], v[156:159], v[148:151]
	global_load_dwordx4 v[8:11], v[10:11], off
	v_mfma_f32_16x16x32_bf16 v[144:147], v[198:201], v[156:159], v[144:147]
	ds_read_b128 v[182:185], v165 offset:11584
	s_waitcnt lgkmcnt(5)
	v_mfma_f32_16x16x32_bf16 v[140:143], v[194:197], v[166:169], v[140:143]
	global_load_dwordx4 v[16:19], v[16:17], off
	v_mfma_f32_16x16x32_bf16 v[136:139], v[198:201], v[166:169], v[136:139]
	global_load_dwordx4 v[20:23], v[20:21], off
	ds_read_b128 v[186:189], v165 offset:13888
	s_waitcnt lgkmcnt(4)
	v_mfma_f32_16x16x32_bf16 v[132:135], v[194:197], v[170:173], v[132:135]
	v_mfma_f32_16x16x32_bf16 v[128:131], v[198:201], v[170:173], v[128:131]
	ds_read_b128 v[190:193], v165 offset:16192
	s_waitcnt lgkmcnt(4)
	v_mfma_f32_16x16x32_bf16 v[124:127], v[194:197], v[174:177], v[124:127]
	v_mfma_f32_16x16x32_bf16 v[120:123], v[198:201], v[174:177], v[120:123]
	s_waitcnt lgkmcnt(0)
	s_barrier
	s_add_i32 s15, s20, 1
	s_cmp_lg_u32 s15, s42
	s_cbranch_scc1 .LBB0_842
	s_cmp_gt_i32 s43, 4
	s_cbranch_scc1 .LBB0_845
	s_add_i32 s21, s43, 1
	s_ashr_i32 s18, s21, 1
	s_bitcmp0_b32 s43, 0
	s_mov_b64 s[14:15], -1
	s_cbranch_scc1 .LBB0_840
	s_ashr_i32 s19, s18, 31
	s_lshl_b64 s[14:15], s[18:19], 21
	s_add_u32 s16, s10, s14
	s_addc_u32 s17, s11, s15
	s_mov_b64 s[14:15], 0

; DI f32x4 mfma16(bf16x8 a, bf16x8 b, f32x4 c) { return __builtin_amdgcn_mfma_f32_16x16x32_bf16(a, b, c, 0, 0, 0); }
; template <int MI, int NJ, bool SWAP, class AP, class BP>
; DI void gemm_main(f32x4 (&acc)[MI][NJ], const AP& ap, int a_kstep, const BP& bp, int b_kstep, int nk, bf16_t* smem) {
;     ...
;   for (int kt = 0; kt < nk; ++kt) {
;     const int buf = kt & 1;
;     sstore(buf ^ 1);
;     gload(kt + 2 < nk ? kt + 2 : nk - 1);
;     __builtin_amdgcn_sched_barrier(0);
;     const bf16_t* As = smem + buf * L::STAGE + (wm * 16 * MI + l15) * LDT + quad * 8;
;     const bf16_t* Bs = smem + buf * L::STAGE + L::A_ELEMS + (wn * 16 * NJ + l15) * LDT + quad * 8;
; #pragma unroll
;     for (int ks = 0; ks < 2; ++ks) {
;       if (MI * NJ >= 32 && ks == 1) asm volatile("" ::: "memory");
;       bf16x8 b[NJ];
; #pragma unroll
;       for (int j = 0; j < NJ; ++j) b[j] = *(const bf16x8*)(Bs + j * 16 * LDT + ks * 32);
; #pragma unroll
;       for (int i = 0; i < MI; ++i) {
;         const bf16x8 a = *(const bf16x8*)(As + i * 16 * LDT + ks * 32);
; #pragma unroll
;         for (int j = 0; j < NJ; ++j) acc[i][j] = SWAP ? mfma16(b[j], a, acc[i][j]) : mfma16(a, b[j], acc[i][j]);
;       }
;     }
;     __syncthreads();
;   }
.Lgm5_main:
	ds_read_b128 v[242:245], v177 offset:4608
	s_waitcnt lgkmcnt(4)
	v_mfma_f32_16x16x32_bf16 v[156:159], v[178:181], v[194:197], v[156:159]
	s_waitcnt lgkmcnt(3)
	v_mfma_f32_16x16x32_bf16 v[152:155], v[182:185], v[194:197], v[152:155]
	s_waitcnt lgkmcnt(2)
	v_mfma_f32_16x16x32_bf16 v[148:151], v[186:189], v[194:197], v[148:151]
	s_waitcnt lgkmcnt(1)
	v_mfma_f32_16x16x32_bf16 v[128:131], v[190:193], v[194:197], v[128:131]
	s_and_b32 s15, s1, 1
	s_min_u32 s16, s1, 13
	s_xor_b32 s17, s15, 1
	s_lshl_b32 s26, s16, 7
	s_mul_i32 s17, s17, 0x12000
	s_add_u32 s16, s2, s26
	v_add3_u32 v250, s17, v172, v170
	v_add3_u32 v251, s17, v174, v170
	v_add3_u32 v252, s17, v175, v170
	v_add3_u32 v253, s17, v176, v170
	s_addc_u32 s17, s3, 0
	s_waitcnt vmcnt(7)
	ds_write_b128 v250, v[112:115]
	ds_read_b128 v[246:249], v177 offset:6912
	v_mfma_f32_16x16x32_bf16 v[108:111], v[178:181], v[198:201], v[108:111]
	v_mfma_f32_16x16x32_bf16 v[104:107], v[182:185], v[198:201], v[104:107]
	v_mfma_f32_16x16x32_bf16 v[100:103], v[186:189], v[198:201], v[100:103]
	v_mfma_f32_16x16x32_bf16 v[96:99], v[190:193], v[198:201], v[96:99]
	s_waitcnt vmcnt(6)
	ds_write_b128 v251, v[116:119]
	ds_read_b128 v[194:197], v177 offset:9216
	s_waitcnt lgkmcnt(4)
	v_mfma_f32_16x16x32_bf16 v[92:95], v[178:181], v[242:245], v[92:95]
	v_mfma_f32_16x16x32_bf16 v[88:91], v[182:185], v[242:245], v[88:91]
	v_mfma_f32_16x16x32_bf16 v[84:87], v[186:189], v[242:245], v[84:87]
	v_mfma_f32_16x16x32_bf16 v[80:83], v[190:193], v[242:245], v[80:83]
	ds_read_b128 v[198:201], v177 offset:11520
	s_waitcnt lgkmcnt(3)
	v_mfma_f32_16x16x32_bf16 v[76:79], v[178:181], v[246:249], v[76:79]
	s_waitcnt vmcnt(5)
	ds_write_b128 v252, v[120:123]
	v_mfma_f32_16x16x32_bf16 v[72:75], v[182:185], v[246:249], v[72:75]
	v_mfma_f32_16x16x32_bf16 v[68:71], v[186:189], v[246:249], v[68:71]
	v_mfma_f32_16x16x32_bf16 v[64:67], v[190:193], v[246:249], v[64:67]
	ds_read_b128 v[242:245], v177 offset:13824
	s_waitcnt lgkmcnt(3)
	v_mfma_f32_16x16x32_bf16 v[60:63], v[178:181], v[194:197], v[60:63]
	s_waitcnt vmcnt(4)
	ds_write_b128 v253, v[124:127]
	v_mfma_f32_16x16x32_bf16 v[56:59], v[182:185], v[194:197], v[56:59]
	v_mfma_f32_16x16x32_bf16 v[52:55], v[186:189], v[194:197], v[52:55]
	v_mfma_f32_16x16x32_bf16 v[48:51], v[190:193], v[194:197], v[48:51]
	ds_read_b128 v[246:249], v177 offset:16128
	s_waitcnt lgkmcnt(4)
	v_mfma_f32_16x16x32_bf16 v[44:47], v[178:181], v[198:201], v[44:47]
	s_waitcnt vmcnt(3)
	ds_write_b128 v250, v[132:135] offset:36864
	v_mfma_f32_16x16x32_bf16 v[40:43], v[182:185], v[198:201], v[40:43]
	v_mfma_f32_16x16x32_bf16 v[36:39], v[186:189], v[198:201], v[36:39]
	v_mfma_f32_16x16x32_bf16 v[32:35], v[190:193], v[198:201], v[32:35]
	ds_read_b128 v[194:197], v177 offset:64
	s_waitcnt lgkmcnt(4)
	v_mfma_f32_16x16x32_bf16 v[28:31], v[178:181], v[242:245], v[28:31]
	s_waitcnt vmcnt(2)
	ds_write_b128 v251, v[136:139] offset:36864
	v_mfma_f32_16x16x32_bf16 v[24:27], v[182:185], v[242:245], v[24:27]
	v_mfma_f32_16x16x32_bf16 v[20:23], v[186:189], v[242:245], v[20:23]
	v_mfma_f32_16x16x32_bf16 v[16:19], v[190:193], v[242:245], v[16:19]
	ds_read_b128 v[198:201], v177 offset:2368
	s_waitcnt lgkmcnt(4)
	v_mfma_f32_16x16x32_bf16 v[8:11], v[178:181], v[246:249], v[8:11]
	ds_read_b128 v[178:181], v202 offset:36928
	s_waitcnt vmcnt(1)
	ds_write_b128 v252, v[140:143] offset:36864
	v_mfma_f32_16x16x32_bf16 v[4:7], v[182:185], v[246:249], v[4:7]
	ds_read_b128 v[182:185], v202 offset:39232
	v_mfma_f32_16x16x32_bf16 v[0:3], v[186:189], v[246:249], v[0:3]
	ds_read_b128 v[186:189], v202 offset:41536
	v_mfma_f32_16x16x32_bf16 v[12:15], v[190:193], v[246:249], v[12:15]
	ds_read_b128 v[190:193], v202 offset:43840
	ds_read_b128 v[242:245], v177 offset:4672
	s_waitcnt lgkmcnt(5)
	v_mfma_f32_16x16x32_bf16 v[156:159], v[178:181], v[194:197], v[156:159]
	s_waitcnt lgkmcnt(3)
	v_mfma_f32_16x16x32_bf16 v[152:155], v[182:185], v[194:197], v[152:155]
	s_waitcnt vmcnt(0)
	ds_write_b128 v253, v[144:147] offset:36864
	s_waitcnt lgkmcnt(3)
	v_mfma_f32_16x16x32_bf16 v[148:151], v[186:189], v[194:197], v[148:151]
	s_waitcnt lgkmcnt(2)
	v_mfma_f32_16x16x32_bf16 v[128:131], v[190:193], v[194:197], v[128:131]
	v_lshl_add_u64 v[112:113], s[16:17], 0, v[162:163]
	v_lshl_add_u64 v[116:117], s[16:17], 0, v[164:165]
	v_lshl_add_u64 v[120:121], s[16:17], 0, v[166:167]
	v_lshl_add_u64 v[124:125], s[16:17], 0, v[168:169]
	s_add_u32 s16, s12, s26
	s_addc_u32 s17, s13, 0
	v_lshl_add_u64 v[132:133], s[16:17], 0, v[162:163]
	v_lshl_add_u64 v[136:137], s[16:17], 0, v[164:165]
	v_lshl_add_u64 v[140:141], s[16:17], 0, v[166:167]
	v_lshl_add_u64 v[144:145], s[16:17], 0, v[168:169]
	global_load_dwordx4 v[112:115], v[112:113], off offset:256
	ds_read_b128 v[246:249], v177 offset:6976
	v_mfma_f32_16x16x32_bf16 v[108:111], v[178:181], v[198:201], v[108:111]
	v_mfma_f32_16x16x32_bf16 v[104:107], v[182:185], v[198:201], v[104:107]
	global_load_dwordx4 v[116:119], v[116:117], off offset:256
	v_mfma_f32_16x16x32_bf16 v[100:103], v[186:189], v[198:201], v[100:103]
	v_mfma_f32_16x16x32_bf16 v[96:99], v[190:193], v[198:201], v[96:99]
	ds_read_b128 v[194:197], v177 offset:9280
	s_waitcnt lgkmcnt(3)
	v_mfma_f32_16x16x32_bf16 v[92:95], v[178:181], v[242:245], v[92:95]
	global_load_dwordx4 v[120:123], v[120:121], off offset:256
	v_mfma_f32_16x16x32_bf16 v[88:91], v[182:185], v[242:245], v[88:91]
	v_mfma_f32_16x16x32_bf16 v[84:87], v[186:189], v[242:245], v[84:87]
	global_load_dwordx4 v[124:127], v[124:125], off offset:256
	v_mfma_f32_16x16x32_bf16 v[80:83], v[190:193], v[242:245], v[80:83]
	ds_read_b128 v[198:201], v177 offset:11584
	s_waitcnt lgkmcnt(2)
	v_mfma_f32_16x16x32_bf16 v[76:79], v[178:181], v[246:249], v[76:79]
	v_mfma_f32_16x16x32_bf16 v[72:75], v[182:185], v[246:249], v[72:75]
	global_load_dwordx4 v[132:135], v[132:133], off offset:256
	v_mfma_f32_16x16x32_bf16 v[68:71], v[186:189], v[246:249], v[68:71]
	v_mfma_f32_16x16x32_bf16 v[64:67], v[190:193], v[246:249], v[64:67]
	global_load_dwordx4 v[136:139], v[136:137], off offset:256
	ds_read_b128 v[242:245], v177 offset:13888
	s_waitcnt lgkmcnt(2)
	v_mfma_f32_16x16x32_bf16 v[60:63], v[178:181], v[194:197], v[60:63]
	v_mfma_f32_16x16x32_bf16 v[56:59], v[182:185], v[194:197], v[56:59]
	v_mfma_f32_16x16x32_bf16 v[52:55], v[186:189], v[194:197], v[52:55]
	global_load_dwordx4 v[140:143], v[140:141], off offset:256
	v_mfma_f32_16x16x32_bf16 v[48:51], v[190:193], v[194:197], v[48:51]
	ds_read_b128 v[246:249], v177 offset:16192
	s_waitcnt lgkmcnt(2)
	v_mfma_f32_16x16x32_bf16 v[44:47], v[178:181], v[198:201], v[44:47]
	global_load_dwordx4 v[144:147], v[144:145], off offset:256
	v_mfma_f32_16x16x32_bf16 v[40:43], v[182:185], v[198:201], v[40:43]
	v_mfma_f32_16x16x32_bf16 v[36:39], v[186:189], v[198:201], v[36:39]
	v_mfma_f32_16x16x32_bf16 v[32:35], v[190:193], v[198:201], v[32:35]
	s_waitcnt lgkmcnt(0)
	s_barrier
; DI f32x4 mfma16(bf16x8 a, bf16x8 b, f32x4 c) { return __builtin_amdgcn_mfma_f32_16x16x32_bf16(a, b, c, 0, 0, 0); }
; template <int MI, int NJ, bool SWAP, class AP, class BP>
; DI void gemm_main(f32x4 (&acc)[MI][NJ], const AP& ap, int a_kstep, const BP& bp, int b_kstep, int nk, bf16_t* smem) {
;     ...
;   for (int kt = 0; kt < nk; ++kt) {
;     const int buf = kt & 1;
;     sstore(buf ^ 1);
;     gload(kt + 2 < nk ? kt + 2 : nk - 1);
;     __builtin_amdgcn_sched_barrier(0);
;     const bf16_t* As = smem + buf * L::STAGE + (wm * 16 * MI + l15) * LDT + quad * 8;
;     const bf16_t* Bs = smem + buf * L::STAGE + L::A_ELEMS + (wn * 16 * NJ + l15) * LDT + quad * 8;
; #pragma unroll
;     for (int ks = 0; ks < 2; ++ks) {
;       if (MI * NJ >= 32 && ks == 1) asm volatile("" ::: "memory");
;       bf16x8 b[NJ];
; #pragma unroll
;       for (int j = 0; j < NJ; ++j) b[j] = *(const bf16x8*)(Bs + j * 16 * LDT + ks * 32);
; #pragma unroll
;       for (int i = 0; i < MI; ++i) {
;         const bf16x8 a = *(const bf16x8*)(As + i * 16 * LDT + ks * 32);
; #pragma unroll
;         for (int j = 0; j < NJ; ++j) acc[i][j] = SWAP ? mfma16(b[j], a, acc[i][j]) : mfma16(a, b[j], acc[i][j]);
;       }
;     }
;     __syncthreads();
;   }
	s_add_i32 s1, s1, 1
	s_cmp_lg_u32 s1, 16
	s_cbranch_scc0 .Lgm5_exit
	s_and_b32 s98, s1, 1
	s_mul_i32 s98, s98, 0x12000
	v_add3_u32 v202, s98, v160, v173
	v_add3_u32 v177, s98, v171, v173
	ds_read_b128 v[194:197], v177
	ds_read_b128 v[198:201], v177 offset:2304
	v_mfma_f32_16x16x32_bf16 v[28:31], v[178:181], v[242:245], v[28:31]
	v_mfma_f32_16x16x32_bf16 v[8:11], v[178:181], v[246:249], v[8:11]
	ds_read_b128 v[178:181], v202 offset:36864
	v_mfma_f32_16x16x32_bf16 v[24:27], v[182:185], v[242:245], v[24:27]
	v_mfma_f32_16x16x32_bf16 v[4:7], v[182:185], v[246:249], v[4:7]
	ds_read_b128 v[182:185], v202 offset:39168
	v_mfma_f32_16x16x32_bf16 v[20:23], v[186:189], v[242:245], v[20:23]
	v_mfma_f32_16x16x32_bf16 v[0:3], v[186:189], v[246:249], v[0:3]
	ds_read_b128 v[186:189], v202 offset:41472
	v_mfma_f32_16x16x32_bf16 v[16:19], v[190:193], v[242:245], v[16:19]
	v_mfma_f32_16x16x32_bf16 v[12:15], v[190:193], v[246:249], v[12:15]
	ds_read_b128 v[190:193], v202 offset:43776
	s_branch .Lgm5_main

; DI f32x4 mfma16(bf16x8 a, bf16x8 b, f32x4 c) { return __builtin_amdgcn_mfma_f32_16x16x32_bf16(a, b, c, 0, 0, 0); }
; template <int MI, int NJ, bool SWAP, class AP, class BP>
; DI void gemm_main(f32x4 (&acc)[MI][NJ], const AP& ap, int a_kstep, const BP& bp, int b_kstep, int nk, bf16_t* smem) {
;     ...
;   auto sstore = [&](int buf) {
;     bf16_t* As = smem + buf * L::STAGE; bf16_t* Bs = As + L::A_ELEMS;
; #pragma unroll
;     for (int i = 0; i < CA; ++i) { const int c = tid + NTHR * i; *(u32x4*)(As + (c >> 3) * LDT + (c & 7) * 8) = oka[i] ? ra[i] : (u32x4){0u, 0u, 0u, 0u}; }
; #pragma unroll
;     for (int i = 0; i < CB; ++i) { const int c = tid + NTHR * i; *(u32x4*)(Bs + (c >> 3) * LDT + (c & 7) * 8) = rb[i]; }
;   };
;   gload(0); sstore(0); gload(nk > 1 ? 1 : 0); __syncthreads();
; #pragma unroll 1
;   for (int kt = 0; kt < nk; ++kt) {
;     const int buf = kt & 1;
;     sstore(buf ^ 1);
;     gload(kt + 2 < nk ? kt + 2 : nk - 1);
;     __builtin_amdgcn_sched_barrier(0);
;     const bf16_t* As = smem + buf * L::STAGE + (wm * 16 * MI + l15) * LDT + quad * 8;
;     const bf16_t* Bs = smem + buf * L::STAGE + L::A_ELEMS + (wn * 16 * NJ + l15) * LDT + quad * 8;
; #pragma unroll
;     for (int ks = 0; ks < 2; ++ks) {
;       if (MI * NJ >= 32 && ks == 1) asm volatile("" ::: "memory");
;       bf16x8 b[NJ];
; #pragma unroll
;       for (int j = 0; j < NJ; ++j) b[j] = *(const bf16x8*)(Bs + j * 16 * LDT + ks * 32);
; #pragma unroll
;       for (int i = 0; i < MI; ++i) {
;         const bf16x8 a = *(const bf16x8*)(As + i * 16 * LDT + ks * 32);
; #pragma unroll
;         for (int j = 0; j < NJ; ++j) acc[i][j] = SWAP ? mfma16(b[j], a, acc[i][j]) : mfma16(a, b[j], acc[i][j]);
;       }
;     }
;     __syncthreads();
;   }
.Lgm6_main:
	ds_read_b128 v[246:249], v181 offset:4608
	s_waitcnt lgkmcnt(4)
	v_mfma_f32_16x16x32_bf16 v[156:159], v[182:185], v[198:201], v[156:159]
	s_waitcnt lgkmcnt(3)
	v_mfma_f32_16x16x32_bf16 v[152:155], v[186:189], v[198:201], v[152:155]
	s_waitcnt lgkmcnt(2)
	v_mfma_f32_16x16x32_bf16 v[148:151], v[190:193], v[198:201], v[148:151]
	s_waitcnt lgkmcnt(1)
	v_mfma_f32_16x16x32_bf16 v[144:147], v[194:197], v[198:201], v[144:147]
	s_and_b32 s31, s30, 1
	s_xor_b32 s33, s31, 1
	s_mul_i32 s33, s33, 0x12000
	s_waitcnt vmcnt(7)
	v_cndmask_b32_e32 v139, 0, v139, vcc
	v_cndmask_b32_e32 v138, 0, v138, vcc
	v_cndmask_b32_e32 v137, 0, v137, vcc
	v_cndmask_b32_e32 v136, 0, v136, vcc
	v_add3_u32 v254, s33, v172, v169
	ds_write_b128 v254, v[136:139]
	ds_read_b128 v[250:253], v181 offset:6912
	v_mfma_f32_16x16x32_bf16 v[108:111], v[182:185], v[242:245], v[108:111]
	v_mfma_f32_16x16x32_bf16 v[104:107], v[186:189], v[242:245], v[104:107]
	v_mfma_f32_16x16x32_bf16 v[100:103], v[190:193], v[242:245], v[100:103]
	v_mfma_f32_16x16x32_bf16 v[96:99], v[194:197], v[242:245], v[96:99]
	s_waitcnt vmcnt(6)
	v_cndmask_b32_e64 v127, 0, v127, s[0:1]
	v_cndmask_b32_e64 v126, 0, v126, s[0:1]
	v_cndmask_b32_e64 v125, 0, v125, s[0:1]
	v_cndmask_b32_e64 v124, 0, v124, s[0:1]
	v_add3_u32 v136, s33, v173, v169
	ds_write_b128 v136, v[124:127]
	ds_read_b128 v[198:201], v181 offset:9216
	s_waitcnt lgkmcnt(4)
	v_mfma_f32_16x16x32_bf16 v[92:95], v[182:185], v[246:249], v[92:95]
	v_mfma_f32_16x16x32_bf16 v[88:91], v[186:189], v[246:249], v[88:91]
	v_mfma_f32_16x16x32_bf16 v[84:87], v[190:193], v[246:249], v[84:87]
	v_mfma_f32_16x16x32_bf16 v[80:83], v[194:197], v[246:249], v[80:83]
	ds_read_b128 v[242:245], v181 offset:11520
	s_waitcnt lgkmcnt(3)
	v_mfma_f32_16x16x32_bf16 v[76:79], v[182:185], v[250:253], v[76:79]
	s_waitcnt vmcnt(5)
	v_cndmask_b32_e64 v115, 0, v115, s[2:3]
	v_cndmask_b32_e64 v114, 0, v114, s[2:3]
	v_cndmask_b32_e64 v113, 0, v113, s[2:3]
	v_cndmask_b32_e64 v112, 0, v112, s[2:3]
	v_add3_u32 v124, s33, v174, v169
	ds_write_b128 v124, v[112:115]
	v_mfma_f32_16x16x32_bf16 v[72:75], v[186:189], v[250:253], v[72:75]
	v_mfma_f32_16x16x32_bf16 v[68:71], v[190:193], v[250:253], v[68:71]
	v_mfma_f32_16x16x32_bf16 v[64:67], v[194:197], v[250:253], v[64:67]
	ds_read_b128 v[246:249], v181 offset:13824
	s_waitcnt lgkmcnt(3)
	v_mfma_f32_16x16x32_bf16 v[60:63], v[182:185], v[198:201], v[60:63]
	s_waitcnt vmcnt(4)
	v_cndmask_b32_e64 v112, 0, v116, s[4:5]
	v_add3_u32 v116, s33, v175, v169
	s_min_u32 s33, s30, 13
	s_lshl_b32 s33, s33, 7
	v_cndmask_b32_e64 v115, 0, v119, s[4:5]
	v_cndmask_b32_e64 v114, 0, v118, s[4:5]
	v_cndmask_b32_e64 v113, 0, v117, s[4:5]
	s_add_u32 s34, s12, s33
	ds_write_b128 v116, v[112:115]
	v_mfma_f32_16x16x32_bf16 v[56:59], v[186:189], v[198:201], v[56:59]
	v_mfma_f32_16x16x32_bf16 v[52:55], v[190:193], v[198:201], v[52:55]
	v_mfma_f32_16x16x32_bf16 v[48:51], v[194:197], v[198:201], v[48:51]
	ds_read_b128 v[250:253], v181 offset:16128
	s_waitcnt lgkmcnt(4)
	v_mfma_f32_16x16x32_bf16 v[44:47], v[182:185], v[242:245], v[44:47]
	s_waitcnt vmcnt(3)
	ds_write_b128 v254, v[120:123] offset:36864
	v_mfma_f32_16x16x32_bf16 v[40:43], v[186:189], v[242:245], v[40:43]
	v_mfma_f32_16x16x32_bf16 v[36:39], v[190:193], v[242:245], v[36:39]
	v_mfma_f32_16x16x32_bf16 v[32:35], v[194:197], v[242:245], v[32:35]
	ds_read_b128 v[198:201], v181 offset:64
	s_waitcnt lgkmcnt(4)
	v_mfma_f32_16x16x32_bf16 v[28:31], v[182:185], v[246:249], v[28:31]
	s_waitcnt vmcnt(2)
	ds_write_b128 v136, v[128:131] offset:36864
	v_mfma_f32_16x16x32_bf16 v[24:27], v[186:189], v[246:249], v[24:27]
	v_mfma_f32_16x16x32_bf16 v[20:23], v[190:193], v[246:249], v[20:23]
	v_mfma_f32_16x16x32_bf16 v[16:19], v[194:197], v[246:249], v[16:19]
	ds_read_b128 v[242:245], v181 offset:2368
	s_waitcnt lgkmcnt(4)
	v_mfma_f32_16x16x32_bf16 v[12:15], v[182:185], v[250:253], v[12:15]
	ds_read_b128 v[182:185], v202 offset:36928
	s_waitcnt vmcnt(1)
; DI f32x4 mfma16(bf16x8 a, bf16x8 b, f32x4 c) { return __builtin_amdgcn_mfma_f32_16x16x32_bf16(a, b, c, 0, 0, 0); }
; template <int MI, int NJ, bool SWAP, class AP, class BP>
; DI void gemm_main(f32x4 (&acc)[MI][NJ], const AP& ap, int a_kstep, const BP& bp, int b_kstep, int nk, bf16_t* smem) {
;     ...
;   for (int kt = 0; kt < nk; ++kt) {
;     const int buf = kt & 1;
;     sstore(buf ^ 1);
;     gload(kt + 2 < nk ? kt + 2 : nk - 1);
;     __builtin_amdgcn_sched_barrier(0);
;     const bf16_t* As = smem + buf * L::STAGE + (wm * 16 * MI + l15) * LDT + quad * 8;
;     const bf16_t* Bs = smem + buf * L::STAGE + L::A_ELEMS + (wn * 16 * NJ + l15) * LDT + quad * 8;
; #pragma unroll
;     for (int ks = 0; ks < 2; ++ks) {
;       if (MI * NJ >= 32 && ks == 1) asm volatile("" ::: "memory");
;       bf16x8 b[NJ];
; #pragma unroll
;       for (int j = 0; j < NJ; ++j) b[j] = *(const bf16x8*)(Bs + j * 16 * LDT + ks * 32);
; #pragma unroll
;       for (int i = 0; i < MI; ++i) {
;         const bf16x8 a = *(const bf16x8*)(As + i * 16 * LDT + ks * 32);
; #pragma unroll
;         for (int j = 0; j < NJ; ++j) acc[i][j] = SWAP ? mfma16(b[j], a, acc[i][j]) : mfma16(a, b[j], acc[i][j]);
;       }
;     }
;     __syncthreads();
;   }
	ds_write_b128 v124, v[132:135] offset:36864
	v_mfma_f32_16x16x32_bf16 v[8:11], v[186:189], v[250:253], v[8:11]
	ds_read_b128 v[186:189], v202 offset:39232
	v_mfma_f32_16x16x32_bf16 v[4:7], v[190:193], v[250:253], v[4:7]
	ds_read_b128 v[190:193], v202 offset:41536
	v_mfma_f32_16x16x32_bf16 v[0:3], v[194:197], v[250:253], v[0:3]
	ds_read_b128 v[194:197], v202 offset:43840
	ds_read_b128 v[246:249], v181 offset:4672
	s_waitcnt lgkmcnt(5)
	v_mfma_f32_16x16x32_bf16 v[156:159], v[182:185], v[198:201], v[156:159]
	s_waitcnt lgkmcnt(3)
	v_mfma_f32_16x16x32_bf16 v[152:155], v[186:189], v[198:201], v[152:155]
	s_waitcnt vmcnt(0)
	ds_write_b128 v116, v[140:143] offset:36864
	s_waitcnt lgkmcnt(3)
	v_mfma_f32_16x16x32_bf16 v[148:151], v[190:193], v[198:201], v[148:151]
	s_waitcnt lgkmcnt(2)
	v_mfma_f32_16x16x32_bf16 v[144:147], v[194:197], v[198:201], v[144:147]
	s_addc_u32 s35, s13, 0
	global_load_dwordx4 v[136:139], v176, s[34:35] offset:256
	ds_read_b128 v[250:253], v181 offset:6976
	v_mfma_f32_16x16x32_bf16 v[108:111], v[182:185], v[242:245], v[108:111]
	v_mfma_f32_16x16x32_bf16 v[104:107], v[186:189], v[242:245], v[104:107]
	global_load_dwordx4 v[124:127], v177, s[34:35] offset:256
	v_mfma_f32_16x16x32_bf16 v[100:103], v[190:193], v[242:245], v[100:103]
	v_mfma_f32_16x16x32_bf16 v[96:99], v[194:197], v[242:245], v[96:99]
	ds_read_b128 v[198:201], v181 offset:9280
	s_waitcnt lgkmcnt(3)
	v_mfma_f32_16x16x32_bf16 v[92:95], v[182:185], v[246:249], v[92:95]
	global_load_dwordx4 v[112:115], v178, s[34:35] offset:256
	v_mfma_f32_16x16x32_bf16 v[88:91], v[186:189], v[246:249], v[88:91]
	v_mfma_f32_16x16x32_bf16 v[84:87], v[190:193], v[246:249], v[84:87]
	global_load_dwordx4 v[116:119], v179, s[34:35] offset:256
	v_mfma_f32_16x16x32_bf16 v[80:83], v[194:197], v[246:249], v[80:83]
	ds_read_b128 v[242:245], v181 offset:11584
	s_waitcnt lgkmcnt(2)
	v_mfma_f32_16x16x32_bf16 v[76:79], v[182:185], v[250:253], v[76:79]
	v_mfma_f32_16x16x32_bf16 v[72:75], v[186:189], v[250:253], v[72:75]
	s_add_u32 s34, s14, s33
	s_addc_u32 s35, s15, 0
	v_lshl_add_u64 v[120:121], v[160:161], 1, s[34:35]
	v_lshl_add_u64 v[128:129], v[162:163], 1, s[34:35]
	v_lshl_add_u64 v[132:133], v[164:165], 1, s[34:35]
	v_lshl_add_u64 v[140:141], v[166:167], 1, s[34:35]
	global_load_dwordx4 v[120:123], v[120:121], off offset:256
	v_mfma_f32_16x16x32_bf16 v[68:71], v[190:193], v[250:253], v[68:71]
	v_mfma_f32_16x16x32_bf16 v[64:67], v[194:197], v[250:253], v[64:67]
	global_load_dwordx4 v[128:131], v[128:129], off offset:256
	ds_read_b128 v[246:249], v181 offset:13888
	s_waitcnt lgkmcnt(2)
	v_mfma_f32_16x16x32_bf16 v[60:63], v[182:185], v[198:201], v[60:63]
	v_mfma_f32_16x16x32_bf16 v[56:59], v[186:189], v[198:201], v[56:59]
	v_mfma_f32_16x16x32_bf16 v[52:55], v[190:193], v[198:201], v[52:55]
	global_load_dwordx4 v[132:135], v[132:133], off offset:256
	v_mfma_f32_16x16x32_bf16 v[48:51], v[194:197], v[198:201], v[48:51]
	ds_read_b128 v[250:253], v181 offset:16192
	s_waitcnt lgkmcnt(2)
	v_mfma_f32_16x16x32_bf16 v[44:47], v[182:185], v[242:245], v[44:47]
	global_load_dwordx4 v[140:143], v[140:141], off offset:256
	v_mfma_f32_16x16x32_bf16 v[40:43], v[186:189], v[242:245], v[40:43]
	v_mfma_f32_16x16x32_bf16 v[36:39], v[190:193], v[242:245], v[36:39]
	v_mfma_f32_16x16x32_bf16 v[32:35], v[194:197], v[242:245], v[32:35]
	s_waitcnt lgkmcnt(0)
	s_barrier
	s_add_i32 s30, s30, 1
	s_cmp_lg_u32 s30, 16
	s_cbranch_scc0 .Lgm6_exit
	s_and_b32 s98, s30, 1
	s_mul_i32 s98, s98, 0x12000
	v_add3_u32 v181, s98, v170, v180
	v_add3_u32 v202, s98, v171, v180
	ds_read_b128 v[198:201], v181
	ds_read_b128 v[242:245], v181 offset:2304
	v_mfma_f32_16x16x32_bf16 v[28:31], v[182:185], v[246:249], v[28:31]
	v_mfma_f32_16x16x32_bf16 v[12:15], v[182:185], v[250:253], v[12:15]
	ds_read_b128 v[182:185], v202 offset:36864
	v_mfma_f32_16x16x32_bf16 v[24:27], v[186:189], v[246:249], v[24:27]
	v_mfma_f32_16x16x32_bf16 v[8:11], v[186:189], v[250:253], v[8:11]
	ds_read_b128 v[186:189], v202 offset:39168
	v_mfma_f32_16x16x32_bf16 v[20:23], v[190:193], v[246:249], v[20:23]
	v_mfma_f32_16x16x32_bf16 v[4:7], v[190:193], v[250:253], v[4:7]
	ds_read_b128 v[190:193], v202 offset:41472
	v_mfma_f32_16x16x32_bf16 v[16:19], v[194:197], v[246:249], v[16:19]
	v_mfma_f32_16x16x32_bf16 v[0:3], v[194:197], v[250:253], v[0:3]
	ds_read_b128 v[194:197], v202 offset:43776
	s_branch .Lgm6_main

; DI f32x4 mfma16(bf16x8 a, bf16x8 b, f32x4 c) { return __builtin_amdgcn_mfma_f32_16x16x32_bf16(a, b, c, 0, 0, 0); }
; template <int MI, int NJ, bool SWAP, class AP, class BP>
; DI void gemm_main(f32x4 (&acc)[MI][NJ], const AP& ap, int a_kstep, const BP& bp, int b_kstep, int nk, bf16_t* smem) {
;     ...
;   for (int kt = 0; kt < nk; ++kt) {
;     const int buf = kt & 1;
;     sstore(buf ^ 1);
;     gload(kt + 2 < nk ? kt + 2 : nk - 1);
;     __builtin_amdgcn_sched_barrier(0);
;     const bf16_t* As = smem + buf * L::STAGE + (wm * 16 * MI + l15) * LDT + quad * 8;
;     const bf16_t* Bs = smem + buf * L::STAGE + L::A_ELEMS + (wn * 16 * NJ + l15) * LDT + quad * 8;
; #pragma unroll
;     for (int ks = 0; ks < 2; ++ks) {
;       if (MI * NJ >= 32 && ks == 1) asm volatile("" ::: "memory");
;       bf16x8 b[NJ];
; #pragma unroll
;       for (int j = 0; j < NJ; ++j) b[j] = *(const bf16x8*)(Bs + j * 16 * LDT + ks * 32);
; #pragma unroll
;       for (int i = 0; i < MI; ++i) {
;         const bf16x8 a = *(const bf16x8*)(As + i * 16 * LDT + ks * 32);
; #pragma unroll
;         for (int j = 0; j < NJ; ++j) acc[i][j] = SWAP ? mfma16(b[j], a, acc[i][j]) : mfma16(a, b[j], acc[i][j]);
;       }
;     }
;     __syncthreads();
;   }
.Lgm7_main:
	ds_read_b128 v[242:245], v177 offset:4608
	s_waitcnt lgkmcnt(4)
	v_mfma_f32_16x16x32_bf16 v[156:159], v[178:181], v[194:197], v[156:159]
	s_waitcnt lgkmcnt(3)
	v_mfma_f32_16x16x32_bf16 v[152:155], v[182:185], v[194:197], v[152:155]
	s_waitcnt lgkmcnt(2)
	v_mfma_f32_16x16x32_bf16 v[148:151], v[186:189], v[194:197], v[148:151]
	s_waitcnt lgkmcnt(1)
	v_mfma_f32_16x16x32_bf16 v[144:147], v[190:193], v[194:197], v[144:147]
	s_and_b32 s24, s21, 1
	s_min_u32 s22, s21, 41
	s_xor_b32 s23, s24, 1
	s_lshl_b32 s25, s22, 7
	s_mul_i32 s23, s23, 0x12000
	s_add_u32 s22, s6, s25
	v_add3_u32 v250, s23, v172, v170
	v_add3_u32 v251, s23, v173, v170
	v_add3_u32 v252, s23, v174, v170
	v_add3_u32 v253, s23, v175, v170
	s_addc_u32 s23, s7, 0
	s_waitcnt vmcnt(7)
	ds_write_b128 v250, v[112:115]
	ds_read_b128 v[246:249], v177 offset:6912
	v_mfma_f32_16x16x32_bf16 v[108:111], v[178:181], v[198:201], v[108:111]
	v_mfma_f32_16x16x32_bf16 v[104:107], v[182:185], v[198:201], v[104:107]
	v_mfma_f32_16x16x32_bf16 v[100:103], v[186:189], v[198:201], v[100:103]
	v_mfma_f32_16x16x32_bf16 v[96:99], v[190:193], v[198:201], v[96:99]
	s_waitcnt vmcnt(6)
	ds_write_b128 v251, v[116:119]
	ds_read_b128 v[194:197], v177 offset:9216
	s_waitcnt lgkmcnt(4)
	v_mfma_f32_16x16x32_bf16 v[92:95], v[178:181], v[242:245], v[92:95]
	v_mfma_f32_16x16x32_bf16 v[88:91], v[182:185], v[242:245], v[88:91]
	v_mfma_f32_16x16x32_bf16 v[84:87], v[186:189], v[242:245], v[84:87]
	v_mfma_f32_16x16x32_bf16 v[80:83], v[190:193], v[242:245], v[80:83]
	ds_read_b128 v[198:201], v177 offset:11520
	s_waitcnt lgkmcnt(3)
	v_mfma_f32_16x16x32_bf16 v[76:79], v[178:181], v[246:249], v[76:79]
	s_waitcnt vmcnt(5)
	ds_write_b128 v252, v[120:123]
	v_mfma_f32_16x16x32_bf16 v[72:75], v[182:185], v[246:249], v[72:75]
	v_mfma_f32_16x16x32_bf16 v[68:71], v[186:189], v[246:249], v[68:71]
	v_mfma_f32_16x16x32_bf16 v[64:67], v[190:193], v[246:249], v[64:67]
	ds_read_b128 v[242:245], v177 offset:13824
	s_waitcnt lgkmcnt(3)
	v_mfma_f32_16x16x32_bf16 v[60:63], v[178:181], v[194:197], v[60:63]
	s_waitcnt vmcnt(4)
	ds_write_b128 v253, v[124:127]
	v_mfma_f32_16x16x32_bf16 v[56:59], v[182:185], v[194:197], v[56:59]
	v_mfma_f32_16x16x32_bf16 v[52:55], v[186:189], v[194:197], v[52:55]
	v_mfma_f32_16x16x32_bf16 v[48:51], v[190:193], v[194:197], v[48:51]
	ds_read_b128 v[246:249], v177 offset:16128
	s_waitcnt lgkmcnt(4)
	v_mfma_f32_16x16x32_bf16 v[44:47], v[178:181], v[198:201], v[44:47]
	s_waitcnt vmcnt(3)
	ds_write_b128 v250, v[128:131] offset:36864
	v_mfma_f32_16x16x32_bf16 v[40:43], v[182:185], v[198:201], v[40:43]
	v_mfma_f32_16x16x32_bf16 v[36:39], v[186:189], v[198:201], v[36:39]
	v_mfma_f32_16x16x32_bf16 v[32:35], v[190:193], v[198:201], v[32:35]
	ds_read_b128 v[194:197], v177 offset:64
	s_waitcnt lgkmcnt(4)
	v_mfma_f32_16x16x32_bf16 v[28:31], v[178:181], v[242:245], v[28:31]
	s_waitcnt vmcnt(2)
	ds_write_b128 v251, v[132:135] offset:36864
	v_mfma_f32_16x16x32_bf16 v[24:27], v[182:185], v[242:245], v[24:27]
	v_mfma_f32_16x16x32_bf16 v[20:23], v[186:189], v[242:245], v[20:23]
	v_mfma_f32_16x16x32_bf16 v[16:19], v[190:193], v[242:245], v[16:19]
	ds_read_b128 v[198:201], v177 offset:2368
	s_waitcnt lgkmcnt(4)
	v_mfma_f32_16x16x32_bf16 v[8:11], v[178:181], v[246:249], v[8:11]
	ds_read_b128 v[178:181], v202 offset:36928
	s_waitcnt vmcnt(1)
	ds_write_b128 v252, v[136:139] offset:36864
	v_mfma_f32_16x16x32_bf16 v[4:7], v[182:185], v[246:249], v[4:7]
	ds_read_b128 v[182:185], v202 offset:39232
	v_mfma_f32_16x16x32_bf16 v[0:3], v[186:189], v[246:249], v[0:3]
	ds_read_b128 v[186:189], v202 offset:41536
	v_mfma_f32_16x16x32_bf16 v[12:15], v[190:193], v[246:249], v[12:15]
	ds_read_b128 v[190:193], v202 offset:43840
	ds_read_b128 v[242:245], v177 offset:4672
	s_waitcnt lgkmcnt(5)
	v_mfma_f32_16x16x32_bf16 v[156:159], v[178:181], v[194:197], v[156:159]
	s_waitcnt lgkmcnt(3)
	v_mfma_f32_16x16x32_bf16 v[152:155], v[182:185], v[194:197], v[152:155]
	s_waitcnt vmcnt(0)
	ds_write_b128 v253, v[140:143] offset:36864
	s_waitcnt lgkmcnt(3)
	v_mfma_f32_16x16x32_bf16 v[148:151], v[186:189], v[194:197], v[148:151]
	s_waitcnt lgkmcnt(2)
	v_mfma_f32_16x16x32_bf16 v[144:147], v[190:193], v[194:197], v[144:147]
	v_lshl_add_u64 v[112:113], s[22:23], 0, v[162:163]
	v_lshl_add_u64 v[116:117], s[22:23], 0, v[164:165]
	v_lshl_add_u64 v[120:121], s[22:23], 0, v[166:167]
	v_lshl_add_u64 v[124:125], s[22:23], 0, v[168:169]
	s_add_u32 s22, s8, s25
	s_addc_u32 s23, s9, 0
	v_lshl_add_u64 v[128:129], s[22:23], 0, v[162:163]
	v_lshl_add_u64 v[132:133], s[22:23], 0, v[164:165]
	v_lshl_add_u64 v[136:137], s[22:23], 0, v[166:167]
	v_lshl_add_u64 v[140:141], s[22:23], 0, v[168:169]
	global_load_dwordx4 v[112:115], v[112:113], off offset:256
	ds_read_b128 v[246:249], v177 offset:6976
	v_mfma_f32_16x16x32_bf16 v[108:111], v[178:181], v[198:201], v[108:111]
	v_mfma_f32_16x16x32_bf16 v[104:107], v[182:185], v[198:201], v[104:107]
	global_load_dwordx4 v[116:119], v[116:117], off offset:256
	v_mfma_f32_16x16x32_bf16 v[100:103], v[186:189], v[198:201], v[100:103]
	v_mfma_f32_16x16x32_bf16 v[96:99], v[190:193], v[198:201], v[96:99]
	ds_read_b128 v[194:197], v177 offset:9280
	s_waitcnt lgkmcnt(3)
	v_mfma_f32_16x16x32_bf16 v[92:95], v[178:181], v[242:245], v[92:95]
	global_load_dwordx4 v[120:123], v[120:121], off offset:256
	v_mfma_f32_16x16x32_bf16 v[88:91], v[182:185], v[242:245], v[88:91]
	v_mfma_f32_16x16x32_bf16 v[84:87], v[186:189], v[242:245], v[84:87]
	global_load_dwordx4 v[124:127], v[124:125], off offset:256
	v_mfma_f32_16x16x32_bf16 v[80:83], v[190:193], v[242:245], v[80:83]
	ds_read_b128 v[198:201], v177 offset:11584
	s_waitcnt lgkmcnt(2)
	v_mfma_f32_16x16x32_bf16 v[76:79], v[178:181], v[246:249], v[76:79]
	v_mfma_f32_16x16x32_bf16 v[72:75], v[182:185], v[246:249], v[72:75]
	global_load_dwordx4 v[128:131], v[128:129], off offset:256
	v_mfma_f32_16x16x32_bf16 v[68:71], v[186:189], v[246:249], v[68:71]
	v_mfma_f32_16x16x32_bf16 v[64:67], v[190:193], v[246:249], v[64:67]
	global_load_dwordx4 v[132:135], v[132:133], off offset:256
	ds_read_b128 v[242:245], v177 offset:13888
	s_waitcnt lgkmcnt(2)
	v_mfma_f32_16x16x32_bf16 v[60:63], v[178:181], v[194:197], v[60:63]
	v_mfma_f32_16x16x32_bf16 v[56:59], v[182:185], v[194:197], v[56:59]
	v_mfma_f32_16x16x32_bf16 v[52:55], v[186:189], v[194:197], v[52:55]
	global_load_dwordx4 v[136:139], v[136:137], off offset:256
	v_mfma_f32_16x16x32_bf16 v[48:51], v[190:193], v[194:197], v[48:51]
	ds_read_b128 v[246:249], v177 offset:16192
	s_waitcnt lgkmcnt(2)
	v_mfma_f32_16x16x32_bf16 v[44:47], v[178:181], v[198:201], v[44:47]
	global_load_dwordx4 v[140:143], v[140:141], off offset:256
	v_mfma_f32_16x16x32_bf16 v[40:43], v[182:185], v[198:201], v[40:43]
	v_mfma_f32_16x16x32_bf16 v[36:39], v[186:189], v[198:201], v[36:39]
	v_mfma_f32_16x16x32_bf16 v[32:35], v[190:193], v[198:201], v[32:35]
	s_waitcnt lgkmcnt(0)
	s_barrier
; DI f32x4 mfma16(bf16x8 a, bf16x8 b, f32x4 c) { return __builtin_amdgcn_mfma_f32_16x16x32_bf16(a, b, c, 0, 0, 0); }
; template <int MI, int NJ, bool SWAP, class AP, class BP>
; DI void gemm_main(f32x4 (&acc)[MI][NJ], const AP& ap, int a_kstep, const BP& bp, int b_kstep, int nk, bf16_t* smem) {
;     ...
;   for (int kt = 0; kt < nk; ++kt) {
;     const int buf = kt & 1;
;     sstore(buf ^ 1);
;     gload(kt + 2 < nk ? kt + 2 : nk - 1);
;     __builtin_amdgcn_sched_barrier(0);
;     const bf16_t* As = smem + buf * L::STAGE + (wm * 16 * MI + l15) * LDT + quad * 8;
;     const bf16_t* Bs = smem + buf * L::STAGE + L::A_ELEMS + (wn * 16 * NJ + l15) * LDT + quad * 8;
; #pragma unroll
;     for (int ks = 0; ks < 2; ++ks) {
;       if (MI * NJ >= 32 && ks == 1) asm volatile("" ::: "memory");
;       bf16x8 b[NJ];
; #pragma unroll
;       for (int j = 0; j < NJ; ++j) b[j] = *(const bf16x8*)(Bs + j * 16 * LDT + ks * 32);
; #pragma unroll
;       for (int i = 0; i < MI; ++i) {
;         const bf16x8 a = *(const bf16x8*)(As + i * 16 * LDT + ks * 32);
; #pragma unroll
;         for (int j = 0; j < NJ; ++j) acc[i][j] = SWAP ? mfma16(b[j], a, acc[i][j]) : mfma16(a, b[j], acc[i][j]);
;       }
;     }
;     __syncthreads();
	s_add_i32 s21, s21, 1
	s_cmp_lg_u32 s21, 44
	s_cbranch_scc0 .Lgm7_exit
	s_and_b32 s98, s21, 1
	s_mul_i32 s98, s98, 0x12000
	v_add3_u32 v202, s98, v160, v176
	v_add3_u32 v177, s98, v171, v176
	ds_read_b128 v[194:197], v177
	ds_read_b128 v[198:201], v177 offset:2304
	v_mfma_f32_16x16x32_bf16 v[28:31], v[178:181], v[242:245], v[28:31]
	v_mfma_f32_16x16x32_bf16 v[8:11], v[178:181], v[246:249], v[8:11]
	ds_read_b128 v[178:181], v202 offset:36864
	v_mfma_f32_16x16x32_bf16 v[24:27], v[182:185], v[242:245], v[24:27]
	v_mfma_f32_16x16x32_bf16 v[4:7], v[182:185], v[246:249], v[4:7]
	ds_read_b128 v[182:185], v202 offset:39168
	v_mfma_f32_16x16x32_bf16 v[20:23], v[186:189], v[242:245], v[20:23]
	v_mfma_f32_16x16x32_bf16 v[0:3], v[186:189], v[246:249], v[0:3]
	ds_read_b128 v[186:189], v202 offset:41472
	v_mfma_f32_16x16x32_bf16 v[16:19], v[190:193], v[242:245], v[16:19]
	v_mfma_f32_16x16x32_bf16 v[12:15], v[190:193], v[246:249], v[12:15]
	ds_read_b128 v[190:193], v202 offset:43776
	s_branch .Lgm7_main

; DI f32x4 mfma16(bf16x8 a, bf16x8 b, f32x4 c) { return __builtin_amdgcn_mfma_f32_16x16x32_bf16(a, b, c, 0, 0, 0); }
; template <int MI, int NJ, bool SWAP, class AP, class BP>
; DI void gemm_main(f32x4 (&acc)[MI][NJ], const AP& ap, int a_kstep, const BP& bp, int b_kstep, int nk, bf16_t* smem) {
;     ...
;   auto gload = [&](int kt) {
;     const bf16_t* ab = ap.base + (size_t)kt * a_kstep; const bf16_t* bb = bp.base + (size_t)kt * b_kstep;
; #pragma unroll
;     for (int i = 0; i < CA; ++i) ra[i] = *(const u32x4*)(ab + pa[i]);
; #pragma unroll
;     for (int i = 0; i < CB; ++i) rb[i] = *(const u32x4*)(bb + pb[i]);
;   };
;   auto sstore = [&](int buf) {
;     bf16_t* As = smem + buf * L::STAGE; bf16_t* Bs = As + L::A_ELEMS;
; #pragma unroll
;     for (int i = 0; i < CA; ++i) { const int c = tid + NTHR * i; *(u32x4*)(As + (c >> 3) * LDT + (c & 7) * 8) = oka[i] ? ra[i] : (u32x4){0u, 0u, 0u, 0u}; }
; #pragma unroll
;     for (int i = 0; i < CB; ++i) { const int c = tid + NTHR * i; *(u32x4*)(Bs + (c >> 3) * LDT + (c & 7) * 8) = rb[i]; }
;   };
;   gload(0); sstore(0); gload(nk > 1 ? 1 : 0); __syncthreads();
; #pragma unroll 1
;   for (int kt = 0; kt < nk; ++kt) {
;     const int buf = kt & 1;
;     sstore(buf ^ 1);
;     gload(kt + 2 < nk ? kt + 2 : nk - 1);
;     __builtin_amdgcn_sched_barrier(0);
;     const bf16_t* As = smem + buf * L::STAGE + (wm * 16 * MI + l15) * LDT + quad * 8;
;     const bf16_t* Bs = smem + buf * L::STAGE + L::A_ELEMS + (wn * 16 * NJ + l15) * LDT + quad * 8;
; #pragma unroll
;     for (int ks = 0; ks < 2; ++ks) {
;       if (MI * NJ >= 32 && ks == 1) asm volatile("" ::: "memory");
;       bf16x8 b[NJ];
; #pragma unroll
;       for (int j = 0; j < NJ; ++j) b[j] = *(const bf16x8*)(Bs + j * 16 * LDT + ks * 32);
; #pragma unroll
;       for (int i = 0; i < MI; ++i) {
;         const bf16x8 a = *(const bf16x8*)(As + i * 16 * LDT + ks * 32);
; #pragma unroll
;         for (int j = 0; j < NJ; ++j) acc[i][j] = SWAP ? mfma16(b[j], a, acc[i][j]) : mfma16(a, b[j], acc[i][j]);
;       }
;     }
;     __syncthreads();
;   }
.Lgm8_main:
	ds_read_b128 v[246:249], v210 offset:4608
	s_waitcnt lgkmcnt(4)
	v_mfma_f32_16x16x32_bf16 v[124:127], v[190:193], v[206:209], v[124:127]
	s_waitcnt lgkmcnt(3)
	v_mfma_f32_16x16x32_bf16 v[120:123], v[194:197], v[206:209], v[120:123]
	s_waitcnt lgkmcnt(2)
	v_mfma_f32_16x16x32_bf16 v[116:119], v[198:201], v[206:209], v[116:119]
	s_waitcnt lgkmcnt(1)
	v_mfma_f32_16x16x32_bf16 v[112:115], v[202:205], v[206:209], v[112:115]
	s_and_b32 s5, s4, 1
	s_xor_b32 s23, s5, 1
	s_mul_i32 s23, s23, 0x12000
	v_add3_u32 v254, s23, v185, v183
	s_waitcnt vmcnt(7)
	ds_write_b128 v254, v[128:131]
	ds_read_b128 v[250:253], v210 offset:6912
	v_mfma_f32_16x16x32_bf16 v[108:111], v[190:193], v[242:245], v[108:111]
	v_mfma_f32_16x16x32_bf16 v[104:107], v[194:197], v[242:245], v[104:107]
	v_mfma_f32_16x16x32_bf16 v[100:103], v[198:201], v[242:245], v[100:103]
	v_mfma_f32_16x16x32_bf16 v[96:99], v[202:205], v[242:245], v[96:99]
	v_add3_u32 v128, s23, v187, v183
	v_add3_u32 v129, s23, v188, v183
	v_add3_u32 v130, s23, v189, v183
	s_min_u32 s23, s4, 13
	s_lshl_b32 s23, s23, 7
	s_add_u32 s26, s0, s23
	s_addc_u32 s27, s1, 0
	s_waitcnt vmcnt(6)
	ds_write_b128 v128, v[132:135]
	ds_read_b128 v[206:209], v210 offset:9216
	s_waitcnt lgkmcnt(4)
	v_mfma_f32_16x16x32_bf16 v[92:95], v[190:193], v[246:249], v[92:95]
	v_mfma_f32_16x16x32_bf16 v[88:91], v[194:197], v[246:249], v[88:91]
	v_mfma_f32_16x16x32_bf16 v[84:87], v[198:201], v[246:249], v[84:87]
	v_mfma_f32_16x16x32_bf16 v[80:83], v[202:205], v[246:249], v[80:83]
	ds_read_b128 v[242:245], v210 offset:11520
	s_waitcnt lgkmcnt(3)
	v_mfma_f32_16x16x32_bf16 v[76:79], v[190:193], v[250:253], v[76:79]
	s_waitcnt vmcnt(5)
	ds_write_b128 v129, v[136:139]
	v_mfma_f32_16x16x32_bf16 v[72:75], v[194:197], v[250:253], v[72:75]
	v_mfma_f32_16x16x32_bf16 v[68:71], v[198:201], v[250:253], v[68:71]
	v_mfma_f32_16x16x32_bf16 v[64:67], v[202:205], v[250:253], v[64:67]
	ds_read_b128 v[246:249], v210 offset:13824
	s_waitcnt lgkmcnt(3)
	v_mfma_f32_16x16x32_bf16 v[60:63], v[190:193], v[206:209], v[60:63]
	s_waitcnt vmcnt(4)
	ds_write_b128 v130, v[140:143]
	v_mfma_f32_16x16x32_bf16 v[56:59], v[194:197], v[206:209], v[56:59]
	v_mfma_f32_16x16x32_bf16 v[52:55], v[198:201], v[206:209], v[52:55]
	v_mfma_f32_16x16x32_bf16 v[48:51], v[202:205], v[206:209], v[48:51]
	ds_read_b128 v[250:253], v210 offset:16128
	s_waitcnt lgkmcnt(4)
	v_mfma_f32_16x16x32_bf16 v[44:47], v[190:193], v[242:245], v[44:47]
	s_waitcnt vmcnt(3)
	ds_write_b128 v254, v[144:147] offset:36864
	v_mfma_f32_16x16x32_bf16 v[40:43], v[194:197], v[242:245], v[40:43]
	v_mfma_f32_16x16x32_bf16 v[36:39], v[198:201], v[242:245], v[36:39]
	v_mfma_f32_16x16x32_bf16 v[32:35], v[202:205], v[242:245], v[32:35]
	ds_read_b128 v[206:209], v210 offset:64
	s_waitcnt lgkmcnt(4)
	v_mfma_f32_16x16x32_bf16 v[28:31], v[190:193], v[246:249], v[28:31]
	s_waitcnt vmcnt(2)
	ds_write_b128 v128, v[148:151] offset:36864
	v_mfma_f32_16x16x32_bf16 v[24:27], v[194:197], v[246:249], v[24:27]
	v_mfma_f32_16x16x32_bf16 v[20:23], v[198:201], v[246:249], v[20:23]
	v_mfma_f32_16x16x32_bf16 v[16:19], v[202:205], v[246:249], v[16:19]
	ds_read_b128 v[242:245], v210 offset:2368
	s_waitcnt lgkmcnt(4)
	v_mfma_f32_16x16x32_bf16 v[12:15], v[190:193], v[250:253], v[12:15]
	ds_read_b128 v[190:193], v211 offset:36928
	s_waitcnt vmcnt(1)
	ds_write_b128 v129, v[152:155] offset:36864
	v_mfma_f32_16x16x32_bf16 v[8:11], v[194:197], v[250:253], v[8:11]
	ds_read_b128 v[194:197], v211 offset:39232
	v_mfma_f32_16x16x32_bf16 v[4:7], v[198:201], v[250:253], v[4:7]
	ds_read_b128 v[198:201], v211 offset:41536
	v_mfma_f32_16x16x32_bf16 v[0:3], v[202:205], v[250:253], v[0:3]
	ds_read_b128 v[202:205], v211 offset:43840
	ds_read_b128 v[246:249], v210 offset:4672
	s_waitcnt lgkmcnt(5)
	v_mfma_f32_16x16x32_bf16 v[124:127], v[190:193], v[206:209], v[124:127]
	s_waitcnt lgkmcnt(3)
	v_mfma_f32_16x16x32_bf16 v[120:123], v[194:197], v[206:209], v[120:123]
	s_waitcnt vmcnt(0)
	ds_write_b128 v130, v[156:159] offset:36864
	s_waitcnt lgkmcnt(3)
	v_mfma_f32_16x16x32_bf16 v[116:119], v[198:201], v[206:209], v[116:119]
	s_waitcnt lgkmcnt(2)
	v_mfma_f32_16x16x32_bf16 v[112:115], v[202:205], v[206:209], v[112:115]
	v_lshl_add_u64 v[128:129], s[26:27], 0, v[162:163]
	v_lshl_add_u64 v[132:133], s[26:27], 0, v[164:165]
	v_lshl_add_u64 v[136:137], s[26:27], 0, v[166:167]
	v_lshl_add_u64 v[140:141], s[26:27], 0, v[168:169]
	s_add_u32 s26, s2, s23
	s_addc_u32 s27, s3, 0
	v_lshl_add_u64 v[144:145], s[26:27], 0, v[162:163]
	v_lshl_add_u64 v[148:149], s[26:27], 0, v[164:165]
	v_lshl_add_u64 v[152:153], s[26:27], 0, v[166:167]
	v_lshl_add_u64 v[156:157], s[26:27], 0, v[168:169]
	global_load_dwordx4 v[128:131], v[128:129], off offset:256
	ds_read_b128 v[250:253], v210 offset:6976
	v_mfma_f32_16x16x32_bf16 v[108:111], v[190:193], v[242:245], v[108:111]
	v_mfma_f32_16x16x32_bf16 v[104:107], v[194:197], v[242:245], v[104:107]
	global_load_dwordx4 v[132:135], v[132:133], off offset:256
	v_mfma_f32_16x16x32_bf16 v[100:103], v[198:201], v[242:245], v[100:103]
	v_mfma_f32_16x16x32_bf16 v[96:99], v[202:205], v[242:245], v[96:99]
	ds_read_b128 v[206:209], v210 offset:9280
	s_waitcnt lgkmcnt(3)
	v_mfma_f32_16x16x32_bf16 v[92:95], v[190:193], v[246:249], v[92:95]
	global_load_dwordx4 v[136:139], v[136:137], off offset:256
	v_mfma_f32_16x16x32_bf16 v[88:91], v[194:197], v[246:249], v[88:91]
	v_mfma_f32_16x16x32_bf16 v[84:87], v[198:201], v[246:249], v[84:87]
	global_load_dwordx4 v[140:143], v[140:141], off offset:256
	v_mfma_f32_16x16x32_bf16 v[80:83], v[202:205], v[246:249], v[80:83]
	ds_read_b128 v[242:245], v210 offset:11584
	s_waitcnt lgkmcnt(2)
	v_mfma_f32_16x16x32_bf16 v[76:79], v[190:193], v[250:253], v[76:79]
	v_mfma_f32_16x16x32_bf16 v[72:75], v[194:197], v[250:253], v[72:75]
	global_load_dwordx4 v[144:147], v[144:145], off offset:256
	v_mfma_f32_16x16x32_bf16 v[68:71], v[198:201], v[250:253], v[68:71]
	v_mfma_f32_16x16x32_bf16 v[64:67], v[202:205], v[250:253], v[64:67]
	global_load_dwordx4 v[148:151], v[148:149], off offset:256
	ds_read_b128 v[246:249], v210 offset:13888
	s_waitcnt lgkmcnt(2)
	v_mfma_f32_16x16x32_bf16 v[60:63], v[190:193], v[206:209], v[60:63]
	v_mfma_f32_16x16x32_bf16 v[56:59], v[194:197], v[206:209], v[56:59]
	v_mfma_f32_16x16x32_bf16 v[52:55], v[198:201], v[206:209], v[52:55]
	global_load_dwordx4 v[152:155], v[152:153], off offset:256
	v_mfma_f32_16x16x32_bf16 v[48:51], v[202:205], v[206:209], v[48:51]
	ds_read_b128 v[250:253], v210 offset:16192
	s_waitcnt lgkmcnt(2)
	v_mfma_f32_16x16x32_bf16 v[44:47], v[190:193], v[242:245], v[44:47]
	global_load_dwordx4 v[156:159], v[156:157], off offset:256
	v_mfma_f32_16x16x32_bf16 v[40:43], v[194:197], v[242:245], v[40:43]
	v_mfma_f32_16x16x32_bf16 v[36:39], v[198:201], v[242:245], v[36:39]
	v_mfma_f32_16x16x32_bf16 v[32:35], v[202:205], v[242:245], v[32:35]
	s_waitcnt lgkmcnt(0)
	s_barrier
; DI f32x4 mfma16(bf16x8 a, bf16x8 b, f32x4 c) { return __builtin_amdgcn_mfma_f32_16x16x32_bf16(a, b, c, 0, 0, 0); }
; template <int MI, int NJ, bool SWAP, class AP, class BP>
; DI void gemm_main(f32x4 (&acc)[MI][NJ], const AP& ap, int a_kstep, const BP& bp, int b_kstep, int nk, bf16_t* smem) {
;     ...
;   for (int kt = 0; kt < nk; ++kt) {
;     const int buf = kt & 1;
;     sstore(buf ^ 1);
;     gload(kt + 2 < nk ? kt + 2 : nk - 1);
;     __builtin_amdgcn_sched_barrier(0);
;     const bf16_t* As = smem + buf * L::STAGE + (wm * 16 * MI + l15) * LDT + quad * 8;
;     const bf16_t* Bs = smem + buf * L::STAGE + L::A_ELEMS + (wn * 16 * NJ + l15) * LDT + quad * 8;
; #pragma unroll
;     for (int ks = 0; ks < 2; ++ks) {
;       if (MI * NJ >= 32 && ks == 1) asm volatile("" ::: "memory");
;       bf16x8 b[NJ];
; #pragma unroll
;       for (int j = 0; j < NJ; ++j) b[j] = *(const bf16x8*)(Bs + j * 16 * LDT + ks * 32);
; #pragma unroll
;       for (int i = 0; i < MI; ++i) {
;         const bf16x8 a = *(const bf16x8*)(As + i * 16 * LDT + ks * 32);
; #pragma unroll
;         for (int j = 0; j < NJ; ++j) acc[i][j] = SWAP ? mfma16(b[j], a, acc[i][j]) : mfma16(a, b[j], acc[i][j]);
;       }
;     }
;     __syncthreads();
	s_add_i32 s4, s4, 1
	s_cmp_lg_u32 s4, 16
	s_cbranch_scc0 .Lgm8_exit
	s_and_b32 s98, s4, 1
	s_mul_i32 s98, s98, 0x12000
	v_add3_u32 v210, s98, v184, v186
	v_add3_u32 v211, s98, v160, v186
	ds_read_b128 v[206:209], v210
	ds_read_b128 v[242:245], v210 offset:2304
	v_mfma_f32_16x16x32_bf16 v[28:31], v[190:193], v[246:249], v[28:31]
	v_mfma_f32_16x16x32_bf16 v[12:15], v[190:193], v[250:253], v[12:15]
	ds_read_b128 v[190:193], v211 offset:36864
	v_mfma_f32_16x16x32_bf16 v[24:27], v[194:197], v[246:249], v[24:27]
	v_mfma_f32_16x16x32_bf16 v[8:11], v[194:197], v[250:253], v[8:11]
	ds_read_b128 v[194:197], v211 offset:39168
	v_mfma_f32_16x16x32_bf16 v[20:23], v[198:201], v[246:249], v[20:23]
	v_mfma_f32_16x16x32_bf16 v[4:7], v[198:201], v[250:253], v[4:7]
	ds_read_b128 v[198:201], v211 offset:41472
	v_mfma_f32_16x16x32_bf16 v[16:19], v[202:205], v[246:249], v[16:19]
	v_mfma_f32_16x16x32_bf16 v[0:3], v[202:205], v[250:253], v[0:3]
	ds_read_b128 v[202:205], v211 offset:43776
	s_branch .Lgm8_main

; DI f32x4 mfma16(bf16x8 a, bf16x8 b, f32x4 c) { return __builtin_amdgcn_mfma_f32_16x16x32_bf16(a, b, c, 0, 0, 0); }
; template <int MI, int NJ, bool SWAP, class AP, class BP>
; DI void gemm_main(f32x4 (&acc)[MI][NJ], const AP& ap, int a_kstep, const BP& bp, int b_kstep, int nk, bf16_t* smem) {
;     ...
;   auto gload = [&](int kt) {
;     const bf16_t* ab = ap.base + (size_t)kt * a_kstep; const bf16_t* bb = bp.base + (size_t)kt * b_kstep;
; #pragma unroll
;     for (int i = 0; i < CA; ++i) ra[i] = *(const u32x4*)(ab + pa[i]);
; #pragma unroll
;     for (int i = 0; i < CB; ++i) rb[i] = *(const u32x4*)(bb + pb[i]);
;   };
;   auto sstore = [&](int buf) {
;     bf16_t* As = smem + buf * L::STAGE; bf16_t* Bs = As + L::A_ELEMS;
; #pragma unroll
;     for (int i = 0; i < CA; ++i) { const int c = tid + NTHR * i; *(u32x4*)(As + (c >> 3) * LDT + (c & 7) * 8) = oka[i] ? ra[i] : (u32x4){0u, 0u, 0u, 0u}; }
; #pragma unroll
;     for (int i = 0; i < CB; ++i) { const int c = tid + NTHR * i; *(u32x4*)(Bs + (c >> 3) * LDT + (c & 7) * 8) = rb[i]; }
;   };
;   gload(0); sstore(0); gload(nk > 1 ? 1 : 0); __syncthreads();
; #pragma unroll 1
;   for (int kt = 0; kt < nk; ++kt) {
;     const int buf = kt & 1;
;     sstore(buf ^ 1);
;     gload(kt + 2 < nk ? kt + 2 : nk - 1);
;     __builtin_amdgcn_sched_barrier(0);
;     const bf16_t* As = smem + buf * L::STAGE + (wm * 16 * MI + l15) * LDT + quad * 8;
;     const bf16_t* Bs = smem + buf * L::STAGE + L::A_ELEMS + (wn * 16 * NJ + l15) * LDT + quad * 8;
; #pragma unroll
;     for (int ks = 0; ks < 2; ++ks) {
;       if (MI * NJ >= 32 && ks == 1) asm volatile("" ::: "memory");
;       bf16x8 b[NJ];
; #pragma unroll
;       for (int j = 0; j < NJ; ++j) b[j] = *(const bf16x8*)(Bs + j * 16 * LDT + ks * 32);
; #pragma unroll
;       for (int i = 0; i < MI; ++i) {
;         const bf16x8 a = *(const bf16x8*)(As + i * 16 * LDT + ks * 32);
; #pragma unroll
;         for (int j = 0; j < NJ; ++j) acc[i][j] = SWAP ? mfma16(b[j], a, acc[i][j]) : mfma16(a, b[j], acc[i][j]);
;       }
;     }
;     __syncthreads();
;   }
.Lgm9_main:
	ds_read_b128 v[246:249], v210 offset:4608
	s_waitcnt lgkmcnt(4)
	v_mfma_f32_16x16x32_bf16 v[124:127], v[206:209], v[190:193], v[124:127]
	s_waitcnt lgkmcnt(3)
	v_mfma_f32_16x16x32_bf16 v[120:123], v[206:209], v[194:197], v[120:123]
	s_waitcnt lgkmcnt(2)
	v_mfma_f32_16x16x32_bf16 v[116:119], v[206:209], v[198:201], v[116:119]
	s_waitcnt lgkmcnt(1)
	v_mfma_f32_16x16x32_bf16 v[112:115], v[206:209], v[202:205], v[112:115]
	s_and_b32 s5, s4, 1
	s_xor_b32 s23, s5, 1
	s_mul_i32 s23, s23, 0x12000
	v_lshlrev_b32_e32 v254, 1, v160
	v_add3_u32 v254, s23, v254, v184
	s_waitcnt vmcnt(7)
	ds_write_b128 v254, v[140:143]
	ds_read_b128 v[250:253], v210 offset:6912
	v_mfma_f32_16x16x32_bf16 v[108:111], v[242:245], v[190:193], v[108:111]
	v_mfma_f32_16x16x32_bf16 v[104:107], v[242:245], v[194:197], v[104:107]
	v_mfma_f32_16x16x32_bf16 v[100:103], v[242:245], v[198:201], v[100:103]
	v_mfma_f32_16x16x32_bf16 v[96:99], v[242:245], v[202:205], v[96:99]
	v_lshlrev_b32_e32 v140, 1, v185
	v_add3_u32 v140, s23, v140, v184
	s_waitcnt vmcnt(6)
	ds_write_b128 v140, v[136:139]
	ds_read_b128 v[206:209], v210 offset:9216
	s_waitcnt lgkmcnt(4)
	v_mfma_f32_16x16x32_bf16 v[92:95], v[246:249], v[190:193], v[92:95]
	v_mfma_f32_16x16x32_bf16 v[88:91], v[246:249], v[194:197], v[88:91]
	v_mfma_f32_16x16x32_bf16 v[84:87], v[246:249], v[198:201], v[84:87]
	v_mfma_f32_16x16x32_bf16 v[80:83], v[246:249], v[202:205], v[80:83]
	ds_read_b128 v[242:245], v210 offset:11520
	s_waitcnt lgkmcnt(3)
	v_mfma_f32_16x16x32_bf16 v[76:79], v[250:253], v[190:193], v[76:79]
	v_lshlrev_b32_e32 v136, 1, v186
	v_add3_u32 v136, s23, v136, v184
	s_waitcnt vmcnt(5)
	ds_write_b128 v136, v[132:135]
	v_mfma_f32_16x16x32_bf16 v[72:75], v[250:253], v[194:197], v[72:75]
	v_mfma_f32_16x16x32_bf16 v[68:71], v[250:253], v[198:201], v[68:71]
	v_mfma_f32_16x16x32_bf16 v[64:67], v[250:253], v[202:205], v[64:67]
	ds_read_b128 v[246:249], v210 offset:13824
	s_waitcnt lgkmcnt(3)
	v_mfma_f32_16x16x32_bf16 v[60:63], v[206:209], v[190:193], v[60:63]
	v_lshlrev_b32_e32 v132, 1, v187
	v_add3_u32 v132, s23, v132, v184
	s_min_u32 s23, s4, 13
	s_lshl_b32 s23, s23, 7
	s_add_u32 s26, s0, s23
	s_addc_u32 s27, s1, 0
	s_waitcnt vmcnt(4)
	ds_write_b128 v132, v[128:131]
	v_mfma_f32_16x16x32_bf16 v[56:59], v[206:209], v[194:197], v[56:59]
	v_mfma_f32_16x16x32_bf16 v[52:55], v[206:209], v[198:201], v[52:55]
	v_mfma_f32_16x16x32_bf16 v[48:51], v[206:209], v[202:205], v[48:51]
	ds_read_b128 v[250:253], v210 offset:16128
	s_waitcnt lgkmcnt(4)
	v_mfma_f32_16x16x32_bf16 v[44:47], v[242:245], v[190:193], v[44:47]
	s_waitcnt vmcnt(3)
	ds_write_b128 v254, v[144:147] offset:36864
	v_mfma_f32_16x16x32_bf16 v[40:43], v[242:245], v[194:197], v[40:43]
	v_mfma_f32_16x16x32_bf16 v[36:39], v[242:245], v[198:201], v[36:39]
	v_mfma_f32_16x16x32_bf16 v[32:35], v[242:245], v[202:205], v[32:35]
	ds_read_b128 v[206:209], v210 offset:64
	s_waitcnt lgkmcnt(4)
	v_mfma_f32_16x16x32_bf16 v[28:31], v[246:249], v[190:193], v[28:31]
	s_waitcnt vmcnt(2)
	ds_write_b128 v140, v[148:151] offset:36864
	v_mfma_f32_16x16x32_bf16 v[24:27], v[246:249], v[194:197], v[24:27]
	v_mfma_f32_16x16x32_bf16 v[20:23], v[246:249], v[198:201], v[20:23]
	v_mfma_f32_16x16x32_bf16 v[16:19], v[246:249], v[202:205], v[16:19]
	ds_read_b128 v[242:245], v210 offset:2368
	s_waitcnt lgkmcnt(4)
	v_mfma_f32_16x16x32_bf16 v[12:15], v[250:253], v[190:193], v[12:15]
	ds_read_b128 v[190:193], v211 offset:36928
	s_waitcnt vmcnt(1)
	ds_write_b128 v136, v[152:155] offset:36864
	v_mfma_f32_16x16x32_bf16 v[8:11], v[250:253], v[194:197], v[8:11]
	ds_read_b128 v[194:197], v211 offset:39232
	v_mfma_f32_16x16x32_bf16 v[4:7], v[250:253], v[198:201], v[4:7]
	ds_read_b128 v[198:201], v211 offset:41536
	v_mfma_f32_16x16x32_bf16 v[0:3], v[250:253], v[202:205], v[0:3]
	ds_read_b128 v[202:205], v211 offset:43840
	ds_read_b128 v[246:249], v210 offset:4672
	s_waitcnt lgkmcnt(5)
	v_mfma_f32_16x16x32_bf16 v[124:127], v[206:209], v[190:193], v[124:127]
	s_waitcnt lgkmcnt(3)
	v_mfma_f32_16x16x32_bf16 v[120:123], v[206:209], v[194:197], v[120:123]
	s_waitcnt vmcnt(0)
	ds_write_b128 v132, v[156:159] offset:36864
	s_waitcnt lgkmcnt(3)
	v_mfma_f32_16x16x32_bf16 v[116:119], v[206:209], v[198:201], v[116:119]
	s_waitcnt lgkmcnt(2)
	v_mfma_f32_16x16x32_bf16 v[112:115], v[206:209], v[202:205], v[112:115]
	v_lshl_add_u64 v[128:129], s[26:27], 0, v[162:163]
	global_load_dwordx4 v[140:143], v[128:129], off offset:256
	ds_read_b128 v[250:253], v210 offset:6976
	v_mfma_f32_16x16x32_bf16 v[108:111], v[242:245], v[190:193], v[108:111]
	v_mfma_f32_16x16x32_bf16 v[104:107], v[242:245], v[194:197], v[104:107]
	v_lshl_add_u64 v[128:129], s[26:27], 0, v[164:165]
	global_load_dwordx4 v[136:139], v[128:129], off offset:256
	v_mfma_f32_16x16x32_bf16 v[100:103], v[242:245], v[198:201], v[100:103]
	v_mfma_f32_16x16x32_bf16 v[96:99], v[242:245], v[202:205], v[96:99]
	ds_read_b128 v[206:209], v210 offset:9280
	s_waitcnt lgkmcnt(3)
	v_mfma_f32_16x16x32_bf16 v[92:95], v[246:249], v[190:193], v[92:95]
	v_lshl_add_u64 v[128:129], s[26:27], 0, v[166:167]
	global_load_dwordx4 v[132:135], v[128:129], off offset:256
	v_mfma_f32_16x16x32_bf16 v[88:91], v[246:249], v[194:197], v[88:91]
	v_mfma_f32_16x16x32_bf16 v[84:87], v[246:249], v[198:201], v[84:87]
	v_lshl_add_u64 v[128:129], s[26:27], 0, v[168:169]
	s_add_u32 s26, s2, s23
	s_addc_u32 s27, s3, 0
	v_lshl_add_u64 v[144:145], s[26:27], 0, v[162:163]
	v_lshl_add_u64 v[148:149], s[26:27], 0, v[164:165]
	v_lshl_add_u64 v[152:153], s[26:27], 0, v[166:167]
	v_lshl_add_u64 v[156:157], s[26:27], 0, v[168:169]
	global_load_dwordx4 v[128:131], v[128:129], off offset:256
	v_mfma_f32_16x16x32_bf16 v[80:83], v[246:249], v[202:205], v[80:83]
	ds_read_b128 v[242:245], v210 offset:11584
	s_waitcnt lgkmcnt(2)
	v_mfma_f32_16x16x32_bf16 v[76:79], v[250:253], v[190:193], v[76:79]
	v_mfma_f32_16x16x32_bf16 v[72:75], v[250:253], v[194:197], v[72:75]
	global_load_dwordx4 v[144:147], v[144:145], off offset:256
	v_mfma_f32_16x16x32_bf16 v[68:71], v[250:253], v[198:201], v[68:71]
	v_mfma_f32_16x16x32_bf16 v[64:67], v[250:253], v[202:205], v[64:67]
	global_load_dwordx4 v[148:151], v[148:149], off offset:256
	ds_read_b128 v[246:249], v210 offset:13888
	s_waitcnt lgkmcnt(2)
	v_mfma_f32_16x16x32_bf16 v[60:63], v[206:209], v[190:193], v[60:63]
	v_mfma_f32_16x16x32_bf16 v[56:59], v[206:209], v[194:197], v[56:59]
	v_mfma_f32_16x16x32_bf16 v[52:55], v[206:209], v[198:201], v[52:55]
	global_load_dwordx4 v[152:155], v[152:153], off offset:256
	v_mfma_f32_16x16x32_bf16 v[48:51], v[206:209], v[202:205], v[48:51]
	ds_read_b128 v[250:253], v210 offset:16192
	s_waitcnt lgkmcnt(2)
	v_mfma_f32_16x16x32_bf16 v[44:47], v[242:245], v[190:193], v[44:47]
	global_load_dwordx4 v[156:159], v[156:157], off offset:256
	v_mfma_f32_16x16x32_bf16 v[40:43], v[242:245], v[194:197], v[40:43]
	v_mfma_f32_16x16x32_bf16 v[36:39], v[242:245], v[198:201], v[36:39]
	v_mfma_f32_16x16x32_bf16 v[32:35], v[242:245], v[202:205], v[32:35]
	s_waitcnt lgkmcnt(0)
	s_barrier
; DI f32x4 mfma16(bf16x8 a, bf16x8 b, f32x4 c) { return __builtin_amdgcn_mfma_f32_16x16x32_bf16(a, b, c, 0, 0, 0); }
; template <int MI, int NJ, bool SWAP, class AP, class BP>
; DI void gemm_main(f32x4 (&acc)[MI][NJ], const AP& ap, int a_kstep, const BP& bp, int b_kstep, int nk, bf16_t* smem) {
;     ...
;   for (int kt = 0; kt < nk; ++kt) {
;     const int buf = kt & 1;
;     sstore(buf ^ 1);
;     gload(kt + 2 < nk ? kt + 2 : nk - 1);
;     __builtin_amdgcn_sched_barrier(0);
;     const bf16_t* As = smem + buf * L::STAGE + (wm * 16 * MI + l15) * LDT + quad * 8;
;     const bf16_t* Bs = smem + buf * L::STAGE + L::A_ELEMS + (wn * 16 * NJ + l15) * LDT + quad * 8;
; #pragma unroll
;     for (int ks = 0; ks < 2; ++ks) {
;       if (MI * NJ >= 32 && ks == 1) asm volatile("" ::: "memory");
;       bf16x8 b[NJ];
; #pragma unroll
;       for (int j = 0; j < NJ; ++j) b[j] = *(const bf16x8*)(Bs + j * 16 * LDT + ks * 32);
; #pragma unroll
;       for (int i = 0; i < MI; ++i) {
;         const bf16x8 a = *(const bf16x8*)(As + i * 16 * LDT + ks * 32);
; #pragma unroll
;         for (int j = 0; j < NJ; ++j) acc[i][j] = SWAP ? mfma16(b[j], a, acc[i][j]) : mfma16(a, b[j], acc[i][j]);
;       }
;     }
;     __syncthreads();
	s_add_i32 s4, s4, 1
	s_cmp_lg_u32 s4, 16
	s_cbranch_scc0 .Lgm9_exit
	s_and_b32 s98, s4, 1
	s_mul_i32 s98, s98, 0x12000
	v_add3_u32 v210, s98, v188, v189
	v_add3_u32 v211, s98, v183, v189
	ds_read_b128 v[206:209], v210
	ds_read_b128 v[242:245], v210 offset:2304
	v_mfma_f32_16x16x32_bf16 v[28:31], v[246:249], v[190:193], v[28:31]
	v_mfma_f32_16x16x32_bf16 v[12:15], v[250:253], v[190:193], v[12:15]
	ds_read_b128 v[190:193], v211 offset:36864
	v_mfma_f32_16x16x32_bf16 v[24:27], v[246:249], v[194:197], v[24:27]
	v_mfma_f32_16x16x32_bf16 v[8:11], v[250:253], v[194:197], v[8:11]
	ds_read_b128 v[194:197], v211 offset:39168
	v_mfma_f32_16x16x32_bf16 v[20:23], v[246:249], v[198:201], v[20:23]
	v_mfma_f32_16x16x32_bf16 v[4:7], v[250:253], v[198:201], v[4:7]
	ds_read_b128 v[198:201], v211 offset:41472
	v_mfma_f32_16x16x32_bf16 v[16:19], v[246:249], v[202:205], v[16:19]
	v_mfma_f32_16x16x32_bf16 v[0:3], v[250:253], v[202:205], v[0:3]
	ds_read_b128 v[202:205], v211 offset:43776
	s_branch .Lgm9_main

; DI f32x4 mfma16(bf16x8 a, bf16x8 b, f32x4 c) { return __builtin_amdgcn_mfma_f32_16x16x32_bf16(a, b, c, 0, 0, 0); }
; template <int MI, int NJ, bool SWAP, class AP, class BP>
; DI void gemm_main(f32x4 (&acc)[MI][NJ], const AP& ap, int a_kstep, const BP& bp, int b_kstep, int nk, bf16_t* smem) {
;     ...
;   auto gload = [&](int kt) {
;     const bf16_t* ab = ap.base + (size_t)kt * a_kstep; const bf16_t* bb = bp.base + (size_t)kt * b_kstep;
; #pragma unroll
;     for (int i = 0; i < CA; ++i) ra[i] = *(const u32x4*)(ab + pa[i]);
; #pragma unroll
;     for (int i = 0; i < CB; ++i) rb[i] = *(const u32x4*)(bb + pb[i]);
;   };
;   auto sstore = [&](int buf) {
;     bf16_t* As = smem + buf * L::STAGE; bf16_t* Bs = As + L::A_ELEMS;
; #pragma unroll
;     for (int i = 0; i < CA; ++i) { const int c = tid + NTHR * i; *(u32x4*)(As + (c >> 3) * LDT + (c & 7) * 8) = oka[i] ? ra[i] : (u32x4){0u, 0u, 0u, 0u}; }
; #pragma unroll
;     for (int i = 0; i < CB; ++i) { const int c = tid + NTHR * i; *(u32x4*)(Bs + (c >> 3) * LDT + (c & 7) * 8) = rb[i]; }
;   };
;   gload(0); sstore(0); gload(nk > 1 ? 1 : 0); __syncthreads();
; #pragma unroll 1
;   for (int kt = 0; kt < nk; ++kt) {
;     const int buf = kt & 1;
;     sstore(buf ^ 1);
;     gload(kt + 2 < nk ? kt + 2 : nk - 1);
;     __builtin_amdgcn_sched_barrier(0);
;     const bf16_t* As = smem + buf * L::STAGE + (wm * 16 * MI + l15) * LDT + quad * 8;
;     const bf16_t* Bs = smem + buf * L::STAGE + L::A_ELEMS + (wn * 16 * NJ + l15) * LDT + quad * 8;
; #pragma unroll
;     for (int ks = 0; ks < 2; ++ks) {
;       if (MI * NJ >= 32 && ks == 1) asm volatile("" ::: "memory");
;       bf16x8 b[NJ];
; #pragma unroll
;       for (int j = 0; j < NJ; ++j) b[j] = *(const bf16x8*)(Bs + j * 16 * LDT + ks * 32);
; #pragma unroll
;       for (int i = 0; i < MI; ++i) {
;         const bf16x8 a = *(const bf16x8*)(As + i * 16 * LDT + ks * 32);
; #pragma unroll
;         for (int j = 0; j < NJ; ++j) acc[i][j] = SWAP ? mfma16(b[j], a, acc[i][j]) : mfma16(a, b[j], acc[i][j]);
;       }
;     }
;     __syncthreads();
;   }
.Lgm10_main:
	ds_read_b128 v[246:249], v198 offset:4608
	s_waitcnt lgkmcnt(4)
	v_mfma_f32_16x16x32_bf16 v[156:159], v[178:181], v[194:197], v[156:159]
	s_waitcnt lgkmcnt(3)
	v_mfma_f32_16x16x32_bf16 v[152:155], v[182:185], v[194:197], v[152:155]
	s_waitcnt lgkmcnt(2)
	v_mfma_f32_16x16x32_bf16 v[148:151], v[186:189], v[194:197], v[148:151]
	s_waitcnt lgkmcnt(1)
	v_mfma_f32_16x16x32_bf16 v[144:147], v[190:193], v[194:197], v[144:147]
	s_and_b32 s33, s8, 1
	s_xor_b32 s37, s33, 1
	s_mul_i32 s37, s37, 0x12000
	v_add3_u32 v254, s37, v173, v171
	s_waitcnt vmcnt(7)
	ds_write_b128 v254, v[112:115]
	ds_read_b128 v[250:253], v198 offset:6912
	v_mfma_f32_16x16x32_bf16 v[108:111], v[178:181], v[242:245], v[108:111]
	v_mfma_f32_16x16x32_bf16 v[104:107], v[182:185], v[242:245], v[104:107]
	v_mfma_f32_16x16x32_bf16 v[100:103], v[186:189], v[242:245], v[100:103]
	v_mfma_f32_16x16x32_bf16 v[96:99], v[190:193], v[242:245], v[96:99]
	v_add3_u32 v112, s37, v174, v171
	v_add3_u32 v113, s37, v175, v171
	v_add3_u32 v114, s37, v176, v171
	s_min_u32 s37, s8, 3
	s_lshl_b32 s37, s37, 7
	s_add_u32 s38, s0, s37
	s_addc_u32 s39, s1, 0
	s_waitcnt vmcnt(5)
	ds_write_b128 v112, v[116:119]
	ds_read_b128 v[194:197], v198 offset:9216
	s_waitcnt lgkmcnt(4)
	v_mfma_f32_16x16x32_bf16 v[92:95], v[178:181], v[246:249], v[92:95]
	v_mfma_f32_16x16x32_bf16 v[88:91], v[182:185], v[246:249], v[88:91]
	v_mfma_f32_16x16x32_bf16 v[84:87], v[186:189], v[246:249], v[84:87]
	v_mfma_f32_16x16x32_bf16 v[80:83], v[190:193], v[246:249], v[80:83]
	ds_read_b128 v[242:245], v198 offset:11520
	s_waitcnt lgkmcnt(3)
	v_mfma_f32_16x16x32_bf16 v[76:79], v[178:181], v[250:253], v[76:79]
	s_waitcnt vmcnt(4)
	ds_write_b128 v113, v[120:123]
	v_mfma_f32_16x16x32_bf16 v[72:75], v[182:185], v[250:253], v[72:75]
	v_mfma_f32_16x16x32_bf16 v[68:71], v[186:189], v[250:253], v[68:71]
	v_mfma_f32_16x16x32_bf16 v[64:67], v[190:193], v[250:253], v[64:67]
	ds_read_b128 v[246:249], v198 offset:13824
	s_waitcnt lgkmcnt(3)
	v_mfma_f32_16x16x32_bf16 v[60:63], v[178:181], v[194:197], v[60:63]
	s_waitcnt vmcnt(3)
	ds_write_b128 v114, v[124:127]
	v_mfma_f32_16x16x32_bf16 v[56:59], v[182:185], v[194:197], v[56:59]
	v_mfma_f32_16x16x32_bf16 v[52:55], v[186:189], v[194:197], v[52:55]
	v_mfma_f32_16x16x32_bf16 v[48:51], v[190:193], v[194:197], v[48:51]
	ds_read_b128 v[250:253], v198 offset:16128
	s_waitcnt lgkmcnt(4)
	v_mfma_f32_16x16x32_bf16 v[44:47], v[178:181], v[242:245], v[44:47]
	ds_write_b128 v254, v[128:131] offset:36864
	v_mfma_f32_16x16x32_bf16 v[40:43], v[182:185], v[242:245], v[40:43]
	v_mfma_f32_16x16x32_bf16 v[36:39], v[186:189], v[242:245], v[36:39]
	v_mfma_f32_16x16x32_bf16 v[32:35], v[190:193], v[242:245], v[32:35]
	ds_read_b128 v[194:197], v198 offset:64
	s_waitcnt lgkmcnt(4)
	v_mfma_f32_16x16x32_bf16 v[28:31], v[178:181], v[246:249], v[28:31]
	s_waitcnt vmcnt(2)
	ds_write_b128 v112, v[132:135] offset:36864
	v_mfma_f32_16x16x32_bf16 v[24:27], v[182:185], v[246:249], v[24:27]
	v_mfma_f32_16x16x32_bf16 v[20:23], v[186:189], v[246:249], v[20:23]
	v_mfma_f32_16x16x32_bf16 v[16:19], v[190:193], v[246:249], v[16:19]
	ds_read_b128 v[242:245], v198 offset:2368
	s_waitcnt lgkmcnt(4)
	v_mfma_f32_16x16x32_bf16 v[12:15], v[178:181], v[250:253], v[12:15]
	ds_read_b128 v[178:181], v199 offset:36928
	s_waitcnt vmcnt(1)
	ds_write_b128 v113, v[136:139] offset:36864
	v_mfma_f32_16x16x32_bf16 v[8:11], v[182:185], v[250:253], v[8:11]
	ds_read_b128 v[182:185], v199 offset:39232
	v_mfma_f32_16x16x32_bf16 v[4:7], v[186:189], v[250:253], v[4:7]
	ds_read_b128 v[186:189], v199 offset:41536
	v_mfma_f32_16x16x32_bf16 v[0:3], v[190:193], v[250:253], v[0:3]
	ds_read_b128 v[190:193], v199 offset:43840
	ds_read_b128 v[246:249], v198 offset:4672
	s_waitcnt lgkmcnt(5)
	v_mfma_f32_16x16x32_bf16 v[156:159], v[178:181], v[194:197], v[156:159]
	s_waitcnt lgkmcnt(3)
	v_mfma_f32_16x16x32_bf16 v[152:155], v[182:185], v[194:197], v[152:155]
	s_waitcnt vmcnt(0)
	ds_write_b128 v114, v[140:143] offset:36864
	s_waitcnt lgkmcnt(3)
	v_mfma_f32_16x16x32_bf16 v[148:151], v[186:189], v[194:197], v[148:151]
	s_waitcnt lgkmcnt(2)
	v_mfma_f32_16x16x32_bf16 v[144:147], v[190:193], v[194:197], v[144:147]
	v_lshl_add_u64 v[112:113], s[38:39], 0, v[162:163]
	v_lshl_add_u64 v[116:117], s[38:39], 0, v[164:165]
	v_lshl_add_u64 v[120:121], s[38:39], 0, v[166:167]
	v_lshl_add_u64 v[124:125], s[38:39], 0, v[168:169]
	s_add_u32 s38, s2, s37
	s_addc_u32 s39, s3, 0
	v_lshl_add_u64 v[128:129], s[38:39], 0, v[162:163]
	v_lshl_add_u64 v[132:133], s[38:39], 0, v[164:165]
	v_lshl_add_u64 v[136:137], s[38:39], 0, v[166:167]
	v_lshl_add_u64 v[140:141], s[38:39], 0, v[168:169]
	global_load_dwordx4 v[112:115], v[112:113], off offset:256
	ds_read_b128 v[250:253], v198 offset:6976
	v_mfma_f32_16x16x32_bf16 v[108:111], v[178:181], v[242:245], v[108:111]
	v_mfma_f32_16x16x32_bf16 v[104:107], v[182:185], v[242:245], v[104:107]
	global_load_dwordx4 v[116:119], v[116:117], off offset:256
	v_mfma_f32_16x16x32_bf16 v[100:103], v[186:189], v[242:245], v[100:103]
	v_mfma_f32_16x16x32_bf16 v[96:99], v[190:193], v[242:245], v[96:99]
	ds_read_b128 v[194:197], v198 offset:9280
	s_waitcnt lgkmcnt(3)
	v_mfma_f32_16x16x32_bf16 v[92:95], v[178:181], v[246:249], v[92:95]
	global_load_dwordx4 v[120:123], v[120:121], off offset:256
	v_mfma_f32_16x16x32_bf16 v[88:91], v[182:185], v[246:249], v[88:91]
	v_mfma_f32_16x16x32_bf16 v[84:87], v[186:189], v[246:249], v[84:87]
	global_load_dwordx4 v[124:127], v[124:125], off offset:256
	v_mfma_f32_16x16x32_bf16 v[80:83], v[190:193], v[246:249], v[80:83]
	ds_read_b128 v[242:245], v198 offset:11584
	s_waitcnt lgkmcnt(2)
	v_mfma_f32_16x16x32_bf16 v[76:79], v[178:181], v[250:253], v[76:79]
	v_mfma_f32_16x16x32_bf16 v[72:75], v[182:185], v[250:253], v[72:75]
	global_load_dwordx4 v[128:131], v[128:129], off offset:256
	v_mfma_f32_16x16x32_bf16 v[68:71], v[186:189], v[250:253], v[68:71]
	v_mfma_f32_16x16x32_bf16 v[64:67], v[190:193], v[250:253], v[64:67]
	global_load_dwordx4 v[132:135], v[132:133], off offset:256
	ds_read_b128 v[246:249], v198 offset:13888
	s_waitcnt lgkmcnt(2)
	v_mfma_f32_16x16x32_bf16 v[60:63], v[178:181], v[194:197], v[60:63]
	v_mfma_f32_16x16x32_bf16 v[56:59], v[182:185], v[194:197], v[56:59]
	v_mfma_f32_16x16x32_bf16 v[52:55], v[186:189], v[194:197], v[52:55]
	global_load_dwordx4 v[136:139], v[136:137], off offset:256
	v_mfma_f32_16x16x32_bf16 v[48:51], v[190:193], v[194:197], v[48:51]
	ds_read_b128 v[250:253], v198 offset:16192
	s_waitcnt lgkmcnt(2)
	v_mfma_f32_16x16x32_bf16 v[44:47], v[178:181], v[242:245], v[44:47]
	global_load_dwordx4 v[140:143], v[140:141], off offset:256
	v_mfma_f32_16x16x32_bf16 v[40:43], v[182:185], v[242:245], v[40:43]
	v_mfma_f32_16x16x32_bf16 v[36:39], v[186:189], v[242:245], v[36:39]
	v_mfma_f32_16x16x32_bf16 v[32:35], v[190:193], v[242:245], v[32:35]
	s_waitcnt lgkmcnt(0)
	s_barrier
; DI f32x4 mfma16(bf16x8 a, bf16x8 b, f32x4 c) { return __builtin_amdgcn_mfma_f32_16x16x32_bf16(a, b, c, 0, 0, 0); }
; template <int MI, int NJ, bool SWAP, class AP, class BP>
; DI void gemm_main(f32x4 (&acc)[MI][NJ], const AP& ap, int a_kstep, const BP& bp, int b_kstep, int nk, bf16_t* smem) {
;     ...
;   for (int kt = 0; kt < nk; ++kt) {
;     const int buf = kt & 1;
;     sstore(buf ^ 1);
;     gload(kt + 2 < nk ? kt + 2 : nk - 1);
;     __builtin_amdgcn_sched_barrier(0);
;     const bf16_t* As = smem + buf * L::STAGE + (wm * 16 * MI + l15) * LDT + quad * 8;
;     const bf16_t* Bs = smem + buf * L::STAGE + L::A_ELEMS + (wn * 16 * NJ + l15) * LDT + quad * 8;
; #pragma unroll
;     for (int ks = 0; ks < 2; ++ks) {
;       if (MI * NJ >= 32 && ks == 1) asm volatile("" ::: "memory");
;       bf16x8 b[NJ];
; #pragma unroll
;       for (int j = 0; j < NJ; ++j) b[j] = *(const bf16x8*)(Bs + j * 16 * LDT + ks * 32);
; #pragma unroll
;       for (int i = 0; i < MI; ++i) {
;         const bf16x8 a = *(const bf16x8*)(As + i * 16 * LDT + ks * 32);
; #pragma unroll
;         for (int j = 0; j < NJ; ++j) acc[i][j] = SWAP ? mfma16(b[j], a, acc[i][j]) : mfma16(a, b[j], acc[i][j]);
;       }
;     }
;     __syncthreads();
	s_add_i32 s8, s8, 1
	s_cmp_lg_u32 s8, 6
	s_cbranch_scc0 .Lgm10_exit
	s_and_b32 s98, s8, 1
	s_mul_i32 s98, s98, 0x12000
	v_add3_u32 v198, s98, v172, v177
	v_add3_u32 v199, s98, v160, v177
	ds_read_b128 v[194:197], v198
	ds_read_b128 v[242:245], v198 offset:2304
	v_mfma_f32_16x16x32_bf16 v[28:31], v[178:181], v[246:249], v[28:31]
	v_mfma_f32_16x16x32_bf16 v[12:15], v[178:181], v[250:253], v[12:15]
	ds_read_b128 v[178:181], v199 offset:36864
	v_mfma_f32_16x16x32_bf16 v[24:27], v[182:185], v[246:249], v[24:27]
	v_mfma_f32_16x16x32_bf16 v[8:11], v[182:185], v[250:253], v[8:11]
	ds_read_b128 v[182:185], v199 offset:39168
	v_mfma_f32_16x16x32_bf16 v[20:23], v[186:189], v[246:249], v[20:23]
	v_mfma_f32_16x16x32_bf16 v[4:7], v[186:189], v[250:253], v[4:7]
	ds_read_b128 v[186:189], v199 offset:41472
	v_mfma_f32_16x16x32_bf16 v[16:19], v[190:193], v[246:249], v[16:19]
	v_mfma_f32_16x16x32_bf16 v[0:3], v[190:193], v[250:253], v[0:3]
	ds_read_b128 v[190:193], v199 offset:43776
	s_branch .Lgm10_main

; DI f32x4 mfma16(bf16x8 a, bf16x8 b, f32x4 c) { return __builtin_amdgcn_mfma_f32_16x16x32_bf16(a, b, c, 0, 0, 0); }
; template <int MI, int NJ, bool SWAP, class AP, class BP>
; DI void gemm_main(f32x4 (&acc)[MI][NJ], const AP& ap, int a_kstep, const BP& bp, int b_kstep, int nk, bf16_t* smem) {
;     ...
;   auto gload = [&](int kt) {
;     const bf16_t* ab = ap.base + (size_t)kt * a_kstep; const bf16_t* bb = bp.base + (size_t)kt * b_kstep;
; #pragma unroll
;     for (int i = 0; i < CA; ++i) ra[i] = *(const u32x4*)(ab + pa[i]);
; #pragma unroll
;     for (int i = 0; i < CB; ++i) rb[i] = *(const u32x4*)(bb + pb[i]);
;   };
;   auto sstore = [&](int buf) {
;     bf16_t* As = smem + buf * L::STAGE; bf16_t* Bs = As + L::A_ELEMS;
; #pragma unroll
;     for (int i = 0; i < CA; ++i) { const int c = tid + NTHR * i; *(u32x4*)(As + (c >> 3) * LDT + (c & 7) * 8) = oka[i] ? ra[i] : (u32x4){0u, 0u, 0u, 0u}; }
; #pragma unroll
;     for (int i = 0; i < CB; ++i) { const int c = tid + NTHR * i; *(u32x4*)(Bs + (c >> 3) * LDT + (c & 7) * 8) = rb[i]; }
;   };
;   gload(0); sstore(0); gload(nk > 1 ? 1 : 0); __syncthreads();
; #pragma unroll 1
;   for (int kt = 0; kt < nk; ++kt) {
;     const int buf = kt & 1;
;     sstore(buf ^ 1);
;     gload(kt + 2 < nk ? kt + 2 : nk - 1);
;     __builtin_amdgcn_sched_barrier(0);
;     const bf16_t* As = smem + buf * L::STAGE + (wm * 16 * MI + l15) * LDT + quad * 8;
;     const bf16_t* Bs = smem + buf * L::STAGE + L::A_ELEMS + (wn * 16 * NJ + l15) * LDT + quad * 8;
; #pragma unroll
;     for (int ks = 0; ks < 2; ++ks) {
;       if (MI * NJ >= 32 && ks == 1) asm volatile("" ::: "memory");
;       bf16x8 b[NJ];
; #pragma unroll
;       for (int j = 0; j < NJ; ++j) b[j] = *(const bf16x8*)(Bs + j * 16 * LDT + ks * 32);
; #pragma unroll
;       for (int i = 0; i < MI; ++i) {
;         const bf16x8 a = *(const bf16x8*)(As + i * 16 * LDT + ks * 32);
; #pragma unroll
;         for (int j = 0; j < NJ; ++j) acc[i][j] = SWAP ? mfma16(b[j], a, acc[i][j]) : mfma16(a, b[j], acc[i][j]);
;       }
;     }
;     __syncthreads();
;   }
.Lgm11_main:
	ds_read_b128 v[246:249], v198 offset:4608
	s_waitcnt lgkmcnt(4)
	v_mfma_f32_16x16x32_bf16 v[156:159], v[178:181], v[194:197], v[156:159]
	s_waitcnt lgkmcnt(3)
	v_mfma_f32_16x16x32_bf16 v[152:155], v[182:185], v[194:197], v[152:155]
	s_waitcnt lgkmcnt(2)
	v_mfma_f32_16x16x32_bf16 v[148:151], v[186:189], v[194:197], v[148:151]
	s_waitcnt lgkmcnt(1)
	v_mfma_f32_16x16x32_bf16 v[144:147], v[190:193], v[194:197], v[144:147]
	s_and_b32 s37, s33, 1
	s_xor_b32 s38, s37, 1
	s_mul_i32 s38, s38, 0x12000
	v_lshlrev_b32_e32 v254, 1, v160
	v_add3_u32 v254, s38, v254, v172
	s_waitcnt vmcnt(7)
	ds_write_b128 v254, v[124:127]
	ds_read_b128 v[250:253], v198 offset:6912
	v_mfma_f32_16x16x32_bf16 v[108:111], v[178:181], v[242:245], v[108:111]
	v_mfma_f32_16x16x32_bf16 v[104:107], v[182:185], v[242:245], v[104:107]
	v_mfma_f32_16x16x32_bf16 v[100:103], v[186:189], v[242:245], v[100:103]
	v_mfma_f32_16x16x32_bf16 v[96:99], v[190:193], v[242:245], v[96:99]
	v_lshlrev_b32_e32 v124, 1, v173
	v_add3_u32 v124, s38, v124, v172
	s_waitcnt vmcnt(6)
	ds_write_b128 v124, v[120:123]
	ds_read_b128 v[194:197], v198 offset:9216
	s_waitcnt lgkmcnt(4)
	v_mfma_f32_16x16x32_bf16 v[92:95], v[178:181], v[246:249], v[92:95]
	v_mfma_f32_16x16x32_bf16 v[88:91], v[182:185], v[246:249], v[88:91]
	v_mfma_f32_16x16x32_bf16 v[84:87], v[186:189], v[246:249], v[84:87]
	v_mfma_f32_16x16x32_bf16 v[80:83], v[190:193], v[246:249], v[80:83]
	ds_read_b128 v[242:245], v198 offset:11520
	s_waitcnt lgkmcnt(3)
	v_mfma_f32_16x16x32_bf16 v[76:79], v[178:181], v[250:253], v[76:79]
	v_lshlrev_b32_e32 v120, 1, v174
	v_add3_u32 v120, s38, v120, v172
	s_cmp_eq_u32 s33, 0
	s_waitcnt vmcnt(5)
	ds_write_b128 v120, v[116:119]
	v_mfma_f32_16x16x32_bf16 v[72:75], v[182:185], v[250:253], v[72:75]
	v_mfma_f32_16x16x32_bf16 v[68:71], v[186:189], v[250:253], v[68:71]
	v_mfma_f32_16x16x32_bf16 v[64:67], v[190:193], v[250:253], v[64:67]
	ds_read_b128 v[246:249], v198 offset:13824
	s_waitcnt lgkmcnt(3)
	v_mfma_f32_16x16x32_bf16 v[60:63], v[178:181], v[194:197], v[60:63]
	v_lshlrev_b32_e32 v116, 1, v175
	s_cselect_b32 s40, s31, 0x180
	v_add3_u32 v116, s38, v116, v172
	s_add_u32 s38, s0, s40
	s_addc_u32 s39, s1, 0
	s_waitcnt vmcnt(4)
	ds_write_b128 v116, v[112:115]
	v_mfma_f32_16x16x32_bf16 v[56:59], v[182:185], v[194:197], v[56:59]
	v_mfma_f32_16x16x32_bf16 v[52:55], v[186:189], v[194:197], v[52:55]
	v_mfma_f32_16x16x32_bf16 v[48:51], v[190:193], v[194:197], v[48:51]
	ds_read_b128 v[250:253], v198 offset:16128
	s_waitcnt lgkmcnt(4)
	v_mfma_f32_16x16x32_bf16 v[44:47], v[178:181], v[242:245], v[44:47]
	s_waitcnt vmcnt(3)
	ds_write_b128 v254, v[128:131] offset:36864
	v_mfma_f32_16x16x32_bf16 v[40:43], v[182:185], v[242:245], v[40:43]
	v_mfma_f32_16x16x32_bf16 v[36:39], v[186:189], v[242:245], v[36:39]
	v_mfma_f32_16x16x32_bf16 v[32:35], v[190:193], v[242:245], v[32:35]
	ds_read_b128 v[194:197], v198 offset:64
	s_waitcnt lgkmcnt(4)
	v_mfma_f32_16x16x32_bf16 v[28:31], v[178:181], v[246:249], v[28:31]
	s_waitcnt vmcnt(2)
	ds_write_b128 v124, v[132:135] offset:36864
	v_mfma_f32_16x16x32_bf16 v[24:27], v[182:185], v[246:249], v[24:27]
	v_mfma_f32_16x16x32_bf16 v[20:23], v[186:189], v[246:249], v[20:23]
	v_mfma_f32_16x16x32_bf16 v[16:19], v[190:193], v[246:249], v[16:19]
	ds_read_b128 v[242:245], v198 offset:2368
	s_waitcnt lgkmcnt(4)
	v_mfma_f32_16x16x32_bf16 v[12:15], v[178:181], v[250:253], v[12:15]
	ds_read_b128 v[178:181], v199 offset:36928
	s_waitcnt vmcnt(1)
	ds_write_b128 v120, v[136:139] offset:36864
	v_mfma_f32_16x16x32_bf16 v[8:11], v[182:185], v[250:253], v[8:11]
	ds_read_b128 v[182:185], v199 offset:39232
	v_mfma_f32_16x16x32_bf16 v[4:7], v[186:189], v[250:253], v[4:7]
	ds_read_b128 v[186:189], v199 offset:41536
	v_mfma_f32_16x16x32_bf16 v[0:3], v[190:193], v[250:253], v[0:3]
	ds_read_b128 v[190:193], v199 offset:43840
	ds_read_b128 v[246:249], v198 offset:4672
	s_waitcnt lgkmcnt(5)
	v_mfma_f32_16x16x32_bf16 v[156:159], v[178:181], v[194:197], v[156:159]
	s_waitcnt lgkmcnt(3)
	v_mfma_f32_16x16x32_bf16 v[152:155], v[182:185], v[194:197], v[152:155]
	s_waitcnt vmcnt(0)
	ds_write_b128 v116, v[140:143] offset:36864
	s_waitcnt lgkmcnt(3)
	v_mfma_f32_16x16x32_bf16 v[148:151], v[186:189], v[194:197], v[148:151]
	s_waitcnt lgkmcnt(2)
	v_mfma_f32_16x16x32_bf16 v[144:147], v[190:193], v[194:197], v[144:147]
	v_lshl_add_u64 v[112:113], s[38:39], 0, v[162:163]
	global_load_dwordx4 v[124:127], v[112:113], off
	ds_read_b128 v[250:253], v198 offset:6976
	v_mfma_f32_16x16x32_bf16 v[108:111], v[178:181], v[242:245], v[108:111]
	v_mfma_f32_16x16x32_bf16 v[104:107], v[182:185], v[242:245], v[104:107]
	v_lshl_add_u64 v[112:113], s[38:39], 0, v[164:165]
	global_load_dwordx4 v[120:123], v[112:113], off
	v_mfma_f32_16x16x32_bf16 v[100:103], v[186:189], v[242:245], v[100:103]
	v_mfma_f32_16x16x32_bf16 v[96:99], v[190:193], v[242:245], v[96:99]
	ds_read_b128 v[194:197], v198 offset:9280
	s_waitcnt lgkmcnt(3)
	v_mfma_f32_16x16x32_bf16 v[92:95], v[178:181], v[246:249], v[92:95]
	v_lshl_add_u64 v[112:113], s[38:39], 0, v[166:167]
	global_load_dwordx4 v[116:119], v[112:113], off
	v_mfma_f32_16x16x32_bf16 v[88:91], v[182:185], v[246:249], v[88:91]
	v_mfma_f32_16x16x32_bf16 v[84:87], v[186:189], v[246:249], v[84:87]
	v_lshl_add_u64 v[112:113], s[38:39], 0, v[168:169]
	s_add_u32 s38, s2, s40
	s_addc_u32 s39, s3, 0
	v_lshl_add_u64 v[128:129], s[38:39], 0, v[162:163]
	v_lshl_add_u64 v[132:133], s[38:39], 0, v[164:165]
	v_lshl_add_u64 v[136:137], s[38:39], 0, v[166:167]
	v_lshl_add_u64 v[140:141], s[38:39], 0, v[168:169]
	global_load_dwordx4 v[112:115], v[112:113], off
	v_mfma_f32_16x16x32_bf16 v[80:83], v[190:193], v[246:249], v[80:83]
	ds_read_b128 v[242:245], v198 offset:11584
	s_waitcnt lgkmcnt(2)
	v_mfma_f32_16x16x32_bf16 v[76:79], v[178:181], v[250:253], v[76:79]
	v_mfma_f32_16x16x32_bf16 v[72:75], v[182:185], v[250:253], v[72:75]
	global_load_dwordx4 v[128:131], v[128:129], off
	v_mfma_f32_16x16x32_bf16 v[68:71], v[186:189], v[250:253], v[68:71]
	v_mfma_f32_16x16x32_bf16 v[64:67], v[190:193], v[250:253], v[64:67]
	global_load_dwordx4 v[132:135], v[132:133], off
	ds_read_b128 v[246:249], v198 offset:13888
	s_waitcnt lgkmcnt(2)
	v_mfma_f32_16x16x32_bf16 v[60:63], v[178:181], v[194:197], v[60:63]
	v_mfma_f32_16x16x32_bf16 v[56:59], v[182:185], v[194:197], v[56:59]
	v_mfma_f32_16x16x32_bf16 v[52:55], v[186:189], v[194:197], v[52:55]
	global_load_dwordx4 v[136:139], v[136:137], off
	v_mfma_f32_16x16x32_bf16 v[48:51], v[190:193], v[194:197], v[48:51]
	ds_read_b128 v[250:253], v198 offset:16192
	s_waitcnt lgkmcnt(2)
	v_mfma_f32_16x16x32_bf16 v[44:47], v[178:181], v[242:245], v[44:47]
	global_load_dwordx4 v[140:143], v[140:141], off
	v_mfma_f32_16x16x32_bf16 v[40:43], v[182:185], v[242:245], v[40:43]
	v_mfma_f32_16x16x32_bf16 v[36:39], v[186:189], v[242:245], v[36:39]
	v_mfma_f32_16x16x32_bf16 v[32:35], v[190:193], v[242:245], v[32:35]
	s_waitcnt lgkmcnt(0)
	s_barrier
; DI f32x4 mfma16(bf16x8 a, bf16x8 b, f32x4 c) { return __builtin_amdgcn_mfma_f32_16x16x32_bf16(a, b, c, 0, 0, 0); }
; template <int MI, int NJ, bool SWAP, class AP, class BP>
; DI void gemm_main(f32x4 (&acc)[MI][NJ], const AP& ap, int a_kstep, const BP& bp, int b_kstep, int nk, bf16_t* smem) {
;     ...
;   for (int kt = 0; kt < nk; ++kt) {
;     const int buf = kt & 1;
;     sstore(buf ^ 1);
;     gload(kt + 2 < nk ? kt + 2 : nk - 1);
;     __builtin_amdgcn_sched_barrier(0);
;     const bf16_t* As = smem + buf * L::STAGE + (wm * 16 * MI + l15) * LDT + quad * 8;
;     const bf16_t* Bs = smem + buf * L::STAGE + L::A_ELEMS + (wn * 16 * NJ + l15) * LDT + quad * 8;
; #pragma unroll
;     for (int ks = 0; ks < 2; ++ks) {
;       if (MI * NJ >= 32 && ks == 1) asm volatile("" ::: "memory");
;       bf16x8 b[NJ];
; #pragma unroll
;       for (int j = 0; j < NJ; ++j) b[j] = *(const bf16x8*)(Bs + j * 16 * LDT + ks * 32);
; #pragma unroll
;       for (int i = 0; i < MI; ++i) {
;         const bf16x8 a = *(const bf16x8*)(As + i * 16 * LDT + ks * 32);
; #pragma unroll
;         for (int j = 0; j < NJ; ++j) acc[i][j] = SWAP ? mfma16(b[j], a, acc[i][j]) : mfma16(a, b[j], acc[i][j]);
;       }
;     }
;     __syncthreads();
	s_add_i32 s33, s33, 1
	s_cmp_lg_u32 s33, 4
	s_cbranch_scc0 .Lgm11_exit
	s_and_b32 s98, s33, 1
	s_mul_i32 s98, s98, 0x12000
	v_add3_u32 v198, s98, v176, v177
	v_add3_u32 v199, s98, v171, v177
	ds_read_b128 v[194:197], v198
	ds_read_b128 v[242:245], v198 offset:2304
	v_mfma_f32_16x16x32_bf16 v[28:31], v[178:181], v[246:249], v[28:31]
	v_mfma_f32_16x16x32_bf16 v[12:15], v[178:181], v[250:253], v[12:15]
	ds_read_b128 v[178:181], v199 offset:36864
	v_mfma_f32_16x16x32_bf16 v[24:27], v[182:185], v[246:249], v[24:27]
	v_mfma_f32_16x16x32_bf16 v[8:11], v[182:185], v[250:253], v[8:11]
	ds_read_b128 v[182:185], v199 offset:39168
	v_mfma_f32_16x16x32_bf16 v[20:23], v[186:189], v[246:249], v[20:23]
	v_mfma_f32_16x16x32_bf16 v[4:7], v[186:189], v[250:253], v[4:7]
	ds_read_b128 v[186:189], v199 offset:41472
	v_mfma_f32_16x16x32_bf16 v[16:19], v[190:193], v[246:249], v[16:19]
	v_mfma_f32_16x16x32_bf16 v[0:3], v[190:193], v[250:253], v[0:3]
	ds_read_b128 v[190:193], v199 offset:43776
	s_branch .Lgm11_main

; DI f32x4 mfma16(bf16x8 a, bf16x8 b, f32x4 c) { return __builtin_amdgcn_mfma_f32_16x16x32_bf16(a, b, c, 0, 0, 0); }
; template <int MI, int NJ, bool SWAP, class AP, class BP>
; DI void gemm_main(f32x4 (&acc)[MI][NJ], const AP& ap, int a_kstep, const BP& bp, int b_kstep, int nk, bf16_t* smem) {
;     ...
;   auto gload = [&](int kt) {
;     const bf16_t* ab = ap.base + (size_t)kt * a_kstep; const bf16_t* bb = bp.base + (size_t)kt * b_kstep;
; #pragma unroll
;     for (int i = 0; i < CA; ++i) ra[i] = *(const u32x4*)(ab + pa[i]);
; #pragma unroll
;     for (int i = 0; i < CB; ++i) rb[i] = *(const u32x4*)(bb + pb[i]);
;   };
;   auto sstore = [&](int buf) {
;     bf16_t* As = smem + buf * L::STAGE; bf16_t* Bs = As + L::A_ELEMS;
; #pragma unroll
;     for (int i = 0; i < CA; ++i) { const int c = tid + NTHR * i; *(u32x4*)(As + (c >> 3) * LDT + (c & 7) * 8) = oka[i] ? ra[i] : (u32x4){0u, 0u, 0u, 0u}; }
; #pragma unroll
;     for (int i = 0; i < CB; ++i) { const int c = tid + NTHR * i; *(u32x4*)(Bs + (c >> 3) * LDT + (c & 7) * 8) = rb[i]; }
;   };
;   gload(0); sstore(0); gload(nk > 1 ? 1 : 0); __syncthreads();
; #pragma unroll 1
;   for (int kt = 0; kt < nk; ++kt) {
;     const int buf = kt & 1;
;     sstore(buf ^ 1);
;     gload(kt + 2 < nk ? kt + 2 : nk - 1);
;     __builtin_amdgcn_sched_barrier(0);
;     const bf16_t* As = smem + buf * L::STAGE + (wm * 16 * MI + l15) * LDT + quad * 8;
;     const bf16_t* Bs = smem + buf * L::STAGE + L::A_ELEMS + (wn * 16 * NJ + l15) * LDT + quad * 8;
; #pragma unroll
;     for (int ks = 0; ks < 2; ++ks) {
;       if (MI * NJ >= 32 && ks == 1) asm volatile("" ::: "memory");
;       bf16x8 b[NJ];
; #pragma unroll
;       for (int j = 0; j < NJ; ++j) b[j] = *(const bf16x8*)(Bs + j * 16 * LDT + ks * 32);
; #pragma unroll
;       for (int i = 0; i < MI; ++i) {
;         const bf16x8 a = *(const bf16x8*)(As + i * 16 * LDT + ks * 32);
; #pragma unroll
;         for (int j = 0; j < NJ; ++j) acc[i][j] = SWAP ? mfma16(b[j], a, acc[i][j]) : mfma16(a, b[j], acc[i][j]);
;       }
;     }
;     __syncthreads();
;   }
.Lgm12_main:
	ds_read_b128 v[246:249], v198 offset:4608
	s_waitcnt lgkmcnt(4)
	v_mfma_f32_16x16x32_bf16 v[124:127], v[194:197], v[178:181], v[124:127]
	s_waitcnt lgkmcnt(3)
	v_mfma_f32_16x16x32_bf16 v[120:123], v[194:197], v[182:185], v[120:123]
	s_waitcnt lgkmcnt(2)
	v_mfma_f32_16x16x32_bf16 v[116:119], v[194:197], v[186:189], v[116:119]
	s_waitcnt lgkmcnt(1)
	v_mfma_f32_16x16x32_bf16 v[112:115], v[194:197], v[190:193], v[112:115]
	s_and_b32 s17, s8, 1
	s_xor_b32 s33, s17, 1
	s_mul_i32 s33, s33, 0x12000
	v_lshlrev_b32_e32 v254, 1, v160
	v_add3_u32 v254, s33, v254, v172
	s_waitcnt vmcnt(7)
	ds_write_b128 v254, v[140:143]
	ds_read_b128 v[250:253], v198 offset:6912
	v_mfma_f32_16x16x32_bf16 v[108:111], v[242:245], v[178:181], v[108:111]
	v_mfma_f32_16x16x32_bf16 v[104:107], v[242:245], v[182:185], v[104:107]
	v_mfma_f32_16x16x32_bf16 v[100:103], v[242:245], v[186:189], v[100:103]
	v_mfma_f32_16x16x32_bf16 v[96:99], v[242:245], v[190:193], v[96:99]
	v_lshlrev_b32_e32 v140, 1, v173
	v_add3_u32 v140, s33, v140, v172
	s_waitcnt vmcnt(6)
	ds_write_b128 v140, v[136:139]
	ds_read_b128 v[194:197], v198 offset:9216
	s_waitcnt lgkmcnt(4)
	v_mfma_f32_16x16x32_bf16 v[92:95], v[246:249], v[178:181], v[92:95]
	v_mfma_f32_16x16x32_bf16 v[88:91], v[246:249], v[182:185], v[88:91]
	v_mfma_f32_16x16x32_bf16 v[84:87], v[246:249], v[186:189], v[84:87]
	v_mfma_f32_16x16x32_bf16 v[80:83], v[246:249], v[190:193], v[80:83]
	ds_read_b128 v[242:245], v198 offset:11520
	s_waitcnt lgkmcnt(3)
	v_mfma_f32_16x16x32_bf16 v[76:79], v[250:253], v[178:181], v[76:79]
	v_lshlrev_b32_e32 v136, 1, v174
	v_add3_u32 v136, s33, v136, v172
	s_waitcnt vmcnt(5)
	ds_write_b128 v136, v[132:135]
	v_mfma_f32_16x16x32_bf16 v[72:75], v[250:253], v[182:185], v[72:75]
	v_mfma_f32_16x16x32_bf16 v[68:71], v[250:253], v[186:189], v[68:71]
	v_mfma_f32_16x16x32_bf16 v[64:67], v[250:253], v[190:193], v[64:67]
	ds_read_b128 v[246:249], v198 offset:13824
	s_waitcnt lgkmcnt(3)
	v_mfma_f32_16x16x32_bf16 v[60:63], v[194:197], v[178:181], v[60:63]
	v_lshlrev_b32_e32 v132, 1, v175
	s_cmp_eq_u32 s8, 0
	v_add3_u32 v132, s33, v132, v172
	s_cselect_b32 s33, s31, 0x180
	s_add_u32 s38, s0, s33
	s_addc_u32 s39, s1, 0
	s_waitcnt vmcnt(4)
	ds_write_b128 v132, v[128:131]
	v_mfma_f32_16x16x32_bf16 v[56:59], v[194:197], v[182:185], v[56:59]
	v_mfma_f32_16x16x32_bf16 v[52:55], v[194:197], v[186:189], v[52:55]
	v_mfma_f32_16x16x32_bf16 v[48:51], v[194:197], v[190:193], v[48:51]
	ds_read_b128 v[250:253], v198 offset:16128
	s_waitcnt lgkmcnt(4)
	v_mfma_f32_16x16x32_bf16 v[44:47], v[242:245], v[178:181], v[44:47]
	s_waitcnt vmcnt(3)
	ds_write_b128 v254, v[144:147] offset:36864
	v_mfma_f32_16x16x32_bf16 v[40:43], v[242:245], v[182:185], v[40:43]
	v_mfma_f32_16x16x32_bf16 v[36:39], v[242:245], v[186:189], v[36:39]
	v_mfma_f32_16x16x32_bf16 v[32:35], v[242:245], v[190:193], v[32:35]
	ds_read_b128 v[194:197], v198 offset:64
	s_waitcnt lgkmcnt(4)
	v_mfma_f32_16x16x32_bf16 v[28:31], v[246:249], v[178:181], v[28:31]
	s_waitcnt vmcnt(2)
	ds_write_b128 v140, v[148:151] offset:36864
	v_mfma_f32_16x16x32_bf16 v[24:27], v[246:249], v[182:185], v[24:27]
	v_mfma_f32_16x16x32_bf16 v[20:23], v[246:249], v[186:189], v[20:23]
	v_mfma_f32_16x16x32_bf16 v[16:19], v[246:249], v[190:193], v[16:19]
	ds_read_b128 v[242:245], v198 offset:2368
	s_waitcnt lgkmcnt(4)
	v_mfma_f32_16x16x32_bf16 v[12:15], v[250:253], v[178:181], v[12:15]
	ds_read_b128 v[178:181], v199 offset:36928
	s_waitcnt vmcnt(1)
	ds_write_b128 v136, v[152:155] offset:36864
	v_mfma_f32_16x16x32_bf16 v[8:11], v[250:253], v[182:185], v[8:11]
	ds_read_b128 v[182:185], v199 offset:39232
	v_mfma_f32_16x16x32_bf16 v[4:7], v[250:253], v[186:189], v[4:7]
	ds_read_b128 v[186:189], v199 offset:41536
	v_mfma_f32_16x16x32_bf16 v[0:3], v[250:253], v[190:193], v[0:3]
	ds_read_b128 v[190:193], v199 offset:43840
	ds_read_b128 v[246:249], v198 offset:4672
	s_waitcnt lgkmcnt(5)
	v_mfma_f32_16x16x32_bf16 v[124:127], v[194:197], v[178:181], v[124:127]
	s_waitcnt lgkmcnt(3)
	v_mfma_f32_16x16x32_bf16 v[120:123], v[194:197], v[182:185], v[120:123]
	s_waitcnt vmcnt(0)
	ds_write_b128 v132, v[156:159] offset:36864
	s_waitcnt lgkmcnt(3)
	v_mfma_f32_16x16x32_bf16 v[116:119], v[194:197], v[186:189], v[116:119]
	s_waitcnt lgkmcnt(2)
	v_mfma_f32_16x16x32_bf16 v[112:115], v[194:197], v[190:193], v[112:115]
	v_lshl_add_u64 v[128:129], s[38:39], 0, v[162:163]
	global_load_dwordx4 v[140:143], v[128:129], off
	ds_read_b128 v[250:253], v198 offset:6976
	v_mfma_f32_16x16x32_bf16 v[108:111], v[242:245], v[178:181], v[108:111]
	v_mfma_f32_16x16x32_bf16 v[104:107], v[242:245], v[182:185], v[104:107]
	v_lshl_add_u64 v[128:129], s[38:39], 0, v[164:165]
	global_load_dwordx4 v[136:139], v[128:129], off
	v_mfma_f32_16x16x32_bf16 v[100:103], v[242:245], v[186:189], v[100:103]
	v_mfma_f32_16x16x32_bf16 v[96:99], v[242:245], v[190:193], v[96:99]
	ds_read_b128 v[194:197], v198 offset:9280
	s_waitcnt lgkmcnt(3)
	v_mfma_f32_16x16x32_bf16 v[92:95], v[246:249], v[178:181], v[92:95]
	v_lshl_add_u64 v[128:129], s[38:39], 0, v[166:167]
	global_load_dwordx4 v[132:135], v[128:129], off
	v_mfma_f32_16x16x32_bf16 v[88:91], v[246:249], v[182:185], v[88:91]
	v_mfma_f32_16x16x32_bf16 v[84:87], v[246:249], v[186:189], v[84:87]
	v_lshl_add_u64 v[128:129], s[38:39], 0, v[168:169]
	s_add_u32 s38, s2, s33
	s_addc_u32 s39, s3, 0
	v_lshl_add_u64 v[144:145], s[38:39], 0, v[162:163]
	v_lshl_add_u64 v[148:149], s[38:39], 0, v[164:165]
	v_lshl_add_u64 v[152:153], s[38:39], 0, v[166:167]
	v_lshl_add_u64 v[156:157], s[38:39], 0, v[168:169]
	global_load_dwordx4 v[128:131], v[128:129], off
	v_mfma_f32_16x16x32_bf16 v[80:83], v[246:249], v[190:193], v[80:83]
	ds_read_b128 v[242:245], v198 offset:11584
	s_waitcnt lgkmcnt(2)
	v_mfma_f32_16x16x32_bf16 v[76:79], v[250:253], v[178:181], v[76:79]
	v_mfma_f32_16x16x32_bf16 v[72:75], v[250:253], v[182:185], v[72:75]
	global_load_dwordx4 v[144:147], v[144:145], off
	v_mfma_f32_16x16x32_bf16 v[68:71], v[250:253], v[186:189], v[68:71]
	v_mfma_f32_16x16x32_bf16 v[64:67], v[250:253], v[190:193], v[64:67]
	global_load_dwordx4 v[148:151], v[148:149], off
	ds_read_b128 v[246:249], v198 offset:13888
	s_waitcnt lgkmcnt(2)
	v_mfma_f32_16x16x32_bf16 v[60:63], v[194:197], v[178:181], v[60:63]
	v_mfma_f32_16x16x32_bf16 v[56:59], v[194:197], v[182:185], v[56:59]
	v_mfma_f32_16x16x32_bf16 v[52:55], v[194:197], v[186:189], v[52:55]
	global_load_dwordx4 v[152:155], v[152:153], off
	v_mfma_f32_16x16x32_bf16 v[48:51], v[194:197], v[190:193], v[48:51]
	ds_read_b128 v[250:253], v198 offset:16192
	s_waitcnt lgkmcnt(2)
	v_mfma_f32_16x16x32_bf16 v[44:47], v[242:245], v[178:181], v[44:47]
	global_load_dwordx4 v[156:159], v[156:157], off
	v_mfma_f32_16x16x32_bf16 v[40:43], v[242:245], v[182:185], v[40:43]
	v_mfma_f32_16x16x32_bf16 v[36:39], v[242:245], v[186:189], v[36:39]
	v_mfma_f32_16x16x32_bf16 v[32:35], v[242:245], v[190:193], v[32:35]
	s_waitcnt lgkmcnt(0)
	s_barrier
; DI f32x4 mfma16(bf16x8 a, bf16x8 b, f32x4 c) { return __builtin_amdgcn_mfma_f32_16x16x32_bf16(a, b, c, 0, 0, 0); }
; template <int MI, int NJ, bool SWAP, class AP, class BP>
; DI void gemm_main(f32x4 (&acc)[MI][NJ], const AP& ap, int a_kstep, const BP& bp, int b_kstep, int nk, bf16_t* smem) {
;     ...
;   for (int kt = 0; kt < nk; ++kt) {
;     const int buf = kt & 1;
;     sstore(buf ^ 1);
;     gload(kt + 2 < nk ? kt + 2 : nk - 1);
;     __builtin_amdgcn_sched_barrier(0);
;     const bf16_t* As = smem + buf * L::STAGE + (wm * 16 * MI + l15) * LDT + quad * 8;
;     const bf16_t* Bs = smem + buf * L::STAGE + L::A_ELEMS + (wn * 16 * NJ + l15) * LDT + quad * 8;
; #pragma unroll
;     for (int ks = 0; ks < 2; ++ks) {
;       if (MI * NJ >= 32 && ks == 1) asm volatile("" ::: "memory");
;       bf16x8 b[NJ];
; #pragma unroll
;       for (int j = 0; j < NJ; ++j) b[j] = *(const bf16x8*)(Bs + j * 16 * LDT + ks * 32);
; #pragma unroll
;       for (int i = 0; i < MI; ++i) {
;         const bf16x8 a = *(const bf16x8*)(As + i * 16 * LDT + ks * 32);
; #pragma unroll
;         for (int j = 0; j < NJ; ++j) acc[i][j] = SWAP ? mfma16(b[j], a, acc[i][j]) : mfma16(a, b[j], acc[i][j]);
;       }
;     }
;     __syncthreads();
	s_add_i32 s8, s8, 1
	s_cmp_lg_u32 s8, 4
	s_cbranch_scc0 .Lgm12_exit
	s_and_b32 s98, s8, 1
	s_mul_i32 s98, s98, 0x12000
	v_add3_u32 v198, s98, v176, v177
	v_add3_u32 v199, s98, v171, v177
	ds_read_b128 v[194:197], v198
	ds_read_b128 v[242:245], v198 offset:2304
	v_mfma_f32_16x16x32_bf16 v[28:31], v[246:249], v[178:181], v[28:31]
	v_mfma_f32_16x16x32_bf16 v[12:15], v[250:253], v[178:181], v[12:15]
	ds_read_b128 v[178:181], v199 offset:36864
	v_mfma_f32_16x16x32_bf16 v[24:27], v[246:249], v[182:185], v[24:27]
	v_mfma_f32_16x16x32_bf16 v[8:11], v[250:253], v[182:185], v[8:11]
	ds_read_b128 v[182:185], v199 offset:39168
	v_mfma_f32_16x16x32_bf16 v[20:23], v[246:249], v[186:189], v[20:23]
	v_mfma_f32_16x16x32_bf16 v[4:7], v[250:253], v[186:189], v[4:7]
	ds_read_b128 v[186:189], v199 offset:41472
	v_mfma_f32_16x16x32_bf16 v[16:19], v[246:249], v[190:193], v[16:19]
	v_mfma_f32_16x16x32_bf16 v[0:3], v[250:253], v[190:193], v[0:3]
	ds_read_b128 v[190:193], v199 offset:43776
	s_branch .Lgm12_main

; DI f32x4 mfma16(bf16x8 a, bf16x8 b, f32x4 c) { return __builtin_amdgcn_mfma_f32_16x16x32_bf16(a, b, c, 0, 0, 0); }
; template <int MI, int NJ, bool SWAP, class AP, class BP>
; DI void gemm_main(f32x4 (&acc)[MI][NJ], const AP& ap, int a_kstep, const BP& bp, int b_kstep, int nk, bf16_t* smem) {
;     ...
;   auto sstore = [&](int buf) {
;     bf16_t* As = smem + buf * L::STAGE; bf16_t* Bs = As + L::A_ELEMS;
; #pragma unroll
;     for (int i = 0; i < CA; ++i) { const int c = tid + NTHR * i; *(u32x4*)(As + (c >> 3) * LDT + (c & 7) * 8) = oka[i] ? ra[i] : (u32x4){0u, 0u, 0u, 0u}; }
; #pragma unroll
;     for (int i = 0; i < CB; ++i) { const int c = tid + NTHR * i; *(u32x4*)(Bs + (c >> 3) * LDT + (c & 7) * 8) = rb[i]; }
;   };
;   gload(0); sstore(0); gload(nk > 1 ? 1 : 0); __syncthreads();
; #pragma unroll 1
;   for (int kt = 0; kt < nk; ++kt) {
;     const int buf = kt & 1;
;     sstore(buf ^ 1);
;     gload(kt + 2 < nk ? kt + 2 : nk - 1);
;     __builtin_amdgcn_sched_barrier(0);
;     const bf16_t* As = smem + buf * L::STAGE + (wm * 16 * MI + l15) * LDT + quad * 8;
;     const bf16_t* Bs = smem + buf * L::STAGE + L::A_ELEMS + (wn * 16 * NJ + l15) * LDT + quad * 8;
; #pragma unroll
;     for (int ks = 0; ks < 2; ++ks) {
;       if (MI * NJ >= 32 && ks == 1) asm volatile("" ::: "memory");
;       bf16x8 b[NJ];
; #pragma unroll
;       for (int j = 0; j < NJ; ++j) b[j] = *(const bf16x8*)(Bs + j * 16 * LDT + ks * 32);
; #pragma unroll
;       for (int i = 0; i < MI; ++i) {
;         const bf16x8 a = *(const bf16x8*)(As + i * 16 * LDT + ks * 32);
; #pragma unroll
;         for (int j = 0; j < NJ; ++j) acc[i][j] = SWAP ? mfma16(b[j], a, acc[i][j]) : mfma16(a, b[j], acc[i][j]);
;       }
;     }
;     __syncthreads();
.Lcp1_main:
	ds_read_b128 v[132:135], v156 offset:4608
	s_waitcnt lgkmcnt(4)
	v_mfma_f32_16x16x32_bf16 v[60:63], v[108:111], v[124:127], v[60:63]
	s_waitcnt lgkmcnt(3)
	v_mfma_f32_16x16x32_bf16 v[44:47], v[112:115], v[124:127], v[44:47]
	s_min_u32 s16, s14, 29
	s_and_b32 s15, s14, 1
	s_add_i32 s18, s16, 2
	s_xor_b32 s17, s15, 1
	s_lshl_b32 s16, s18, 9
	s_mul_i32 s17, s17, 0xd800
	s_add_u32 s16, s6, s16
	s_waitcnt vmcnt(5)
	v_cndmask_b32_e32 v83, 0, v83, vcc
	v_cndmask_b32_e32 v82, 0, v82, vcc
	v_cndmask_b32_e32 v81, 0, v81, vcc
	v_cndmask_b32_e32 v80, 0, v80, vcc
	v_add3_u32 v246, s17, v103, v100
	v_add3_u32 v247, s17, v104, v100
	v_add3_u32 v248, s17, v105, v100
	v_add3_u32 v249, s17, v106, v100
	s_addc_u32 s17, s7, 0
	s_lshl_b32 s18, s18, 7
	s_waitcnt vmcnt(4)
	v_cndmask_b32_e64 v71, 0, v71, s[0:1]
	v_cndmask_b32_e64 v70, 0, v70, s[0:1]
	v_cndmask_b32_e64 v69, 0, v69, s[0:1]
	v_cndmask_b32_e64 v68, 0, v68, s[0:1]
	ds_write_b128 v246, v[80:83]
	s_waitcnt lgkmcnt(3)
	v_mfma_f32_16x16x32_bf16 v[28:31], v[116:119], v[124:127], v[28:31]
	s_waitcnt lgkmcnt(2)
	v_mfma_f32_16x16x32_bf16 v[12:15], v[120:123], v[124:127], v[12:15]
	ds_read_b128 v[136:139], v156 offset:6912
	ds_read_b128 v[140:143], v144 offset:18496
	ds_read_b128 v[148:151], v144 offset:20800
	ds_read_b128 v[152:155], v144 offset:23104
	ds_read_b128 v[242:245], v144 offset:25408
	v_mfma_f32_16x16x32_bf16 v[56:59], v[108:111], v[128:131], v[56:59]
	ds_write_b128 v247, v[68:71]
	v_mfma_f32_16x16x32_bf16 v[40:43], v[112:115], v[128:131], v[40:43]
	v_mfma_f32_16x16x32_bf16 v[24:27], v[116:119], v[128:131], v[24:27]
	s_waitcnt vmcnt(3)
	ds_write_b128 v246, v[64:67] offset:18432
	v_mfma_f32_16x16x32_bf16 v[8:11], v[120:123], v[128:131], v[8:11]
	ds_read_b128 v[124:127], v156 offset:64
	s_waitcnt lgkmcnt(9)
	v_mfma_f32_16x16x32_bf16 v[52:55], v[108:111], v[132:135], v[52:55]
	v_mfma_f32_16x16x32_bf16 v[36:39], v[112:115], v[132:135], v[36:39]
	s_waitcnt vmcnt(2)
	ds_write_b128 v247, v[72:75] offset:18432
	v_mfma_f32_16x16x32_bf16 v[20:23], v[116:119], v[132:135], v[20:23]
	v_mfma_f32_16x16x32_bf16 v[4:7], v[120:123], v[132:135], v[4:7]
	s_waitcnt vmcnt(1)
	ds_write_b128 v248, v[76:79] offset:18432
	ds_read_b128 v[128:131], v156 offset:2368
	s_waitcnt lgkmcnt(10)
	v_mfma_f32_16x16x32_bf16 v[48:51], v[108:111], v[136:139], v[48:51]
	v_mfma_f32_16x16x32_bf16 v[32:35], v[112:115], v[136:139], v[32:35]
	s_waitcnt vmcnt(0)
	ds_write_b128 v249, v[84:87] offset:18432
	v_mfma_f32_16x16x32_bf16 v[16:19], v[116:119], v[136:139], v[16:19]
	v_mfma_f32_16x16x32_bf16 v[0:3], v[120:123], v[136:139], v[0:3]
	v_lshl_add_u64 v[64:65], v[88:89], 1, s[16:17]
	v_lshl_add_u64 v[66:67], v[90:91], 1, s[16:17]
	s_add_u32 s16, s8, s18
	s_addc_u32 s17, s9, 0
	global_load_dwordx4 v[80:83], v[64:65], off
	ds_read_b128 v[132:135], v156 offset:4672
	s_waitcnt lgkmcnt(5)
	v_mfma_f32_16x16x32_bf16 v[60:63], v[140:143], v[124:127], v[60:63]
	global_load_dwordx4 v[68:71], v[66:67], off
	v_mfma_f32_16x16x32_bf16 v[44:47], v[148:151], v[124:127], v[44:47]
	v_mfma_f32_16x16x32_bf16 v[28:31], v[152:155], v[124:127], v[28:31]
	v_lshl_add_u64 v[64:65], v[92:93], 1, s[16:17]
	v_lshl_add_u64 v[72:73], v[94:95], 1, s[16:17]
	v_lshl_add_u64 v[76:77], v[96:97], 1, s[16:17]
	v_lshl_add_u64 v[84:85], v[98:99], 1, s[16:17]
	global_load_dwordx4 v[64:67], v[64:65], off
	v_mfma_f32_16x16x32_bf16 v[12:15], v[242:245], v[124:127], v[12:15]
	global_load_dwordx4 v[72:75], v[72:73], off
	ds_read_b128 v[136:139], v156 offset:6976
	s_waitcnt lgkmcnt(3)
	v_mfma_f32_16x16x32_bf16 v[56:59], v[140:143], v[128:131], v[56:59]
	global_load_dwordx4 v[76:79], v[76:77], off
	v_mfma_f32_16x16x32_bf16 v[40:43], v[148:151], v[128:131], v[40:43]
	v_mfma_f32_16x16x32_bf16 v[24:27], v[152:155], v[128:131], v[24:27]
	global_load_dwordx4 v[84:87], v[84:85], off
	v_mfma_f32_16x16x32_bf16 v[8:11], v[242:245], v[128:131], v[8:11]
	s_waitcnt lgkmcnt(0)
	s_barrier
	s_add_i32 s14, s14, 1
	s_cmp_lg_u32 s14, 32
	s_cbranch_scc0 .Lcp1_exit
	s_and_b32 s98, s14, 1
	s_mul_i32 s98, s98, 0xd800
	v_add3_u32 v144, s98, v102, v107
	v_add3_u32 v156, s98, v101, v107
	ds_read_b128 v[124:127], v156
	ds_read_b128 v[128:131], v156 offset:2304
	ds_read_b128 v[108:111], v144 offset:18432
	ds_read_b128 v[112:115], v144 offset:20736
	ds_read_b128 v[116:119], v144 offset:23040
	ds_read_b128 v[120:123], v144 offset:25344
	v_mfma_f32_16x16x32_bf16 v[52:55], v[140:143], v[132:135], v[52:55]
	v_mfma_f32_16x16x32_bf16 v[48:51], v[140:143], v[136:139], v[48:51]
	v_mfma_f32_16x16x32_bf16 v[36:39], v[148:151], v[132:135], v[36:39]
	v_mfma_f32_16x16x32_bf16 v[32:35], v[148:151], v[136:139], v[32:35]
	v_mfma_f32_16x16x32_bf16 v[20:23], v[152:155], v[132:135], v[20:23]
	v_mfma_f32_16x16x32_bf16 v[16:19], v[152:155], v[136:139], v[16:19]
	v_mfma_f32_16x16x32_bf16 v[4:7], v[242:245], v[132:135], v[4:7]
	v_mfma_f32_16x16x32_bf16 v[0:3], v[242:245], v[136:139], v[0:3]
	s_branch .Lcp1_main

; DI f32x4 mfma16(bf16x8 a, bf16x8 b, f32x4 c) { return __builtin_amdgcn_mfma_f32_16x16x32_bf16(a, b, c, 0, 0, 0); }
; DI void merge_tile(const Params& p, int layer, int tm, int tn, bf16_t* smem) {
;     ...
;   auto gload_next = [&]() {
;     const bf16_t* ab = la + (size_t)lkt * laks; const bf16_t* bb = lb + (size_t)lkt * 64;
; #pragma unroll
;     for (int i = 0; i < 4; ++i) ra[i] = *(const u32x4*)(ab + pa0 + (size_t)i * 64 * lald);
; #pragma unroll
;     for (int i = 0; i < 2; ++i) rb[i] = *(const u32x4*)(bb + pb0 + (size_t)i * 64 * lbld);
;     if (++lkt == lnk) {
;       if (ls + 1 < 6) { ++ls; lkt = 0; get_seg(ls); set_offsets(); } else lkt = lnk - 1;
;     }
;   };
;   auto sstore = [&](int buf) {
;     bf16_t* As = smem + buf * L::STAGE; bf16_t* Bs = As + L::A_ELEMS;
; #pragma unroll
;     for (int i = 0; i < 4; ++i) { const int c = tid + NTHR * i; *(u32x4*)(As + (c >> 3) * LDT + (c & 7) * 8) = ra[i]; }
; #pragma unroll
;     for (int i = 0; i < 2; ++i) { const int c = tid + NTHR * i; *(u32x4*)(Bs + (c >> 3) * LDT + (c & 7) * 8) = rb[i]; }
;   };
;   gload_next(); sstore(0); gload_next(); __syncthreads();
;   int buf = 0;
; #pragma unroll 1
;   for (int sg = 0; sg < 6; ++sg) {
;     const int nk = (sg & 1) ? 8 : 16;
; #pragma unroll 1
;     for (int kt = 0; kt < nk; ++kt) {
;       sstore(buf ^ 1);
;       gload_next();
;       __builtin_amdgcn_sched_barrier(0);
;       const bf16_t* As = smem + buf * L::STAGE + (wm * 128 + l15) * LDT + quad * 8;
;       const bf16_t* Bs = smem + buf * L::STAGE + L::A_ELEMS + (wn * 32 + l15) * LDT + quad * 8;
; #pragma unroll
;       for (int ks = 0; ks < 2; ++ks) {
;         if (ks == 1) asm volatile("" ::: "memory");
;         bf16x8 b[2];
; #pragma unroll
;         for (int j = 0; j < 2; ++j) b[j] = *(const bf16x8*)(Bs + j * 16 * LDT + ks * 32);
; #pragma unroll
;         for (int i = 0; i < 8; ++i) {
;           const bf16x8 a = *(const bf16x8*)(As + i * 16 * LDT + ks * 32);
; #pragma unroll
;           for (int j = 0; j < 2; ++j) acc[i][j] = mfma16(b[j], a, acc[i][j]);
;         }
;       }
;       __syncthreads();
.Lmg1_main:
	ds_read_b128 v[182:185], v168 offset:9216
	s_waitcnt lgkmcnt(2)
	v_mfma_f32_16x16x32_bf16 v[148:151], v[152:155], v[156:159], v[148:151]
	s_waitcnt lgkmcnt(1)
	v_mfma_f32_16x16x32_bf16 v[144:147], v[160:163], v[156:159], v[144:147]
	s_xor_b32 s55, s57, 1
	s_mul_i32 s2, s55, 0xd800
	v_add3_u32 v169, s2, v232, v229
	s_waitcnt vmcnt(5)
	ds_write_b128 v169, v[4:7]
	ds_read_b128 v[186:189], v168 offset:11520
	ds_read_b128 v[198:201], v164 offset:36928
	ds_read_b128 v[202:205], v164 offset:39232
	v_mfma_f32_16x16x32_bf16 v[140:143], v[152:155], v[170:173], v[140:143]
	v_mfma_f32_16x16x32_bf16 v[136:139], v[160:163], v[170:173], v[136:139]
	v_add3_u32 v4, s2, v233, v229
	s_waitcnt vmcnt(4)
	ds_write_b128 v4, v[0:3]
	ds_read_b128 v[190:193], v168 offset:13824
	v_mfma_f32_16x16x32_bf16 v[132:135], v[152:155], v[174:177], v[132:135]
	v_add3_u32 v0, s2, v234, v229
	s_ashr_i32 s27, s26, 31
	s_waitcnt vmcnt(3)
	ds_write_b128 v0, v[12:15]
	v_mfma_f32_16x16x32_bf16 v[128:131], v[160:163], v[174:177], v[128:131]
	ds_read_b128 v[194:197], v168 offset:16128
	v_mfma_f32_16x16x32_bf16 v[124:127], v[152:155], v[178:181], v[124:127]
	v_add3_u32 v0, s2, v235, v229
	s_mul_hi_u32 s2, s52, s26
	s_mul_i32 s3, s52, s27
	s_add_i32 s3, s2, s3
	s_mul_i32 s2, s52, s26
	s_lshl_b64 s[2:3], s[2:3], 1
	s_add_u32 s2, s24, s2
	s_addc_u32 s3, s25, s3
	s_waitcnt vmcnt(2)
	ds_write_b128 v0, v[8:11]
	v_mfma_f32_16x16x32_bf16 v[120:123], v[160:163], v[178:181], v[120:123]
	ds_read_b128 v[156:159], v168 offset:64
	s_waitcnt lgkmcnt(10)
	v_mfma_f32_16x16x32_bf16 v[116:119], v[152:155], v[182:185], v[116:119]
	s_waitcnt vmcnt(1)
	ds_write_b128 v169, v[16:19] offset:36864
	v_mfma_f32_16x16x32_bf16 v[112:115], v[160:163], v[182:185], v[112:115]
	ds_read_b128 v[170:173], v168 offset:2368
	s_waitcnt lgkmcnt(10)
	v_mfma_f32_16x16x32_bf16 v[108:111], v[152:155], v[186:189], v[108:111]
	s_waitcnt vmcnt(0)
	ds_write_b128 v4, v[20:23] offset:36864
	v_mfma_f32_16x16x32_bf16 v[104:107], v[160:163], v[186:189], v[104:107]
	v_lshl_add_u64 v[0:1], v[216:217], 1, s[2:3]
	s_lshl_b64 s[2:3], s[8:9], 7
	v_lshl_add_u64 v[8:9], v[0:1], 0, s[2:3]
	s_lshl_b64 s[4:5], s[26:27], 7
	global_load_dwordx4 v[4:7], v[0:1], off
	ds_read_b128 v[174:177], v168 offset:4672
	s_waitcnt lgkmcnt(8)
	v_mfma_f32_16x16x32_bf16 v[100:103], v[152:155], v[190:193], v[100:103]
	v_mfma_f32_16x16x32_bf16 v[96:99], v[160:163], v[190:193], v[96:99]
	global_load_dwordx4 v[0:3], v[8:9], off
	ds_read_b128 v[178:181], v168 offset:6976
	s_waitcnt lgkmcnt(7)
	v_mfma_f32_16x16x32_bf16 v[92:95], v[152:155], v[194:197], v[92:95]
	v_mfma_f32_16x16x32_bf16 v[88:91], v[160:163], v[194:197], v[88:91]
	v_lshl_add_u64 v[8:9], v[8:9], 0, s[2:3]
	v_lshl_add_u64 v[10:11], v[8:9], 0, s[2:3]
	s_add_u32 s2, s22, s4
	s_addc_u32 s3, s23, s5
	v_mov_b32_e32 v219, v217
	s_mov_b32 s21, s9
	v_lshl_add_u64 v[16:17], v[218:219], 1, s[2:3]
	s_lshl_b64 s[2:3], s[20:21], 7
	v_lshl_add_u64 v[20:21], v[16:17], 0, s[2:3]
	global_load_dwordx4 v[12:15], v[8:9], off
	ds_read_b128 v[182:185], v168 offset:9280
	s_waitcnt lgkmcnt(6)
	v_mfma_f32_16x16x32_bf16 v[148:151], v[198:201], v[156:159], v[148:151]
	global_load_dwordx4 v[8:11], v[10:11], off
	v_mfma_f32_16x16x32_bf16 v[144:147], v[202:205], v[156:159], v[144:147]
	ds_read_b128 v[186:189], v168 offset:11584
	s_waitcnt lgkmcnt(5)
	v_mfma_f32_16x16x32_bf16 v[140:143], v[198:201], v[170:173], v[140:143]
	global_load_dwordx4 v[16:19], v[16:17], off
	v_mfma_f32_16x16x32_bf16 v[136:139], v[202:205], v[170:173], v[136:139]
	global_load_dwordx4 v[20:23], v[20:21], off
	ds_read_b128 v[190:193], v168 offset:13888
	s_waitcnt lgkmcnt(4)
	v_mfma_f32_16x16x32_bf16 v[132:135], v[198:201], v[174:177], v[132:135]
	v_mfma_f32_16x16x32_bf16 v[128:131], v[202:205], v[174:177], v[128:131]
	ds_read_b128 v[194:197], v168 offset:16192
	s_waitcnt lgkmcnt(4)
	v_mfma_f32_16x16x32_bf16 v[124:127], v[198:201], v[178:181], v[124:127]
	v_mfma_f32_16x16x32_bf16 v[120:123], v[202:205], v[178:181], v[120:123]
	s_waitcnt lgkmcnt(0)
	s_barrier
	s_add_i32 s2, s26, 1
	s_cmp_lg_u32 s2, s53
	s_cbranch_scc1 .LBB0_1876
	s_cmp_gt_i32 s54, 4
	s_cbranch_scc1 .LBB0_1879
	s_add_i32 s21, s54, 1
	s_ashr_i32 s2, s21, 1
	s_bitcmp0_b32 s54, 0
	s_mov_b64 s[4:5], -1
	s_cbranch_scc1 .LBB0_1874
	s_ashr_i32 s3, s2, 31
	s_lshl_b64 s[4:5], s[2:3], 21
	s_add_u32 s22, s16, s4
	s_addc_u32 s23, s17, s5
	s_mov_b64 s[4:5], 0

; DI f32x4 mfma16(bf16x8 a, bf16x8 b, f32x4 c) { return __builtin_amdgcn_mfma_f32_16x16x32_bf16(a, b, c, 0, 0, 0); }
; template <int MI, int NJ, bool SWAP, class AP, class BP>
; DI void gemm_main(f32x4 (&acc)[MI][NJ], const AP& ap, int a_kstep, const BP& bp, int b_kstep, int nk, bf16_t* smem) {
;     ...
;   auto gload = [&](int kt) {
;     const bf16_t* ab = ap.base + (size_t)kt * a_kstep; const bf16_t* bb = bp.base + (size_t)kt * b_kstep;
; #pragma unroll
;     for (int i = 0; i < CA; ++i) ra[i] = *(const u32x4*)(ab + pa[i]);
; #pragma unroll
;     for (int i = 0; i < CB; ++i) rb[i] = *(const u32x4*)(bb + pb[i]);
;   };
;   auto sstore = [&](int buf) {
;     bf16_t* As = smem + buf * L::STAGE; bf16_t* Bs = As + L::A_ELEMS;
; #pragma unroll
;     for (int i = 0; i < CA; ++i) { const int c = tid + NTHR * i; *(u32x4*)(As + (c >> 3) * LDT + (c & 7) * 8) = oka[i] ? ra[i] : (u32x4){0u, 0u, 0u, 0u}; }
; #pragma unroll
;     for (int i = 0; i < CB; ++i) { const int c = tid + NTHR * i; *(u32x4*)(Bs + (c >> 3) * LDT + (c & 7) * 8) = rb[i]; }
;   };
;   gload(0); sstore(0); gload(nk > 1 ? 1 : 0); __syncthreads();
; #pragma unroll 1
;   for (int kt = 0; kt < nk; ++kt) {
;     const int buf = kt & 1;
;     sstore(buf ^ 1);
;     gload(kt + 2 < nk ? kt + 2 : nk - 1);
;     __builtin_amdgcn_sched_barrier(0);
;     const bf16_t* As = smem + buf * L::STAGE + (wm * 16 * MI + l15) * LDT + quad * 8;
;     const bf16_t* Bs = smem + buf * L::STAGE + L::A_ELEMS + (wn * 16 * NJ + l15) * LDT + quad * 8;
; #pragma unroll
;     for (int ks = 0; ks < 2; ++ks) {
;       if (MI * NJ >= 32 && ks == 1) asm volatile("" ::: "memory");
;       bf16x8 b[NJ];
; #pragma unroll
;       for (int j = 0; j < NJ; ++j) b[j] = *(const bf16x8*)(Bs + j * 16 * LDT + ks * 32);
; #pragma unroll
;       for (int i = 0; i < MI; ++i) {
;         const bf16x8 a = *(const bf16x8*)(As + i * 16 * LDT + ks * 32);
; #pragma unroll
;         for (int j = 0; j < NJ; ++j) acc[i][j] = SWAP ? mfma16(b[j], a, acc[i][j]) : mfma16(a, b[j], acc[i][j]);
;       }
;     }
;     __syncthreads();
;   }
.Lgm13_main:
	ds_read_b128 v[242:245], v177 offset:4608
	s_waitcnt lgkmcnt(4)
	v_mfma_f32_16x16x32_bf16 v[156:159], v[178:181], v[194:197], v[156:159]
	s_waitcnt lgkmcnt(3)
	v_mfma_f32_16x16x32_bf16 v[152:155], v[182:185], v[194:197], v[152:155]
	s_waitcnt lgkmcnt(2)
	v_mfma_f32_16x16x32_bf16 v[148:151], v[186:189], v[194:197], v[148:151]
	s_waitcnt lgkmcnt(1)
	v_mfma_f32_16x16x32_bf16 v[144:147], v[190:193], v[194:197], v[144:147]
	s_and_b32 s15, s1, 1
	s_min_u32 s16, s1, 13
	s_xor_b32 s17, s15, 1
	s_lshl_b32 s26, s16, 7
	s_mul_i32 s17, s17, 0x12000
	s_add_u32 s16, s2, s26
	v_add3_u32 v250, s17, v172, v170
	v_add3_u32 v251, s17, v174, v170
	v_add3_u32 v252, s17, v175, v170
	v_add3_u32 v253, s17, v176, v170
	s_addc_u32 s17, s3, 0
	s_waitcnt vmcnt(7)
	ds_write_b128 v250, v[112:115]
	ds_read_b128 v[246:249], v177 offset:6912
	v_mfma_f32_16x16x32_bf16 v[108:111], v[178:181], v[198:201], v[108:111]
	v_mfma_f32_16x16x32_bf16 v[104:107], v[182:185], v[198:201], v[104:107]
	v_mfma_f32_16x16x32_bf16 v[100:103], v[186:189], v[198:201], v[100:103]
	v_mfma_f32_16x16x32_bf16 v[96:99], v[190:193], v[198:201], v[96:99]
	s_waitcnt vmcnt(6)
	ds_write_b128 v251, v[116:119]
	ds_read_b128 v[194:197], v177 offset:9216
	s_waitcnt lgkmcnt(4)
	v_mfma_f32_16x16x32_bf16 v[92:95], v[178:181], v[242:245], v[92:95]
	v_mfma_f32_16x16x32_bf16 v[88:91], v[182:185], v[242:245], v[88:91]
	v_mfma_f32_16x16x32_bf16 v[84:87], v[186:189], v[242:245], v[84:87]
	v_mfma_f32_16x16x32_bf16 v[80:83], v[190:193], v[242:245], v[80:83]
	ds_read_b128 v[198:201], v177 offset:11520
	s_waitcnt lgkmcnt(3)
	v_mfma_f32_16x16x32_bf16 v[76:79], v[178:181], v[246:249], v[76:79]
	s_waitcnt vmcnt(5)
	ds_write_b128 v252, v[120:123]
	v_mfma_f32_16x16x32_bf16 v[72:75], v[182:185], v[246:249], v[72:75]
	v_mfma_f32_16x16x32_bf16 v[68:71], v[186:189], v[246:249], v[68:71]
	v_mfma_f32_16x16x32_bf16 v[64:67], v[190:193], v[246:249], v[64:67]
	ds_read_b128 v[242:245], v177 offset:13824
	s_waitcnt lgkmcnt(3)
	v_mfma_f32_16x16x32_bf16 v[60:63], v[178:181], v[194:197], v[60:63]
	s_waitcnt vmcnt(4)
	ds_write_b128 v253, v[124:127]
	v_mfma_f32_16x16x32_bf16 v[56:59], v[182:185], v[194:197], v[56:59]
	v_mfma_f32_16x16x32_bf16 v[52:55], v[186:189], v[194:197], v[52:55]
	v_mfma_f32_16x16x32_bf16 v[48:51], v[190:193], v[194:197], v[48:51]
	ds_read_b128 v[246:249], v177 offset:16128
	s_waitcnt lgkmcnt(4)
	v_mfma_f32_16x16x32_bf16 v[44:47], v[178:181], v[198:201], v[44:47]
	s_waitcnt vmcnt(3)
	ds_write_b128 v250, v[128:131] offset:36864
	v_mfma_f32_16x16x32_bf16 v[40:43], v[182:185], v[198:201], v[40:43]
	v_mfma_f32_16x16x32_bf16 v[36:39], v[186:189], v[198:201], v[36:39]
	v_mfma_f32_16x16x32_bf16 v[32:35], v[190:193], v[198:201], v[32:35]
	ds_read_b128 v[194:197], v177 offset:64
	s_waitcnt lgkmcnt(4)
	v_mfma_f32_16x16x32_bf16 v[28:31], v[178:181], v[242:245], v[28:31]
	s_waitcnt vmcnt(2)
	ds_write_b128 v251, v[132:135] offset:36864
	v_mfma_f32_16x16x32_bf16 v[24:27], v[182:185], v[242:245], v[24:27]
	v_mfma_f32_16x16x32_bf16 v[20:23], v[186:189], v[242:245], v[20:23]
	v_mfma_f32_16x16x32_bf16 v[16:19], v[190:193], v[242:245], v[16:19]
	ds_read_b128 v[198:201], v177 offset:2368
	s_waitcnt lgkmcnt(4)
	v_mfma_f32_16x16x32_bf16 v[8:11], v[178:181], v[246:249], v[8:11]
	ds_read_b128 v[178:181], v202 offset:36928
	s_waitcnt vmcnt(1)
	ds_write_b128 v252, v[136:139] offset:36864
	v_mfma_f32_16x16x32_bf16 v[4:7], v[182:185], v[246:249], v[4:7]
	ds_read_b128 v[182:185], v202 offset:39232
	v_mfma_f32_16x16x32_bf16 v[0:3], v[186:189], v[246:249], v[0:3]
	ds_read_b128 v[186:189], v202 offset:41536
	v_mfma_f32_16x16x32_bf16 v[12:15], v[190:193], v[246:249], v[12:15]
	ds_read_b128 v[190:193], v202 offset:43840
	ds_read_b128 v[242:245], v177 offset:4672
	s_waitcnt lgkmcnt(5)
	v_mfma_f32_16x16x32_bf16 v[156:159], v[178:181], v[194:197], v[156:159]
	s_waitcnt lgkmcnt(3)
	v_mfma_f32_16x16x32_bf16 v[152:155], v[182:185], v[194:197], v[152:155]
	s_waitcnt vmcnt(0)
	ds_write_b128 v253, v[140:143] offset:36864
	s_waitcnt lgkmcnt(3)
	v_mfma_f32_16x16x32_bf16 v[148:151], v[186:189], v[194:197], v[148:151]
	s_waitcnt lgkmcnt(2)
	v_mfma_f32_16x16x32_bf16 v[144:147], v[190:193], v[194:197], v[144:147]
	v_lshl_add_u64 v[112:113], s[16:17], 0, v[162:163]
	v_lshl_add_u64 v[116:117], s[16:17], 0, v[164:165]
	v_lshl_add_u64 v[120:121], s[16:17], 0, v[166:167]
	v_lshl_add_u64 v[124:125], s[16:17], 0, v[168:169]
	s_add_u32 s16, s12, s26
	s_addc_u32 s17, s13, 0
	v_lshl_add_u64 v[128:129], s[16:17], 0, v[162:163]
	v_lshl_add_u64 v[132:133], s[16:17], 0, v[164:165]
	v_lshl_add_u64 v[136:137], s[16:17], 0, v[166:167]
	v_lshl_add_u64 v[140:141], s[16:17], 0, v[168:169]
	global_load_dwordx4 v[112:115], v[112:113], off offset:256
	ds_read_b128 v[246:249], v177 offset:6976
	v_mfma_f32_16x16x32_bf16 v[108:111], v[178:181], v[198:201], v[108:111]
	v_mfma_f32_16x16x32_bf16 v[104:107], v[182:185], v[198:201], v[104:107]
	global_load_dwordx4 v[116:119], v[116:117], off offset:256
	v_mfma_f32_16x16x32_bf16 v[100:103], v[186:189], v[198:201], v[100:103]
	v_mfma_f32_16x16x32_bf16 v[96:99], v[190:193], v[198:201], v[96:99]
	ds_read_b128 v[194:197], v177 offset:9280
	s_waitcnt lgkmcnt(3)
	v_mfma_f32_16x16x32_bf16 v[92:95], v[178:181], v[242:245], v[92:95]
	global_load_dwordx4 v[120:123], v[120:121], off offset:256
	v_mfma_f32_16x16x32_bf16 v[88:91], v[182:185], v[242:245], v[88:91]
	v_mfma_f32_16x16x32_bf16 v[84:87], v[186:189], v[242:245], v[84:87]
	global_load_dwordx4 v[124:127], v[124:125], off offset:256
	v_mfma_f32_16x16x32_bf16 v[80:83], v[190:193], v[242:245], v[80:83]
	ds_read_b128 v[198:201], v177 offset:11584
	s_waitcnt lgkmcnt(2)
	v_mfma_f32_16x16x32_bf16 v[76:79], v[178:181], v[246:249], v[76:79]
	v_mfma_f32_16x16x32_bf16 v[72:75], v[182:185], v[246:249], v[72:75]
	global_load_dwordx4 v[128:131], v[128:129], off offset:256
	v_mfma_f32_16x16x32_bf16 v[68:71], v[186:189], v[246:249], v[68:71]
	v_mfma_f32_16x16x32_bf16 v[64:67], v[190:193], v[246:249], v[64:67]
	global_load_dwordx4 v[132:135], v[132:133], off offset:256
	ds_read_b128 v[242:245], v177 offset:13888
	s_waitcnt lgkmcnt(2)
	v_mfma_f32_16x16x32_bf16 v[60:63], v[178:181], v[194:197], v[60:63]
	v_mfma_f32_16x16x32_bf16 v[56:59], v[182:185], v[194:197], v[56:59]
	v_mfma_f32_16x16x32_bf16 v[52:55], v[186:189], v[194:197], v[52:55]
	global_load_dwordx4 v[136:139], v[136:137], off offset:256
	v_mfma_f32_16x16x32_bf16 v[48:51], v[190:193], v[194:197], v[48:51]
	ds_read_b128 v[246:249], v177 offset:16192
	s_waitcnt lgkmcnt(2)
	v_mfma_f32_16x16x32_bf16 v[44:47], v[178:181], v[198:201], v[44:47]
	global_load_dwordx4 v[140:143], v[140:141], off offset:256
	v_mfma_f32_16x16x32_bf16 v[40:43], v[182:185], v[198:201], v[40:43]
	v_mfma_f32_16x16x32_bf16 v[36:39], v[186:189], v[198:201], v[36:39]
	v_mfma_f32_16x16x32_bf16 v[32:35], v[190:193], v[198:201], v[32:35]
	s_waitcnt lgkmcnt(0)
	s_barrier
; DI f32x4 mfma16(bf16x8 a, bf16x8 b, f32x4 c) { return __builtin_amdgcn_mfma_f32_16x16x32_bf16(a, b, c, 0, 0, 0); }
; template <int MI, int NJ, bool SWAP, class AP, class BP>
; DI void gemm_main(f32x4 (&acc)[MI][NJ], const AP& ap, int a_kstep, const BP& bp, int b_kstep, int nk, bf16_t* smem) {
;     ...
;   for (int kt = 0; kt < nk; ++kt) {
;     const int buf = kt & 1;
;     sstore(buf ^ 1);
;     gload(kt + 2 < nk ? kt + 2 : nk - 1);
;     __builtin_amdgcn_sched_barrier(0);
;     const bf16_t* As = smem + buf * L::STAGE + (wm * 16 * MI + l15) * LDT + quad * 8;
;     const bf16_t* Bs = smem + buf * L::STAGE + L::A_ELEMS + (wn * 16 * NJ + l15) * LDT + quad * 8;
; #pragma unroll
;     for (int ks = 0; ks < 2; ++ks) {
;       if (MI * NJ >= 32 && ks == 1) asm volatile("" ::: "memory");
;       bf16x8 b[NJ];
; #pragma unroll
;       for (int j = 0; j < NJ; ++j) b[j] = *(const bf16x8*)(Bs + j * 16 * LDT + ks * 32);
; #pragma unroll
;       for (int i = 0; i < MI; ++i) {
;         const bf16x8 a = *(const bf16x8*)(As + i * 16 * LDT + ks * 32);
; #pragma unroll
;         for (int j = 0; j < NJ; ++j) acc[i][j] = SWAP ? mfma16(b[j], a, acc[i][j]) : mfma16(a, b[j], acc[i][j]);
;       }
;     }
;     __syncthreads();
	s_add_i32 s1, s1, 1
	s_cmp_lg_u32 s1, 16
	s_cbranch_scc0 .Lgm13_exit
	s_and_b32 s98, s1, 1
	s_mul_i32 s98, s98, 0x12000
	v_add3_u32 v202, s98, v160, v173
	v_add3_u32 v177, s98, v171, v173
	ds_read_b128 v[194:197], v177
	ds_read_b128 v[198:201], v177 offset:2304
	v_mfma_f32_16x16x32_bf16 v[28:31], v[178:181], v[242:245], v[28:31]
	v_mfma_f32_16x16x32_bf16 v[8:11], v[178:181], v[246:249], v[8:11]
	ds_read_b128 v[178:181], v202 offset:36864
	v_mfma_f32_16x16x32_bf16 v[24:27], v[182:185], v[242:245], v[24:27]
	v_mfma_f32_16x16x32_bf16 v[4:7], v[182:185], v[246:249], v[4:7]
	ds_read_b128 v[182:185], v202 offset:39168
	v_mfma_f32_16x16x32_bf16 v[20:23], v[186:189], v[242:245], v[20:23]
	v_mfma_f32_16x16x32_bf16 v[0:3], v[186:189], v[246:249], v[0:3]
	ds_read_b128 v[186:189], v202 offset:41472
	v_mfma_f32_16x16x32_bf16 v[16:19], v[190:193], v[242:245], v[16:19]
	v_mfma_f32_16x16x32_bf16 v[12:15], v[190:193], v[246:249], v[12:15]
	ds_read_b128 v[190:193], v202 offset:43776
	s_branch .Lgm13_main

; DI f32x4 mfma16(bf16x8 a, bf16x8 b, f32x4 c) { return __builtin_amdgcn_mfma_f32_16x16x32_bf16(a, b, c, 0, 0, 0); }
; template <int MI, int NJ, bool SWAP, class AP, class BP>
; DI void gemm_main(f32x4 (&acc)[MI][NJ], const AP& ap, int a_kstep, const BP& bp, int b_kstep, int nk, bf16_t* smem) {
;     ...
;   auto gload = [&](int kt) {
;     const bf16_t* ab = ap.base + (size_t)kt * a_kstep; const bf16_t* bb = bp.base + (size_t)kt * b_kstep;
; #pragma unroll
;     for (int i = 0; i < CA; ++i) ra[i] = *(const u32x4*)(ab + pa[i]);
; #pragma unroll
;     for (int i = 0; i < CB; ++i) rb[i] = *(const u32x4*)(bb + pb[i]);
;   };
;   auto sstore = [&](int buf) {
;     bf16_t* As = smem + buf * L::STAGE; bf16_t* Bs = As + L::A_ELEMS;
; #pragma unroll
;     for (int i = 0; i < CA; ++i) { const int c = tid + NTHR * i; *(u32x4*)(As + (c >> 3) * LDT + (c & 7) * 8) = oka[i] ? ra[i] : (u32x4){0u, 0u, 0u, 0u}; }
; #pragma unroll
;     for (int i = 0; i < CB; ++i) { const int c = tid + NTHR * i; *(u32x4*)(Bs + (c >> 3) * LDT + (c & 7) * 8) = rb[i]; }
;   };
;   gload(0); sstore(0); gload(nk > 1 ? 1 : 0); __syncthreads();
; #pragma unroll 1
;   for (int kt = 0; kt < nk; ++kt) {
;     const int buf = kt & 1;
;     sstore(buf ^ 1);
;     gload(kt + 2 < nk ? kt + 2 : nk - 1);
;     __builtin_amdgcn_sched_barrier(0);
;     const bf16_t* As = smem + buf * L::STAGE + (wm * 16 * MI + l15) * LDT + quad * 8;
;     const bf16_t* Bs = smem + buf * L::STAGE + L::A_ELEMS + (wn * 16 * NJ + l15) * LDT + quad * 8;
; #pragma unroll
;     for (int ks = 0; ks < 2; ++ks) {
;       if (MI * NJ >= 32 && ks == 1) asm volatile("" ::: "memory");
;       bf16x8 b[NJ];
; #pragma unroll
;       for (int j = 0; j < NJ; ++j) b[j] = *(const bf16x8*)(Bs + j * 16 * LDT + ks * 32);
; #pragma unroll
;       for (int i = 0; i < MI; ++i) {
;         const bf16x8 a = *(const bf16x8*)(As + i * 16 * LDT + ks * 32);
; #pragma unroll
;         for (int j = 0; j < NJ; ++j) acc[i][j] = SWAP ? mfma16(b[j], a, acc[i][j]) : mfma16(a, b[j], acc[i][j]);
.Lgm14_main:
	ds_read_b128 v[242:245], v181 offset:4608
	s_waitcnt lgkmcnt(4)
	v_mfma_f32_16x16x32_bf16 v[156:159], v[182:185], v[198:201], v[156:159]
	s_waitcnt lgkmcnt(3)
	v_mfma_f32_16x16x32_bf16 v[152:155], v[186:189], v[198:201], v[152:155]
	s_waitcnt lgkmcnt(2)
	v_mfma_f32_16x16x32_bf16 v[148:151], v[190:193], v[198:201], v[148:151]
	s_waitcnt lgkmcnt(1)
	v_mfma_f32_16x16x32_bf16 v[144:147], v[194:197], v[198:201], v[144:147]
	s_and_b32 s46, s43, 1
	s_min_u32 s44, s43, 13
	s_xor_b32 s45, s46, 1
	s_lshl_b32 s47, s44, 7
	s_mul_i32 s45, s45, 0x12000
	s_waitcnt vmcnt(7)
	v_cndmask_b32_e32 v143, 0, v143, vcc
	v_cndmask_b32_e32 v142, 0, v142, vcc
	v_cndmask_b32_e32 v141, 0, v141, vcc
	v_cndmask_b32_e32 v140, 0, v140, vcc
	s_add_u32 s44, s18, s47
	v_add3_u32 v250, s45, v172, v169
	s_waitcnt vmcnt(6)
	v_cndmask_b32_e64 v131, 0, v131, s[0:1]
	v_cndmask_b32_e64 v130, 0, v130, s[0:1]
	v_cndmask_b32_e64 v129, 0, v129, s[0:1]
	v_cndmask_b32_e64 v128, 0, v128, s[0:1]
	s_waitcnt vmcnt(5)
	v_cndmask_b32_e64 v115, 0, v115, s[2:3]
	v_cndmask_b32_e64 v114, 0, v114, s[2:3]
	v_cndmask_b32_e64 v113, 0, v113, s[2:3]
	v_cndmask_b32_e64 v112, 0, v112, s[2:3]
	s_waitcnt vmcnt(4)
	v_cndmask_b32_e64 v135, 0, v135, s[4:5]
	v_cndmask_b32_e64 v134, 0, v134, s[4:5]
	v_cndmask_b32_e64 v133, 0, v133, s[4:5]
	v_cndmask_b32_e64 v132, 0, v132, s[4:5]
	v_add3_u32 v251, s45, v173, v169
	v_add3_u32 v252, s45, v174, v169
	v_add3_u32 v253, s45, v175, v169
	s_addc_u32 s45, s19, 0
	ds_write_b128 v250, v[140:143]
	ds_read_b128 v[246:249], v181 offset:6912
	v_mfma_f32_16x16x32_bf16 v[108:111], v[182:185], v[202:205], v[108:111]
	v_mfma_f32_16x16x32_bf16 v[104:107], v[186:189], v[202:205], v[104:107]
	v_mfma_f32_16x16x32_bf16 v[100:103], v[190:193], v[202:205], v[100:103]
	v_mfma_f32_16x16x32_bf16 v[96:99], v[194:197], v[202:205], v[96:99]
	ds_write_b128 v251, v[128:131]
	ds_read_b128 v[198:201], v181 offset:9216
	s_waitcnt lgkmcnt(4)
	v_mfma_f32_16x16x32_bf16 v[92:95], v[182:185], v[242:245], v[92:95]
	v_mfma_f32_16x16x32_bf16 v[88:91], v[186:189], v[242:245], v[88:91]
	v_mfma_f32_16x16x32_bf16 v[84:87], v[190:193], v[242:245], v[84:87]
	v_mfma_f32_16x16x32_bf16 v[80:83], v[194:197], v[242:245], v[80:83]
	ds_read_b128 v[202:205], v181 offset:11520
	s_waitcnt lgkmcnt(3)
	v_mfma_f32_16x16x32_bf16 v[76:79], v[182:185], v[246:249], v[76:79]
	ds_write_b128 v252, v[112:115]
	v_mfma_f32_16x16x32_bf16 v[72:75], v[186:189], v[246:249], v[72:75]
	v_mfma_f32_16x16x32_bf16 v[68:71], v[190:193], v[246:249], v[68:71]
	v_mfma_f32_16x16x32_bf16 v[64:67], v[194:197], v[246:249], v[64:67]
	ds_read_b128 v[242:245], v181 offset:13824
	s_waitcnt lgkmcnt(3)
	v_mfma_f32_16x16x32_bf16 v[60:63], v[182:185], v[198:201], v[60:63]
	ds_write_b128 v253, v[132:135]
	v_mfma_f32_16x16x32_bf16 v[56:59], v[186:189], v[198:201], v[56:59]
	v_mfma_f32_16x16x32_bf16 v[52:55], v[190:193], v[198:201], v[52:55]
	v_mfma_f32_16x16x32_bf16 v[48:51], v[194:197], v[198:201], v[48:51]
	ds_read_b128 v[246:249], v181 offset:16128
	s_waitcnt lgkmcnt(4)
	v_mfma_f32_16x16x32_bf16 v[44:47], v[182:185], v[202:205], v[44:47]
	s_waitcnt vmcnt(3)
	ds_write_b128 v250, v[116:119] offset:36864
	v_mfma_f32_16x16x32_bf16 v[40:43], v[186:189], v[202:205], v[40:43]
	v_mfma_f32_16x16x32_bf16 v[36:39], v[190:193], v[202:205], v[36:39]
	v_mfma_f32_16x16x32_bf16 v[32:35], v[194:197], v[202:205], v[32:35]
	ds_read_b128 v[198:201], v181 offset:64
	s_waitcnt lgkmcnt(4)
	v_mfma_f32_16x16x32_bf16 v[28:31], v[182:185], v[242:245], v[28:31]
	s_waitcnt vmcnt(2)
	ds_write_b128 v251, v[120:123] offset:36864
	v_mfma_f32_16x16x32_bf16 v[24:27], v[186:189], v[242:245], v[24:27]
	v_mfma_f32_16x16x32_bf16 v[20:23], v[190:193], v[242:245], v[20:23]
	v_mfma_f32_16x16x32_bf16 v[12:15], v[194:197], v[242:245], v[12:15]
	ds_read_b128 v[202:205], v181 offset:2368
	s_waitcnt lgkmcnt(4)
	v_mfma_f32_16x16x32_bf16 v[8:11], v[182:185], v[246:249], v[8:11]
	ds_read_b128 v[182:185], v206 offset:36928
	s_waitcnt vmcnt(1)
; DI f32x4 mfma16(bf16x8 a, bf16x8 b, f32x4 c) { return __builtin_amdgcn_mfma_f32_16x16x32_bf16(a, b, c, 0, 0, 0); }
; template <int MI, int NJ, bool SWAP, class AP, class BP>
; DI void gemm_main(f32x4 (&acc)[MI][NJ], const AP& ap, int a_kstep, const BP& bp, int b_kstep, int nk, bf16_t* smem) {
;     ...
;   auto gload = [&](int kt) {
;     const bf16_t* ab = ap.base + (size_t)kt * a_kstep; const bf16_t* bb = bp.base + (size_t)kt * b_kstep;
; #pragma unroll
;     for (int i = 0; i < CA; ++i) ra[i] = *(const u32x4*)(ab + pa[i]);
; #pragma unroll
;     for (int i = 0; i < CB; ++i) rb[i] = *(const u32x4*)(bb + pb[i]);
;   };
;   auto sstore = [&](int buf) {
;     bf16_t* As = smem + buf * L::STAGE; bf16_t* Bs = As + L::A_ELEMS;
; #pragma unroll
;     for (int i = 0; i < CA; ++i) { const int c = tid + NTHR * i; *(u32x4*)(As + (c >> 3) * LDT + (c & 7) * 8) = oka[i] ? ra[i] : (u32x4){0u, 0u, 0u, 0u}; }
; #pragma unroll
;     for (int i = 0; i < CB; ++i) { const int c = tid + NTHR * i; *(u32x4*)(Bs + (c >> 3) * LDT + (c & 7) * 8) = rb[i]; }
;   };
;   gload(0); sstore(0); gload(nk > 1 ? 1 : 0); __syncthreads();
; #pragma unroll 1
;   for (int kt = 0; kt < nk; ++kt) {
;     const int buf = kt & 1;
;     sstore(buf ^ 1);
;     gload(kt + 2 < nk ? kt + 2 : nk - 1);
;     __builtin_amdgcn_sched_barrier(0);
;     const bf16_t* As = smem + buf * L::STAGE + (wm * 16 * MI + l15) * LDT + quad * 8;
;     const bf16_t* Bs = smem + buf * L::STAGE + L::A_ELEMS + (wn * 16 * NJ + l15) * LDT + quad * 8;
; #pragma unroll
;     for (int ks = 0; ks < 2; ++ks) {
;       if (MI * NJ >= 32 && ks == 1) asm volatile("" ::: "memory");
;       bf16x8 b[NJ];
; #pragma unroll
;       for (int j = 0; j < NJ; ++j) b[j] = *(const bf16x8*)(Bs + j * 16 * LDT + ks * 32);
; #pragma unroll
;       for (int i = 0; i < MI; ++i) {
;         const bf16x8 a = *(const bf16x8*)(As + i * 16 * LDT + ks * 32);
; #pragma unroll
;         for (int j = 0; j < NJ; ++j) acc[i][j] = SWAP ? mfma16(b[j], a, acc[i][j]) : mfma16(a, b[j], acc[i][j]);
;       }
;     }
;     __syncthreads();
;   }
	ds_write_b128 v252, v[124:127] offset:36864
	v_mfma_f32_16x16x32_bf16 v[4:7], v[186:189], v[246:249], v[4:7]
	ds_read_b128 v[186:189], v206 offset:39232
	v_mfma_f32_16x16x32_bf16 v[0:3], v[190:193], v[246:249], v[0:3]
	ds_read_b128 v[190:193], v206 offset:41536
	v_mfma_f32_16x16x32_bf16 v[16:19], v[194:197], v[246:249], v[16:19]
	ds_read_b128 v[194:197], v206 offset:43840
	ds_read_b128 v[242:245], v181 offset:4672
	s_waitcnt lgkmcnt(5)
	v_mfma_f32_16x16x32_bf16 v[156:159], v[182:185], v[198:201], v[156:159]
	s_waitcnt lgkmcnt(3)
	v_mfma_f32_16x16x32_bf16 v[152:155], v[186:189], v[198:201], v[152:155]
	s_waitcnt vmcnt(0)
	ds_write_b128 v253, v[136:139] offset:36864
	s_waitcnt lgkmcnt(3)
	v_mfma_f32_16x16x32_bf16 v[148:151], v[190:193], v[198:201], v[148:151]
	s_waitcnt lgkmcnt(2)
	v_mfma_f32_16x16x32_bf16 v[144:147], v[194:197], v[198:201], v[144:147]
	global_load_dwordx4 v[140:143], v176, s[44:45] offset:256
	ds_read_b128 v[246:249], v181 offset:6976
	v_mfma_f32_16x16x32_bf16 v[108:111], v[182:185], v[202:205], v[108:111]
	v_mfma_f32_16x16x32_bf16 v[104:107], v[186:189], v[202:205], v[104:107]
	global_load_dwordx4 v[128:131], v177, s[44:45] offset:256
	v_mfma_f32_16x16x32_bf16 v[100:103], v[190:193], v[202:205], v[100:103]
	v_mfma_f32_16x16x32_bf16 v[96:99], v[194:197], v[202:205], v[96:99]
	ds_read_b128 v[198:201], v181 offset:9280
	s_waitcnt lgkmcnt(3)
	v_mfma_f32_16x16x32_bf16 v[92:95], v[182:185], v[242:245], v[92:95]
	global_load_dwordx4 v[112:115], v178, s[44:45] offset:256
	v_mfma_f32_16x16x32_bf16 v[88:91], v[186:189], v[242:245], v[88:91]
	v_mfma_f32_16x16x32_bf16 v[84:87], v[190:193], v[242:245], v[84:87]
	global_load_dwordx4 v[132:135], v179, s[44:45] offset:256
	v_mfma_f32_16x16x32_bf16 v[80:83], v[194:197], v[242:245], v[80:83]
	ds_read_b128 v[202:205], v181 offset:11584
	s_waitcnt lgkmcnt(2)
	v_mfma_f32_16x16x32_bf16 v[76:79], v[182:185], v[246:249], v[76:79]
	v_mfma_f32_16x16x32_bf16 v[72:75], v[186:189], v[246:249], v[72:75]
	s_add_u32 s44, s20, s47
	s_addc_u32 s45, s21, 0
	v_lshl_add_u64 v[116:117], v[160:161], 1, s[44:45]
	v_lshl_add_u64 v[120:121], v[162:163], 1, s[44:45]
	v_lshl_add_u64 v[124:125], v[164:165], 1, s[44:45]
	v_lshl_add_u64 v[136:137], v[166:167], 1, s[44:45]
	global_load_dwordx4 v[116:119], v[116:117], off offset:256
	v_mfma_f32_16x16x32_bf16 v[68:71], v[190:193], v[246:249], v[68:71]
	v_mfma_f32_16x16x32_bf16 v[64:67], v[194:197], v[246:249], v[64:67]
	global_load_dwordx4 v[120:123], v[120:121], off offset:256
	ds_read_b128 v[242:245], v181 offset:13888
	s_waitcnt lgkmcnt(2)
	v_mfma_f32_16x16x32_bf16 v[60:63], v[182:185], v[198:201], v[60:63]
	v_mfma_f32_16x16x32_bf16 v[56:59], v[186:189], v[198:201], v[56:59]
	v_mfma_f32_16x16x32_bf16 v[52:55], v[190:193], v[198:201], v[52:55]
	global_load_dwordx4 v[124:127], v[124:125], off offset:256
	v_mfma_f32_16x16x32_bf16 v[48:51], v[194:197], v[198:201], v[48:51]
	ds_read_b128 v[246:249], v181 offset:16192
	s_waitcnt lgkmcnt(2)
	v_mfma_f32_16x16x32_bf16 v[44:47], v[182:185], v[202:205], v[44:47]
	global_load_dwordx4 v[136:139], v[136:137], off offset:256
	v_mfma_f32_16x16x32_bf16 v[40:43], v[186:189], v[202:205], v[40:43]
	v_mfma_f32_16x16x32_bf16 v[36:39], v[190:193], v[202:205], v[36:39]
	v_mfma_f32_16x16x32_bf16 v[32:35], v[194:197], v[202:205], v[32:35]
	s_waitcnt lgkmcnt(0)
	s_barrier
	s_add_i32 s43, s43, 1
	s_cmp_lg_u32 s43, 16
	s_cbranch_scc0 .Lgm14_exit
	s_and_b32 s98, s43, 1
	s_mul_i32 s98, s98, 0x12000
	v_add3_u32 v206, s98, v171, v180
	v_add3_u32 v181, s98, v170, v180
	ds_read_b128 v[198:201], v181
	ds_read_b128 v[202:205], v181 offset:2304
	v_mfma_f32_16x16x32_bf16 v[28:31], v[182:185], v[242:245], v[28:31]
	v_mfma_f32_16x16x32_bf16 v[8:11], v[182:185], v[246:249], v[8:11]
	ds_read_b128 v[182:185], v206 offset:36864
	v_mfma_f32_16x16x32_bf16 v[24:27], v[186:189], v[242:245], v[24:27]
	v_mfma_f32_16x16x32_bf16 v[4:7], v[186:189], v[246:249], v[4:7]
	ds_read_b128 v[186:189], v206 offset:39168
	v_mfma_f32_16x16x32_bf16 v[20:23], v[190:193], v[242:245], v[20:23]
	v_mfma_f32_16x16x32_bf16 v[0:3], v[190:193], v[246:249], v[0:3]
	ds_read_b128 v[190:193], v206 offset:41472
	v_mfma_f32_16x16x32_bf16 v[12:15], v[194:197], v[242:245], v[12:15]
	v_mfma_f32_16x16x32_bf16 v[16:19], v[194:197], v[246:249], v[16:19]
	ds_read_b128 v[194:197], v206 offset:43776
	s_branch .Lgm14_main

; DI f32x4 mfma16(bf16x8 a, bf16x8 b, f32x4 c) { return __builtin_amdgcn_mfma_f32_16x16x32_bf16(a, b, c, 0, 0, 0); }
; template <int MI, int NJ, bool SWAP, class AP, class BP>
; DI void gemm_main(f32x4 (&acc)[MI][NJ], const AP& ap, int a_kstep, const BP& bp, int b_kstep, int nk, bf16_t* smem) {
;     ...
;   auto gload = [&](int kt) {
;     const bf16_t* ab = ap.base + (size_t)kt * a_kstep; const bf16_t* bb = bp.base + (size_t)kt * b_kstep;
; #pragma unroll
;     for (int i = 0; i < CA; ++i) ra[i] = *(const u32x4*)(ab + pa[i]);
; #pragma unroll
;     for (int i = 0; i < CB; ++i) rb[i] = *(const u32x4*)(bb + pb[i]);
;   };
;   auto sstore = [&](int buf) {
;     bf16_t* As = smem + buf * L::STAGE; bf16_t* Bs = As + L::A_ELEMS;
; #pragma unroll
;     for (int i = 0; i < CA; ++i) { const int c = tid + NTHR * i; *(u32x4*)(As + (c >> 3) * LDT + (c & 7) * 8) = oka[i] ? ra[i] : (u32x4){0u, 0u, 0u, 0u}; }
; #pragma unroll
;     for (int i = 0; i < CB; ++i) { const int c = tid + NTHR * i; *(u32x4*)(Bs + (c >> 3) * LDT + (c & 7) * 8) = rb[i]; }
;   };
;   gload(0); sstore(0); gload(nk > 1 ? 1 : 0); __syncthreads();
; #pragma unroll 1
;   for (int kt = 0; kt < nk; ++kt) {
;     const int buf = kt & 1;
;     sstore(buf ^ 1);
;     gload(kt + 2 < nk ? kt + 2 : nk - 1);
;     __builtin_amdgcn_sched_barrier(0);
;     const bf16_t* As = smem + buf * L::STAGE + (wm * 16 * MI + l15) * LDT + quad * 8;
;     const bf16_t* Bs = smem + buf * L::STAGE + L::A_ELEMS + (wn * 16 * NJ + l15) * LDT + quad * 8;
; #pragma unroll
;     for (int ks = 0; ks < 2; ++ks) {
;       if (MI * NJ >= 32 && ks == 1) asm volatile("" ::: "memory");
;       bf16x8 b[NJ];
; #pragma unroll
;       for (int j = 0; j < NJ; ++j) b[j] = *(const bf16x8*)(Bs + j * 16 * LDT + ks * 32);
; #pragma unroll
;       for (int i = 0; i < MI; ++i) {
;         const bf16x8 a = *(const bf16x8*)(As + i * 16 * LDT + ks * 32);
; #pragma unroll
;         for (int j = 0; j < NJ; ++j) acc[i][j] = SWAP ? mfma16(b[j], a, acc[i][j]) : mfma16(a, b[j], acc[i][j]);
;       }
;     }
;     __syncthreads();
;   }
.Lgm15_main:
	ds_read_b128 v[242:245], v177 offset:4608
	s_waitcnt lgkmcnt(4)
	v_mfma_f32_16x16x32_bf16 v[156:159], v[178:181], v[194:197], v[156:159]
	s_waitcnt lgkmcnt(3)
	v_mfma_f32_16x16x32_bf16 v[152:155], v[182:185], v[194:197], v[152:155]
	s_waitcnt lgkmcnt(2)
	v_mfma_f32_16x16x32_bf16 v[148:151], v[186:189], v[194:197], v[148:151]
	s_waitcnt lgkmcnt(1)
	v_mfma_f32_16x16x32_bf16 v[144:147], v[190:193], v[194:197], v[144:147]
	s_and_b32 s17, s16, 1
	s_min_u32 s18, s16, 41
	s_xor_b32 s19, s17, 1
	s_lshl_b32 s20, s18, 7
	s_mul_i32 s19, s19, 0x12000
	s_add_u32 s18, s2, s20
	v_add3_u32 v250, s19, v172, v170
	v_add3_u32 v251, s19, v173, v170
	v_add3_u32 v252, s19, v174, v170
	v_add3_u32 v253, s19, v175, v170
	s_addc_u32 s19, s3, 0
	s_waitcnt vmcnt(7)
	ds_write_b128 v250, v[112:115]
	ds_read_b128 v[246:249], v177 offset:6912
	v_mfma_f32_16x16x32_bf16 v[108:111], v[178:181], v[198:201], v[108:111]
	v_mfma_f32_16x16x32_bf16 v[104:107], v[182:185], v[198:201], v[104:107]
	v_mfma_f32_16x16x32_bf16 v[100:103], v[186:189], v[198:201], v[100:103]
	v_mfma_f32_16x16x32_bf16 v[96:99], v[190:193], v[198:201], v[96:99]
	s_waitcnt vmcnt(6)
	ds_write_b128 v251, v[116:119]
	ds_read_b128 v[194:197], v177 offset:9216
	s_waitcnt lgkmcnt(4)
	v_mfma_f32_16x16x32_bf16 v[92:95], v[178:181], v[242:245], v[92:95]
	v_mfma_f32_16x16x32_bf16 v[88:91], v[182:185], v[242:245], v[88:91]
	v_mfma_f32_16x16x32_bf16 v[84:87], v[186:189], v[242:245], v[84:87]
	v_mfma_f32_16x16x32_bf16 v[80:83], v[190:193], v[242:245], v[80:83]
	ds_read_b128 v[198:201], v177 offset:11520
	s_waitcnt lgkmcnt(3)
	v_mfma_f32_16x16x32_bf16 v[76:79], v[178:181], v[246:249], v[76:79]
	s_waitcnt vmcnt(5)
	ds_write_b128 v252, v[120:123]
	v_mfma_f32_16x16x32_bf16 v[72:75], v[182:185], v[246:249], v[72:75]
	v_mfma_f32_16x16x32_bf16 v[68:71], v[186:189], v[246:249], v[68:71]
	v_mfma_f32_16x16x32_bf16 v[64:67], v[190:193], v[246:249], v[64:67]
	ds_read_b128 v[242:245], v177 offset:13824
	s_waitcnt lgkmcnt(3)
	v_mfma_f32_16x16x32_bf16 v[60:63], v[178:181], v[194:197], v[60:63]
	s_waitcnt vmcnt(4)
	ds_write_b128 v253, v[124:127]
	v_mfma_f32_16x16x32_bf16 v[56:59], v[182:185], v[194:197], v[56:59]
	v_mfma_f32_16x16x32_bf16 v[52:55], v[186:189], v[194:197], v[52:55]
	v_mfma_f32_16x16x32_bf16 v[48:51], v[190:193], v[194:197], v[48:51]
	ds_read_b128 v[246:249], v177 offset:16128
	s_waitcnt lgkmcnt(4)
	v_mfma_f32_16x16x32_bf16 v[44:47], v[178:181], v[198:201], v[44:47]
	s_waitcnt vmcnt(3)
	ds_write_b128 v250, v[128:131] offset:36864
	v_mfma_f32_16x16x32_bf16 v[40:43], v[182:185], v[198:201], v[40:43]
	v_mfma_f32_16x16x32_bf16 v[36:39], v[186:189], v[198:201], v[36:39]
	v_mfma_f32_16x16x32_bf16 v[32:35], v[190:193], v[198:201], v[32:35]
	ds_read_b128 v[194:197], v177 offset:64
	s_waitcnt lgkmcnt(4)
	v_mfma_f32_16x16x32_bf16 v[28:31], v[178:181], v[242:245], v[28:31]
	s_waitcnt vmcnt(2)
	ds_write_b128 v251, v[132:135] offset:36864
	v_mfma_f32_16x16x32_bf16 v[24:27], v[182:185], v[242:245], v[24:27]
	v_mfma_f32_16x16x32_bf16 v[20:23], v[186:189], v[242:245], v[20:23]
	v_mfma_f32_16x16x32_bf16 v[16:19], v[190:193], v[242:245], v[16:19]
	ds_read_b128 v[198:201], v177 offset:2368
	s_waitcnt lgkmcnt(4)
	v_mfma_f32_16x16x32_bf16 v[8:11], v[178:181], v[246:249], v[8:11]
	ds_read_b128 v[178:181], v202 offset:36928
	s_waitcnt vmcnt(1)
	ds_write_b128 v252, v[136:139] offset:36864
	v_mfma_f32_16x16x32_bf16 v[4:7], v[182:185], v[246:249], v[4:7]
	ds_read_b128 v[182:185], v202 offset:39232
	v_mfma_f32_16x16x32_bf16 v[0:3], v[186:189], v[246:249], v[0:3]
	ds_read_b128 v[186:189], v202 offset:41536
	v_mfma_f32_16x16x32_bf16 v[12:15], v[190:193], v[246:249], v[12:15]
	ds_read_b128 v[190:193], v202 offset:43840
	ds_read_b128 v[242:245], v177 offset:4672
	s_waitcnt lgkmcnt(5)
	v_mfma_f32_16x16x32_bf16 v[156:159], v[178:181], v[194:197], v[156:159]
	s_waitcnt lgkmcnt(3)
	v_mfma_f32_16x16x32_bf16 v[152:155], v[182:185], v[194:197], v[152:155]
	s_waitcnt vmcnt(0)
	ds_write_b128 v253, v[140:143] offset:36864
	s_waitcnt lgkmcnt(3)
	v_mfma_f32_16x16x32_bf16 v[148:151], v[186:189], v[194:197], v[148:151]
	s_waitcnt lgkmcnt(2)
	v_mfma_f32_16x16x32_bf16 v[144:147], v[190:193], v[194:197], v[144:147]
	v_lshl_add_u64 v[112:113], s[18:19], 0, v[162:163]
	v_lshl_add_u64 v[116:117], s[18:19], 0, v[164:165]
	v_lshl_add_u64 v[120:121], s[18:19], 0, v[166:167]
	v_lshl_add_u64 v[124:125], s[18:19], 0, v[168:169]
	s_add_u32 s18, s4, s20
	s_addc_u32 s19, s5, 0
	v_lshl_add_u64 v[128:129], s[18:19], 0, v[162:163]
	v_lshl_add_u64 v[132:133], s[18:19], 0, v[164:165]
	v_lshl_add_u64 v[136:137], s[18:19], 0, v[166:167]
	v_lshl_add_u64 v[140:141], s[18:19], 0, v[168:169]
	global_load_dwordx4 v[112:115], v[112:113], off offset:256
	ds_read_b128 v[246:249], v177 offset:6976
	v_mfma_f32_16x16x32_bf16 v[108:111], v[178:181], v[198:201], v[108:111]
	v_mfma_f32_16x16x32_bf16 v[104:107], v[182:185], v[198:201], v[104:107]
	global_load_dwordx4 v[116:119], v[116:117], off offset:256
	v_mfma_f32_16x16x32_bf16 v[100:103], v[186:189], v[198:201], v[100:103]
	v_mfma_f32_16x16x32_bf16 v[96:99], v[190:193], v[198:201], v[96:99]
	ds_read_b128 v[194:197], v177 offset:9280
	s_waitcnt lgkmcnt(3)
	v_mfma_f32_16x16x32_bf16 v[92:95], v[178:181], v[242:245], v[92:95]
	global_load_dwordx4 v[120:123], v[120:121], off offset:256
	v_mfma_f32_16x16x32_bf16 v[88:91], v[182:185], v[242:245], v[88:91]
	v_mfma_f32_16x16x32_bf16 v[84:87], v[186:189], v[242:245], v[84:87]
	global_load_dwordx4 v[124:127], v[124:125], off offset:256
	v_mfma_f32_16x16x32_bf16 v[80:83], v[190:193], v[242:245], v[80:83]
	ds_read_b128 v[198:201], v177 offset:11584
	s_waitcnt lgkmcnt(2)
	v_mfma_f32_16x16x32_bf16 v[76:79], v[178:181], v[246:249], v[76:79]
	v_mfma_f32_16x16x32_bf16 v[72:75], v[182:185], v[246:249], v[72:75]
	global_load_dwordx4 v[128:131], v[128:129], off offset:256
	v_mfma_f32_16x16x32_bf16 v[68:71], v[186:189], v[246:249], v[68:71]
	v_mfma_f32_16x16x32_bf16 v[64:67], v[190:193], v[246:249], v[64:67]
	global_load_dwordx4 v[132:135], v[132:133], off offset:256
	ds_read_b128 v[242:245], v177 offset:13888
	s_waitcnt lgkmcnt(2)
	v_mfma_f32_16x16x32_bf16 v[60:63], v[178:181], v[194:197], v[60:63]
	v_mfma_f32_16x16x32_bf16 v[56:59], v[182:185], v[194:197], v[56:59]
	v_mfma_f32_16x16x32_bf16 v[52:55], v[186:189], v[194:197], v[52:55]
	global_load_dwordx4 v[136:139], v[136:137], off offset:256
	v_mfma_f32_16x16x32_bf16 v[48:51], v[190:193], v[194:197], v[48:51]
	ds_read_b128 v[246:249], v177 offset:16192
	s_waitcnt lgkmcnt(2)
	v_mfma_f32_16x16x32_bf16 v[44:47], v[178:181], v[198:201], v[44:47]
	global_load_dwordx4 v[140:143], v[140:141], off offset:256
	v_mfma_f32_16x16x32_bf16 v[40:43], v[182:185], v[198:201], v[40:43]
	v_mfma_f32_16x16x32_bf16 v[36:39], v[186:189], v[198:201], v[36:39]
	v_mfma_f32_16x16x32_bf16 v[32:35], v[190:193], v[198:201], v[32:35]
	s_waitcnt lgkmcnt(0)
	s_barrier
; DI f32x4 mfma16(bf16x8 a, bf16x8 b, f32x4 c) { return __builtin_amdgcn_mfma_f32_16x16x32_bf16(a, b, c, 0, 0, 0); }
; template <int MI, int NJ, bool SWAP, class AP, class BP>
; DI void gemm_main(f32x4 (&acc)[MI][NJ], const AP& ap, int a_kstep, const BP& bp, int b_kstep, int nk, bf16_t* smem) {
;     ...
;   for (int kt = 0; kt < nk; ++kt) {
;     const int buf = kt & 1;
;     sstore(buf ^ 1);
;     gload(kt + 2 < nk ? kt + 2 : nk - 1);
;     __builtin_amdgcn_sched_barrier(0);
;     const bf16_t* As = smem + buf * L::STAGE + (wm * 16 * MI + l15) * LDT + quad * 8;
;     const bf16_t* Bs = smem + buf * L::STAGE + L::A_ELEMS + (wn * 16 * NJ + l15) * LDT + quad * 8;
; #pragma unroll
;     for (int ks = 0; ks < 2; ++ks) {
;       if (MI * NJ >= 32 && ks == 1) asm volatile("" ::: "memory");
;       bf16x8 b[NJ];
; #pragma unroll
;       for (int j = 0; j < NJ; ++j) b[j] = *(const bf16x8*)(Bs + j * 16 * LDT + ks * 32);
; #pragma unroll
;       for (int i = 0; i < MI; ++i) {
;         const bf16x8 a = *(const bf16x8*)(As + i * 16 * LDT + ks * 32);
; #pragma unroll
;         for (int j = 0; j < NJ; ++j) acc[i][j] = SWAP ? mfma16(b[j], a, acc[i][j]) : mfma16(a, b[j], acc[i][j]);
;       }
;     }
;     __syncthreads();
	s_add_i32 s16, s16, 1
	s_cmp_lg_u32 s16, 44
	s_cbranch_scc0 .Lgm15_exit
	s_and_b32 s98, s16, 1
	s_mul_i32 s98, s98, 0x12000
	v_add3_u32 v202, s98, v160, v176
	v_add3_u32 v177, s98, v171, v176
	ds_read_b128 v[194:197], v177
	ds_read_b128 v[198:201], v177 offset:2304
	v_mfma_f32_16x16x32_bf16 v[28:31], v[178:181], v[242:245], v[28:31]
	v_mfma_f32_16x16x32_bf16 v[8:11], v[178:181], v[246:249], v[8:11]
	ds_read_b128 v[178:181], v202 offset:36864
	v_mfma_f32_16x16x32_bf16 v[24:27], v[182:185], v[242:245], v[24:27]
	v_mfma_f32_16x16x32_bf16 v[4:7], v[182:185], v[246:249], v[4:7]
	ds_read_b128 v[182:185], v202 offset:39168
	v_mfma_f32_16x16x32_bf16 v[20:23], v[186:189], v[242:245], v[20:23]
	v_mfma_f32_16x16x32_bf16 v[0:3], v[186:189], v[246:249], v[0:3]
	ds_read_b128 v[186:189], v202 offset:41472
	v_mfma_f32_16x16x32_bf16 v[16:19], v[190:193], v[242:245], v[16:19]
	v_mfma_f32_16x16x32_bf16 v[12:15], v[190:193], v[246:249], v[12:15]
	ds_read_b128 v[190:193], v202 offset:43776
	s_branch .Lgm15_main
